# code placement: every v_mfma of the six GEMM K-loops (peel + loop) 8-byte aligned by 40 inserted s_nop 0 (half of them were at 4 mod 8)
# speedup vs baseline: 1.0019x; 1.0019x over previous
.LBB0_215:
	s_ashr_i32 s43, s42, 31
	s_lshl_b64 s[28:29], s[42:43], 20
	s_add_u32 s44, s68, s28
	s_addc_u32 s45, s69, s29
	s_and_b64 s[28:29], s[38:39], exec
	s_cselect_b32 s43, s45, s51
	s_cselect_b32 s84, s44, s50
	s_ashr_i32 s41, s40, 31
	s_lshl_b64 s[28:29], s[40:41], 20
	v_readlane_b32 s41, v255, 6
	s_add_u32 s46, s41, s28
	v_readlane_b32 s28, v255, 7
	s_addc_u32 s47, s28, s29
	s_and_b64 s[28:29], s[38:39], exec
	s_cselect_b32 s41, s47, s53
	s_cselect_b32 s85, s46, s52
	s_add_u32 s50, s50, 0x80080
	s_addc_u32 s51, s51, 0
	s_add_u32 s86, s52, 0x100
	s_addc_u32 s87, s53, 0
	s_mov_b32 s88, -2
	s_add_u32 s28, s50, 0xfff80080
	s_addc_u32 s29, s51, -1
	s_add_i32 s89, 0, 0x10000
	s_cmp_eq_u32 s88, 28
	s_cselect_b32 s53, s43, s29
	s_cselect_b32 s52, s84, s28
	s_cselect_b32 s29, s41, s87
	s_cselect_b32 s28, s85, s86
	s_add_i32 s92, 0, 0x14000
	v_add_u32_e32 v158, s89, v147
	v_add_u32_e32 v174, s92, v147
	ds_read_b128 v[142:145], v158
	ds_read_b128 v[150:153], v158 offset:1024
	ds_read_b128 v[154:157], v158 offset:2048
	ds_read_b128 v[158:161], v158 offset:3072
	ds_read_b128 v[162:165], v174
	ds_read_b128 v[166:169], v174 offset:1024
	ds_read_b128 v[170:173], v174 offset:2048
	ds_read_b128 v[174:177], v174 offset:3072
	s_add_i32 m0, s36, 0xc000
	ds_read_b128 v[178:181], v149
	ds_read_b128 v[182:185], v149 offset:1024
	ds_read_b128 v[186:189], v149 offset:2048
	ds_read_b128 v[190:193], v149 offset:3072
	ds_read_b128 v[194:197], v149 offset:4096
	ds_read_b128 v[198:201], v149 offset:5120
	ds_read_b128 v[202:205], v149 offset:6144
	ds_read_b128 v[224:227], v149 offset:7168
	global_load_lds_dwordx4 v138, s[50:51]
	s_add_i32 m0, s36, 0xe000
	s_nop 0
	global_load_lds_dwordx4 v140, s[50:51]
	s_waitcnt vmcnt(8)
	s_waitcnt lgkmcnt(0)
	s_barrier
	s_setprio 1
	s_waitcnt lgkmcnt(0)
	v_mfma_f32_16x16x32_bf16 v[126:129], v[142:145], v[178:181], 0
	v_mfma_f32_16x16x32_bf16 v[122:125], v[154:157], v[178:181], 0
	v_mfma_f32_16x16x32_bf16 v[118:121], v[142:145], v[186:189], 0
	v_mfma_f32_16x16x32_bf16 v[110:113], v[154:157], v[186:189], 0
	v_mfma_f32_16x16x32_bf16 v[102:105], v[142:145], v[194:197], 0
	v_mfma_f32_16x16x32_bf16 v[94:97], v[154:157], v[194:197], 0
	v_mfma_f32_16x16x32_bf16 v[86:89], v[142:145], v[202:205], 0
	v_mfma_f32_16x16x32_bf16 v[78:81], v[154:157], v[202:205], 0
	v_mfma_f32_16x16x32_bf16 v[126:129], v[150:153], v[182:185], v[126:129]
	v_mfma_f32_16x16x32_bf16 v[122:125], v[158:161], v[182:185], v[122:125]
	v_mfma_f32_16x16x32_bf16 v[118:121], v[150:153], v[190:193], v[118:121]
	v_mfma_f32_16x16x32_bf16 v[110:113], v[158:161], v[190:193], v[110:113]
	v_mfma_f32_16x16x32_bf16 v[102:105], v[150:153], v[198:201], v[102:105]
	v_mfma_f32_16x16x32_bf16 v[94:97], v[158:161], v[198:201], v[94:97]
	v_mfma_f32_16x16x32_bf16 v[86:89], v[150:153], v[224:227], v[86:89]
	v_mfma_f32_16x16x32_bf16 v[78:81], v[158:161], v[224:227], v[78:81]
	s_setprio 0
	s_setprio 1
	v_mfma_f32_16x16x32_bf16 v[114:117], v[162:165], v[178:181], 0
	v_mfma_f32_16x16x32_bf16 v[106:109], v[170:173], v[178:181], 0
	v_mfma_f32_16x16x32_bf16 v[98:101], v[162:165], v[186:189], 0
	v_mfma_f32_16x16x32_bf16 v[90:93], v[170:173], v[186:189], 0
	v_mfma_f32_16x16x32_bf16 v[82:85], v[162:165], v[194:197], 0
	v_mfma_f32_16x16x32_bf16 v[74:77], v[170:173], v[194:197], 0
	v_mfma_f32_16x16x32_bf16 v[70:73], v[162:165], v[202:205], 0
	v_mfma_f32_16x16x32_bf16 v[66:69], v[170:173], v[202:205], 0
	v_mfma_f32_16x16x32_bf16 v[114:117], v[166:169], v[182:185], v[114:117]
	v_mfma_f32_16x16x32_bf16 v[106:109], v[174:177], v[182:185], v[106:109]
	v_mfma_f32_16x16x32_bf16 v[98:101], v[166:169], v[190:193], v[98:101]
	v_mfma_f32_16x16x32_bf16 v[90:93], v[174:177], v[190:193], v[90:93]
	v_mfma_f32_16x16x32_bf16 v[82:85], v[166:169], v[198:201], v[82:85]
	v_mfma_f32_16x16x32_bf16 v[74:77], v[174:177], v[198:201], v[74:77]
	v_mfma_f32_16x16x32_bf16 v[70:73], v[166:169], v[224:227], v[70:73]
	v_mfma_f32_16x16x32_bf16 v[66:69], v[174:177], v[224:227], v[66:69]
	s_setprio 0
	s_barrier
	s_add_i32 s89, s89, s26
	s_mov_b32 m0, s89
	ds_read_b128 v[178:181], v149 offset:16384
	ds_read_b128 v[182:185], v149 offset:17408
	ds_read_b128 v[186:189], v149 offset:18432
	ds_read_b128 v[190:193], v149 offset:19456
	ds_read_b128 v[194:197], v149 offset:20480
	ds_read_b128 v[198:201], v149 offset:21504
	ds_read_b128 v[202:205], v149 offset:22528
	ds_read_b128 v[224:227], v149 offset:23552
	global_load_lds_dwordx4 v134, s[28:29]
	s_add_i32 m0, s89, 0x2000
	s_add_u32 s90, s28, 0x80000
	s_addc_u32 s91, s29, 0
	s_add_i32 s89, s92, s26
	global_load_lds_dwordx4 v130, s[28:29]
	s_mov_b32 m0, s89
	v_lshl_add_u64 v[232:233], s[52:53], 0, v[132:133]
	global_load_lds_dwordx4 v134, s[90:91]
	s_add_i32 m0, s89, 0x2000
	s_nop 0
	global_load_lds_dwordx4 v130, s[90:91]
	v_lshl_add_u64 v[230:231], s[52:53], 0, v[136:137]
	s_mov_b32 m0, s36
	s_nop 0
	global_load_lds_dwordx4 v[230:231], off
	s_mov_b32 m0, s37
	s_nop 0
	global_load_lds_dwordx4 v[232:233], off
	s_waitcnt vmcnt(8)
	s_waitcnt lgkmcnt(0)
	s_barrier
	s_setprio 1
	s_waitcnt lgkmcnt(0)
	s_nop 0
	v_mfma_f32_16x16x32_bf16 v[62:65], v[142:145], v[178:181], 0
	v_mfma_f32_16x16x32_bf16 v[58:61], v[154:157], v[178:181], 0
	v_mfma_f32_16x16x32_bf16 v[54:57], v[142:145], v[186:189], 0
	v_mfma_f32_16x16x32_bf16 v[46:49], v[154:157], v[186:189], 0
	v_mfma_f32_16x16x32_bf16 v[38:41], v[142:145], v[194:197], 0
	v_mfma_f32_16x16x32_bf16 v[30:33], v[154:157], v[194:197], 0
	v_mfma_f32_16x16x32_bf16 v[22:25], v[142:145], v[202:205], 0
	v_mfma_f32_16x16x32_bf16 v[12:15], v[154:157], v[202:205], 0
	v_mfma_f32_16x16x32_bf16 v[62:65], v[150:153], v[182:185], v[62:65]
	v_mfma_f32_16x16x32_bf16 v[58:61], v[158:161], v[182:185], v[58:61]
	v_mfma_f32_16x16x32_bf16 v[54:57], v[150:153], v[190:193], v[54:57]
	v_mfma_f32_16x16x32_bf16 v[46:49], v[158:161], v[190:193], v[46:49]
	v_mfma_f32_16x16x32_bf16 v[38:41], v[150:153], v[198:201], v[38:41]
	v_mfma_f32_16x16x32_bf16 v[30:33], v[158:161], v[198:201], v[30:33]
	v_mfma_f32_16x16x32_bf16 v[22:25], v[150:153], v[224:227], v[22:25]
	v_mfma_f32_16x16x32_bf16 v[12:15], v[158:161], v[224:227], v[12:15]
	s_setprio 0
	s_setprio 1
	v_mfma_f32_16x16x32_bf16 v[50:53], v[162:165], v[178:181], 0
	v_mfma_f32_16x16x32_bf16 v[42:45], v[170:173], v[178:181], 0
	v_mfma_f32_16x16x32_bf16 v[34:37], v[162:165], v[186:189], 0
	v_mfma_f32_16x16x32_bf16 v[26:29], v[170:173], v[186:189], 0
	v_mfma_f32_16x16x32_bf16 v[18:21], v[162:165], v[194:197], 0
	v_mfma_f32_16x16x32_bf16 v[8:11], v[170:173], v[194:197], 0
	v_mfma_f32_16x16x32_bf16 v[4:7], v[162:165], v[202:205], 0
	v_mfma_f32_16x16x32_bf16 v[0:3], v[170:173], v[202:205], 0
	v_mfma_f32_16x16x32_bf16 v[50:53], v[166:169], v[182:185], v[50:53]
	v_mfma_f32_16x16x32_bf16 v[42:45], v[174:177], v[182:185], v[42:45]
	v_mfma_f32_16x16x32_bf16 v[34:37], v[166:169], v[190:193], v[34:37]
	v_mfma_f32_16x16x32_bf16 v[26:29], v[174:177], v[190:193], v[26:29]
	v_mfma_f32_16x16x32_bf16 v[18:21], v[166:169], v[198:201], v[18:21]
	v_mfma_f32_16x16x32_bf16 v[8:11], v[174:177], v[198:201], v[8:11]
	v_mfma_f32_16x16x32_bf16 v[4:7], v[166:169], v[224:227], v[4:7]
	v_mfma_f32_16x16x32_bf16 v[0:3], v[174:177], v[224:227], v[0:3]
	s_setprio 0
	s_barrier
	s_add_i32 s89, 0, 0x18000
	s_add_i32 s90, 0, 0x1c000
	v_add_u32_e32 v158, s89, v147
	v_add_u32_e32 v174, s90, v147
	ds_read_b128 v[142:145], v158
	ds_read_b128 v[150:153], v158 offset:1024
	ds_read_b128 v[154:157], v158 offset:2048
	ds_read_b128 v[158:161], v158 offset:3072
	ds_read_b128 v[162:165], v174
	ds_read_b128 v[166:169], v174 offset:1024
	ds_read_b128 v[170:173], v174 offset:2048
	ds_read_b128 v[174:177], v174 offset:3072
	s_add_u32 s52, s52, 0x80000
	s_addc_u32 s53, s53, 0
	s_mov_b32 m0, s49
	ds_read_b128 v[178:181], v149 offset:32768
	ds_read_b128 v[182:185], v149 offset:33792
	ds_read_b128 v[186:189], v149 offset:34816
	ds_read_b128 v[190:193], v149 offset:35840
	ds_read_b128 v[194:197], v149 offset:36864
	ds_read_b128 v[198:201], v149 offset:37888
	ds_read_b128 v[202:205], v149 offset:38912
	ds_read_b128 v[224:227], v149 offset:39936
	global_load_lds_dwordx4 v136, s[52:53]
	s_mov_b32 m0, s56
	s_nop 0
	global_load_lds_dwordx4 v132, s[52:53]
	s_waitcnt vmcnt(8)
	s_waitcnt lgkmcnt(0)
	s_barrier
	s_setprio 1
	s_waitcnt lgkmcnt(0)
	s_nop 0
	v_mfma_f32_16x16x32_bf16 v[126:129], v[142:145], v[178:181], v[126:129]
	v_mfma_f32_16x16x32_bf16 v[122:125], v[154:157], v[178:181], v[122:125]
	v_mfma_f32_16x16x32_bf16 v[118:121], v[142:145], v[186:189], v[118:121]
	v_mfma_f32_16x16x32_bf16 v[110:113], v[154:157], v[186:189], v[110:113]
	v_mfma_f32_16x16x32_bf16 v[102:105], v[142:145], v[194:197], v[102:105]
	v_mfma_f32_16x16x32_bf16 v[94:97], v[154:157], v[194:197], v[94:97]
	v_mfma_f32_16x16x32_bf16 v[86:89], v[142:145], v[202:205], v[86:89]
	v_mfma_f32_16x16x32_bf16 v[78:81], v[154:157], v[202:205], v[78:81]
	v_mfma_f32_16x16x32_bf16 v[126:129], v[150:153], v[182:185], v[126:129]
	v_mfma_f32_16x16x32_bf16 v[122:125], v[158:161], v[182:185], v[122:125]
	v_mfma_f32_16x16x32_bf16 v[118:121], v[150:153], v[190:193], v[118:121]
	v_mfma_f32_16x16x32_bf16 v[110:113], v[158:161], v[190:193], v[110:113]
	v_mfma_f32_16x16x32_bf16 v[102:105], v[150:153], v[198:201], v[102:105]
	v_mfma_f32_16x16x32_bf16 v[94:97], v[158:161], v[198:201], v[94:97]
	v_mfma_f32_16x16x32_bf16 v[86:89], v[150:153], v[224:227], v[86:89]
	v_mfma_f32_16x16x32_bf16 v[78:81], v[158:161], v[224:227], v[78:81]
	s_setprio 0
	s_setprio 1
	v_mfma_f32_16x16x32_bf16 v[114:117], v[162:165], v[178:181], v[114:117]
	v_mfma_f32_16x16x32_bf16 v[106:109], v[170:173], v[178:181], v[106:109]
	v_mfma_f32_16x16x32_bf16 v[98:101], v[162:165], v[186:189], v[98:101]
	v_mfma_f32_16x16x32_bf16 v[90:93], v[170:173], v[186:189], v[90:93]
	v_mfma_f32_16x16x32_bf16 v[82:85], v[162:165], v[194:197], v[82:85]
	v_mfma_f32_16x16x32_bf16 v[74:77], v[170:173], v[194:197], v[74:77]
	v_mfma_f32_16x16x32_bf16 v[70:73], v[162:165], v[202:205], v[70:73]
	v_mfma_f32_16x16x32_bf16 v[66:69], v[170:173], v[202:205], v[66:69]
	v_mfma_f32_16x16x32_bf16 v[114:117], v[166:169], v[182:185], v[114:117]
	v_mfma_f32_16x16x32_bf16 v[106:109], v[174:177], v[182:185], v[106:109]
	v_mfma_f32_16x16x32_bf16 v[98:101], v[166:169], v[190:193], v[98:101]
	v_mfma_f32_16x16x32_bf16 v[90:93], v[174:177], v[190:193], v[90:93]
	v_mfma_f32_16x16x32_bf16 v[82:85], v[166:169], v[198:201], v[82:85]
	v_mfma_f32_16x16x32_bf16 v[74:77], v[174:177], v[198:201], v[74:77]
	v_mfma_f32_16x16x32_bf16 v[70:73], v[166:169], v[224:227], v[70:73]
	v_mfma_f32_16x16x32_bf16 v[66:69], v[174:177], v[224:227], v[66:69]
	s_setprio 0
	s_barrier
	s_add_i32 s52, s89, s26
	s_add_u32 s28, s28, 0x80
	s_addc_u32 s29, s29, 0
	s_mov_b32 m0, s52
	ds_read_b128 v[178:181], v149 offset:49152
	ds_read_b128 v[182:185], v149 offset:50176
	ds_read_b128 v[186:189], v149 offset:51200
	ds_read_b128 v[190:193], v149 offset:52224
	ds_read_b128 v[194:197], v149 offset:53248
	ds_read_b128 v[198:201], v149 offset:54272
	ds_read_b128 v[202:205], v149 offset:55296
	ds_read_b128 v[224:227], v149 offset:56320
	global_load_lds_dwordx4 v134, s[28:29]
	s_add_i32 m0, s52, 0x2000
	s_add_i32 s52, s90, s26
	global_load_lds_dwordx4 v130, s[28:29]
	s_add_u32 s28, s28, 0x80000
	s_addc_u32 s29, s29, 0
	s_mov_b32 m0, s52
	s_nop 0
	global_load_lds_dwordx4 v134, s[28:29]
	s_add_i32 m0, s52, 0x2000
	s_nop 0
	global_load_lds_dwordx4 v130, s[28:29]
	v_lshl_add_u64 v[206:207], v[230:231], 0, s[34:35]
	s_mov_b32 m0, s57
	s_nop 0
	global_load_lds_dwordx4 v[206:207], off
	v_lshl_add_u64 v[206:207], v[232:233], 0, s[34:35]
	s_mov_b32 m0, s58
	s_nop 0
	global_load_lds_dwordx4 v[206:207], off
	s_waitcnt vmcnt(8)
	s_waitcnt lgkmcnt(0)
	s_barrier
	s_setprio 1
	s_waitcnt lgkmcnt(0)
	s_nop 0
	v_mfma_f32_16x16x32_bf16 v[62:65], v[142:145], v[178:181], v[62:65]
	v_mfma_f32_16x16x32_bf16 v[58:61], v[154:157], v[178:181], v[58:61]
	v_mfma_f32_16x16x32_bf16 v[54:57], v[142:145], v[186:189], v[54:57]
	v_mfma_f32_16x16x32_bf16 v[46:49], v[154:157], v[186:189], v[46:49]
	v_mfma_f32_16x16x32_bf16 v[38:41], v[142:145], v[194:197], v[38:41]
	v_mfma_f32_16x16x32_bf16 v[30:33], v[154:157], v[194:197], v[30:33]
	v_mfma_f32_16x16x32_bf16 v[22:25], v[142:145], v[202:205], v[22:25]
	v_mfma_f32_16x16x32_bf16 v[12:15], v[154:157], v[202:205], v[12:15]
	v_mfma_f32_16x16x32_bf16 v[62:65], v[150:153], v[182:185], v[62:65]
	v_mfma_f32_16x16x32_bf16 v[58:61], v[158:161], v[182:185], v[58:61]
	v_mfma_f32_16x16x32_bf16 v[54:57], v[150:153], v[190:193], v[54:57]
	v_mfma_f32_16x16x32_bf16 v[46:49], v[158:161], v[190:193], v[46:49]
	v_mfma_f32_16x16x32_bf16 v[38:41], v[150:153], v[198:201], v[38:41]
	v_mfma_f32_16x16x32_bf16 v[30:33], v[158:161], v[198:201], v[30:33]
	v_mfma_f32_16x16x32_bf16 v[22:25], v[150:153], v[224:227], v[22:25]
	v_mfma_f32_16x16x32_bf16 v[12:15], v[158:161], v[224:227], v[12:15]
	s_setprio 0
	s_setprio 1
	v_mfma_f32_16x16x32_bf16 v[50:53], v[162:165], v[178:181], v[50:53]
	v_mfma_f32_16x16x32_bf16 v[42:45], v[170:173], v[178:181], v[42:45]
	v_mfma_f32_16x16x32_bf16 v[34:37], v[162:165], v[186:189], v[34:37]
	v_mfma_f32_16x16x32_bf16 v[26:29], v[170:173], v[186:189], v[26:29]
	v_mfma_f32_16x16x32_bf16 v[18:21], v[162:165], v[194:197], v[18:21]
	v_mfma_f32_16x16x32_bf16 v[8:11], v[170:173], v[194:197], v[8:11]
	v_mfma_f32_16x16x32_bf16 v[4:7], v[162:165], v[202:205], v[4:7]
	v_mfma_f32_16x16x32_bf16 v[0:3], v[170:173], v[202:205], v[0:3]
	v_mfma_f32_16x16x32_bf16 v[50:53], v[166:169], v[182:185], v[50:53]
	v_mfma_f32_16x16x32_bf16 v[42:45], v[174:177], v[182:185], v[42:45]
	v_mfma_f32_16x16x32_bf16 v[34:37], v[166:169], v[190:193], v[34:37]
	v_mfma_f32_16x16x32_bf16 v[26:29], v[174:177], v[190:193], v[26:29]
	v_mfma_f32_16x16x32_bf16 v[18:21], v[166:169], v[198:201], v[18:21]
	v_mfma_f32_16x16x32_bf16 v[8:11], v[174:177], v[198:201], v[8:11]
	v_mfma_f32_16x16x32_bf16 v[4:7], v[166:169], v[224:227], v[4:7]
	v_mfma_f32_16x16x32_bf16 v[0:3], v[174:177], v[224:227], v[0:3]
	s_setprio 0
	s_barrier
	s_add_i32 s88, s88, 2
	s_add_u32 s50, s50, 0x100
	s_addc_u32 s51, s51, 0
	s_add_u32 s86, s86, 0x100
	s_addc_u32 s87, s87, 0
	s_cmp_gt_u32 s88, 29
	s_cbranch_scc1 .Lpz_B_exit
.LBB0_216:
	s_add_u32 s28, s50, 0xfff80080
	s_addc_u32 s29, s51, -1
	s_add_i32 s89, 0, 0x10000
	s_cmp_eq_u32 s88, 28
	s_cselect_b32 s53, s43, s29
	s_cselect_b32 s52, s84, s28
	s_cselect_b32 s29, s41, s87
	s_cselect_b32 s28, s85, s86
	s_add_i32 s92, 0, 0x14000
	v_add_u32_e32 v158, s89, v147
	v_add_u32_e32 v174, s92, v147
	ds_read_b128 v[142:145], v158
	ds_read_b128 v[150:153], v158 offset:1024
	ds_read_b128 v[154:157], v158 offset:2048
	ds_read_b128 v[158:161], v158 offset:3072
	ds_read_b128 v[162:165], v174
	ds_read_b128 v[166:169], v174 offset:1024
	ds_read_b128 v[170:173], v174 offset:2048
	ds_read_b128 v[174:177], v174 offset:3072
	s_add_i32 m0, s36, 0xc000
	ds_read_b128 v[178:181], v149
	ds_read_b128 v[182:185], v149 offset:1024
	ds_read_b128 v[186:189], v149 offset:2048
	ds_read_b128 v[190:193], v149 offset:3072
	ds_read_b128 v[194:197], v149 offset:4096
	ds_read_b128 v[198:201], v149 offset:5120
	ds_read_b128 v[202:205], v149 offset:6144
	ds_read_b128 v[224:227], v149 offset:7168
	global_load_lds_dwordx4 v138, s[50:51]
	s_add_i32 m0, s36, 0xe000
	s_nop 0
	global_load_lds_dwordx4 v140, s[50:51]
	s_waitcnt vmcnt(8)
	s_waitcnt lgkmcnt(0)
	s_barrier
	s_setprio 1
	s_waitcnt lgkmcnt(0)
	s_nop 0
	v_mfma_f32_16x16x32_bf16 v[126:129], v[142:145], v[178:181], v[126:129]
	v_mfma_f32_16x16x32_bf16 v[122:125], v[154:157], v[178:181], v[122:125]
	v_mfma_f32_16x16x32_bf16 v[118:121], v[142:145], v[186:189], v[118:121]
	v_mfma_f32_16x16x32_bf16 v[110:113], v[154:157], v[186:189], v[110:113]
	v_mfma_f32_16x16x32_bf16 v[102:105], v[142:145], v[194:197], v[102:105]
	v_mfma_f32_16x16x32_bf16 v[94:97], v[154:157], v[194:197], v[94:97]
	v_mfma_f32_16x16x32_bf16 v[86:89], v[142:145], v[202:205], v[86:89]
	v_mfma_f32_16x16x32_bf16 v[78:81], v[154:157], v[202:205], v[78:81]
	v_mfma_f32_16x16x32_bf16 v[126:129], v[150:153], v[182:185], v[126:129]
	v_mfma_f32_16x16x32_bf16 v[122:125], v[158:161], v[182:185], v[122:125]
	v_mfma_f32_16x16x32_bf16 v[118:121], v[150:153], v[190:193], v[118:121]
	v_mfma_f32_16x16x32_bf16 v[110:113], v[158:161], v[190:193], v[110:113]
	v_mfma_f32_16x16x32_bf16 v[102:105], v[150:153], v[198:201], v[102:105]
	v_mfma_f32_16x16x32_bf16 v[94:97], v[158:161], v[198:201], v[94:97]
	v_mfma_f32_16x16x32_bf16 v[86:89], v[150:153], v[224:227], v[86:89]
	v_mfma_f32_16x16x32_bf16 v[78:81], v[158:161], v[224:227], v[78:81]
	s_setprio 0
	s_setprio 1
	v_mfma_f32_16x16x32_bf16 v[114:117], v[162:165], v[178:181], v[114:117]
	v_mfma_f32_16x16x32_bf16 v[106:109], v[170:173], v[178:181], v[106:109]
	v_mfma_f32_16x16x32_bf16 v[98:101], v[162:165], v[186:189], v[98:101]
	v_mfma_f32_16x16x32_bf16 v[90:93], v[170:173], v[186:189], v[90:93]
	v_mfma_f32_16x16x32_bf16 v[82:85], v[162:165], v[194:197], v[82:85]
	v_mfma_f32_16x16x32_bf16 v[74:77], v[170:173], v[194:197], v[74:77]
	v_mfma_f32_16x16x32_bf16 v[70:73], v[162:165], v[202:205], v[70:73]
	v_mfma_f32_16x16x32_bf16 v[66:69], v[170:173], v[202:205], v[66:69]
	v_mfma_f32_16x16x32_bf16 v[114:117], v[166:169], v[182:185], v[114:117]
	v_mfma_f32_16x16x32_bf16 v[106:109], v[174:177], v[182:185], v[106:109]
	v_mfma_f32_16x16x32_bf16 v[98:101], v[166:169], v[190:193], v[98:101]
	v_mfma_f32_16x16x32_bf16 v[90:93], v[174:177], v[190:193], v[90:93]
	v_mfma_f32_16x16x32_bf16 v[82:85], v[166:169], v[198:201], v[82:85]
	v_mfma_f32_16x16x32_bf16 v[74:77], v[174:177], v[198:201], v[74:77]
	v_mfma_f32_16x16x32_bf16 v[70:73], v[166:169], v[224:227], v[70:73]
	v_mfma_f32_16x16x32_bf16 v[66:69], v[174:177], v[224:227], v[66:69]
	s_setprio 0
	s_barrier
	s_add_i32 s89, s89, s26
	s_mov_b32 m0, s89
	ds_read_b128 v[178:181], v149 offset:16384
	ds_read_b128 v[182:185], v149 offset:17408
	ds_read_b128 v[186:189], v149 offset:18432
	ds_read_b128 v[190:193], v149 offset:19456
	ds_read_b128 v[194:197], v149 offset:20480
	ds_read_b128 v[198:201], v149 offset:21504
	ds_read_b128 v[202:205], v149 offset:22528
	ds_read_b128 v[224:227], v149 offset:23552
	global_load_lds_dwordx4 v134, s[28:29]
	s_add_i32 m0, s89, 0x2000
	s_add_u32 s90, s28, 0x80000
	s_addc_u32 s91, s29, 0
	s_add_i32 s89, s92, s26
	global_load_lds_dwordx4 v130, s[28:29]
	s_mov_b32 m0, s89
	v_lshl_add_u64 v[232:233], s[52:53], 0, v[132:133]
	global_load_lds_dwordx4 v134, s[90:91]
	s_add_i32 m0, s89, 0x2000
	s_nop 0
	global_load_lds_dwordx4 v130, s[90:91]
	v_lshl_add_u64 v[230:231], s[52:53], 0, v[136:137]
	s_mov_b32 m0, s36
	s_nop 0
	global_load_lds_dwordx4 v[230:231], off
	s_mov_b32 m0, s37
	s_nop 0
	global_load_lds_dwordx4 v[232:233], off
	s_waitcnt vmcnt(8)
	s_waitcnt lgkmcnt(0)
	s_barrier
	s_setprio 1
	s_waitcnt lgkmcnt(0)
	s_nop 0
	v_mfma_f32_16x16x32_bf16 v[62:65], v[142:145], v[178:181], v[62:65]
	v_mfma_f32_16x16x32_bf16 v[58:61], v[154:157], v[178:181], v[58:61]
	v_mfma_f32_16x16x32_bf16 v[54:57], v[142:145], v[186:189], v[54:57]
	v_mfma_f32_16x16x32_bf16 v[46:49], v[154:157], v[186:189], v[46:49]
	v_mfma_f32_16x16x32_bf16 v[38:41], v[142:145], v[194:197], v[38:41]
	v_mfma_f32_16x16x32_bf16 v[30:33], v[154:157], v[194:197], v[30:33]
	v_mfma_f32_16x16x32_bf16 v[22:25], v[142:145], v[202:205], v[22:25]
	v_mfma_f32_16x16x32_bf16 v[12:15], v[154:157], v[202:205], v[12:15]
	v_mfma_f32_16x16x32_bf16 v[62:65], v[150:153], v[182:185], v[62:65]
	v_mfma_f32_16x16x32_bf16 v[58:61], v[158:161], v[182:185], v[58:61]
	v_mfma_f32_16x16x32_bf16 v[54:57], v[150:153], v[190:193], v[54:57]
	v_mfma_f32_16x16x32_bf16 v[46:49], v[158:161], v[190:193], v[46:49]
	v_mfma_f32_16x16x32_bf16 v[38:41], v[150:153], v[198:201], v[38:41]
	v_mfma_f32_16x16x32_bf16 v[30:33], v[158:161], v[198:201], v[30:33]
	v_mfma_f32_16x16x32_bf16 v[22:25], v[150:153], v[224:227], v[22:25]
	v_mfma_f32_16x16x32_bf16 v[12:15], v[158:161], v[224:227], v[12:15]
	s_setprio 0
	s_setprio 1
	v_mfma_f32_16x16x32_bf16 v[50:53], v[162:165], v[178:181], v[50:53]
	v_mfma_f32_16x16x32_bf16 v[42:45], v[170:173], v[178:181], v[42:45]
	v_mfma_f32_16x16x32_bf16 v[34:37], v[162:165], v[186:189], v[34:37]
	v_mfma_f32_16x16x32_bf16 v[26:29], v[170:173], v[186:189], v[26:29]
	v_mfma_f32_16x16x32_bf16 v[18:21], v[162:165], v[194:197], v[18:21]
	v_mfma_f32_16x16x32_bf16 v[8:11], v[170:173], v[194:197], v[8:11]
	v_mfma_f32_16x16x32_bf16 v[4:7], v[162:165], v[202:205], v[4:7]
	v_mfma_f32_16x16x32_bf16 v[0:3], v[170:173], v[202:205], v[0:3]
	v_mfma_f32_16x16x32_bf16 v[50:53], v[166:169], v[182:185], v[50:53]
	v_mfma_f32_16x16x32_bf16 v[42:45], v[174:177], v[182:185], v[42:45]
	v_mfma_f32_16x16x32_bf16 v[34:37], v[166:169], v[190:193], v[34:37]
	v_mfma_f32_16x16x32_bf16 v[26:29], v[174:177], v[190:193], v[26:29]
	v_mfma_f32_16x16x32_bf16 v[18:21], v[166:169], v[198:201], v[18:21]
	v_mfma_f32_16x16x32_bf16 v[8:11], v[174:177], v[198:201], v[8:11]
	v_mfma_f32_16x16x32_bf16 v[4:7], v[166:169], v[224:227], v[4:7]
	v_mfma_f32_16x16x32_bf16 v[0:3], v[174:177], v[224:227], v[0:3]
	s_setprio 0
	s_barrier
	s_add_i32 s89, 0, 0x18000
	s_add_i32 s90, 0, 0x1c000
	v_add_u32_e32 v158, s89, v147
	v_add_u32_e32 v174, s90, v147
	ds_read_b128 v[142:145], v158
	ds_read_b128 v[150:153], v158 offset:1024
	ds_read_b128 v[154:157], v158 offset:2048
	ds_read_b128 v[158:161], v158 offset:3072
	ds_read_b128 v[162:165], v174
	ds_read_b128 v[166:169], v174 offset:1024
	ds_read_b128 v[170:173], v174 offset:2048
	ds_read_b128 v[174:177], v174 offset:3072
	s_add_u32 s52, s52, 0x80000
	s_addc_u32 s53, s53, 0
	s_mov_b32 m0, s49
	ds_read_b128 v[178:181], v149 offset:32768
	ds_read_b128 v[182:185], v149 offset:33792
	ds_read_b128 v[186:189], v149 offset:34816
	ds_read_b128 v[190:193], v149 offset:35840
	ds_read_b128 v[194:197], v149 offset:36864
	ds_read_b128 v[198:201], v149 offset:37888
	ds_read_b128 v[202:205], v149 offset:38912
	ds_read_b128 v[224:227], v149 offset:39936
	global_load_lds_dwordx4 v136, s[52:53]
	s_mov_b32 m0, s56
	s_nop 0
	global_load_lds_dwordx4 v132, s[52:53]
	s_waitcnt vmcnt(8)
	s_waitcnt lgkmcnt(0)
	s_barrier
	s_setprio 1
	s_waitcnt lgkmcnt(0)
	s_nop 0
	v_mfma_f32_16x16x32_bf16 v[126:129], v[142:145], v[178:181], v[126:129]
	v_mfma_f32_16x16x32_bf16 v[122:125], v[154:157], v[178:181], v[122:125]
	v_mfma_f32_16x16x32_bf16 v[118:121], v[142:145], v[186:189], v[118:121]
	v_mfma_f32_16x16x32_bf16 v[110:113], v[154:157], v[186:189], v[110:113]
	v_mfma_f32_16x16x32_bf16 v[102:105], v[142:145], v[194:197], v[102:105]
	v_mfma_f32_16x16x32_bf16 v[94:97], v[154:157], v[194:197], v[94:97]
	v_mfma_f32_16x16x32_bf16 v[86:89], v[142:145], v[202:205], v[86:89]
	v_mfma_f32_16x16x32_bf16 v[78:81], v[154:157], v[202:205], v[78:81]
	v_mfma_f32_16x16x32_bf16 v[126:129], v[150:153], v[182:185], v[126:129]
	v_mfma_f32_16x16x32_bf16 v[122:125], v[158:161], v[182:185], v[122:125]
	v_mfma_f32_16x16x32_bf16 v[118:121], v[150:153], v[190:193], v[118:121]
	v_mfma_f32_16x16x32_bf16 v[110:113], v[158:161], v[190:193], v[110:113]
	v_mfma_f32_16x16x32_bf16 v[102:105], v[150:153], v[198:201], v[102:105]
	v_mfma_f32_16x16x32_bf16 v[94:97], v[158:161], v[198:201], v[94:97]
	v_mfma_f32_16x16x32_bf16 v[86:89], v[150:153], v[224:227], v[86:89]
	v_mfma_f32_16x16x32_bf16 v[78:81], v[158:161], v[224:227], v[78:81]
	s_setprio 0
	s_setprio 1
	v_mfma_f32_16x16x32_bf16 v[114:117], v[162:165], v[178:181], v[114:117]
	v_mfma_f32_16x16x32_bf16 v[106:109], v[170:173], v[178:181], v[106:109]
	v_mfma_f32_16x16x32_bf16 v[98:101], v[162:165], v[186:189], v[98:101]
	v_mfma_f32_16x16x32_bf16 v[90:93], v[170:173], v[186:189], v[90:93]
	v_mfma_f32_16x16x32_bf16 v[82:85], v[162:165], v[194:197], v[82:85]
	v_mfma_f32_16x16x32_bf16 v[74:77], v[170:173], v[194:197], v[74:77]
	v_mfma_f32_16x16x32_bf16 v[70:73], v[162:165], v[202:205], v[70:73]
	v_mfma_f32_16x16x32_bf16 v[66:69], v[170:173], v[202:205], v[66:69]
	v_mfma_f32_16x16x32_bf16 v[114:117], v[166:169], v[182:185], v[114:117]
	v_mfma_f32_16x16x32_bf16 v[106:109], v[174:177], v[182:185], v[106:109]
	v_mfma_f32_16x16x32_bf16 v[98:101], v[166:169], v[190:193], v[98:101]
	v_mfma_f32_16x16x32_bf16 v[90:93], v[174:177], v[190:193], v[90:93]
	v_mfma_f32_16x16x32_bf16 v[82:85], v[166:169], v[198:201], v[82:85]
	v_mfma_f32_16x16x32_bf16 v[74:77], v[174:177], v[198:201], v[74:77]
	v_mfma_f32_16x16x32_bf16 v[70:73], v[166:169], v[224:227], v[70:73]
	v_mfma_f32_16x16x32_bf16 v[66:69], v[174:177], v[224:227], v[66:69]
	s_setprio 0
	s_barrier
	s_add_i32 s52, s89, s26
	s_add_u32 s28, s28, 0x80
	s_addc_u32 s29, s29, 0
	s_mov_b32 m0, s52
	ds_read_b128 v[178:181], v149 offset:49152
	ds_read_b128 v[182:185], v149 offset:50176
	ds_read_b128 v[186:189], v149 offset:51200
	ds_read_b128 v[190:193], v149 offset:52224
	ds_read_b128 v[194:197], v149 offset:53248
	ds_read_b128 v[198:201], v149 offset:54272
	ds_read_b128 v[202:205], v149 offset:55296
	ds_read_b128 v[224:227], v149 offset:56320
	global_load_lds_dwordx4 v134, s[28:29]
	s_add_i32 m0, s52, 0x2000
	s_add_i32 s52, s90, s26
	global_load_lds_dwordx4 v130, s[28:29]
	s_add_u32 s28, s28, 0x80000
	s_addc_u32 s29, s29, 0
	s_mov_b32 m0, s52
	s_nop 0
	global_load_lds_dwordx4 v134, s[28:29]
	s_add_i32 m0, s52, 0x2000
	s_nop 0
	global_load_lds_dwordx4 v130, s[28:29]
	v_lshl_add_u64 v[206:207], v[230:231], 0, s[34:35]
	s_mov_b32 m0, s57
	s_nop 0
	global_load_lds_dwordx4 v[206:207], off
	v_lshl_add_u64 v[206:207], v[232:233], 0, s[34:35]
	s_mov_b32 m0, s58
	s_nop 0
	global_load_lds_dwordx4 v[206:207], off
	s_waitcnt vmcnt(8)
	s_waitcnt lgkmcnt(0)
	s_barrier
	s_setprio 1
	s_waitcnt lgkmcnt(0)
	s_nop 0
	v_mfma_f32_16x16x32_bf16 v[62:65], v[142:145], v[178:181], v[62:65]
	v_mfma_f32_16x16x32_bf16 v[58:61], v[154:157], v[178:181], v[58:61]
	v_mfma_f32_16x16x32_bf16 v[54:57], v[142:145], v[186:189], v[54:57]
	v_mfma_f32_16x16x32_bf16 v[46:49], v[154:157], v[186:189], v[46:49]
	v_mfma_f32_16x16x32_bf16 v[38:41], v[142:145], v[194:197], v[38:41]
	v_mfma_f32_16x16x32_bf16 v[30:33], v[154:157], v[194:197], v[30:33]
	v_mfma_f32_16x16x32_bf16 v[22:25], v[142:145], v[202:205], v[22:25]
	v_mfma_f32_16x16x32_bf16 v[12:15], v[154:157], v[202:205], v[12:15]
	v_mfma_f32_16x16x32_bf16 v[62:65], v[150:153], v[182:185], v[62:65]
	v_mfma_f32_16x16x32_bf16 v[58:61], v[158:161], v[182:185], v[58:61]
	v_mfma_f32_16x16x32_bf16 v[54:57], v[150:153], v[190:193], v[54:57]
	v_mfma_f32_16x16x32_bf16 v[46:49], v[158:161], v[190:193], v[46:49]
	v_mfma_f32_16x16x32_bf16 v[38:41], v[150:153], v[198:201], v[38:41]
	v_mfma_f32_16x16x32_bf16 v[30:33], v[158:161], v[198:201], v[30:33]
	v_mfma_f32_16x16x32_bf16 v[22:25], v[150:153], v[224:227], v[22:25]
	v_mfma_f32_16x16x32_bf16 v[12:15], v[158:161], v[224:227], v[12:15]
	s_setprio 0
	s_setprio 1
	v_mfma_f32_16x16x32_bf16 v[50:53], v[162:165], v[178:181], v[50:53]
	v_mfma_f32_16x16x32_bf16 v[42:45], v[170:173], v[178:181], v[42:45]
	v_mfma_f32_16x16x32_bf16 v[34:37], v[162:165], v[186:189], v[34:37]
	v_mfma_f32_16x16x32_bf16 v[26:29], v[170:173], v[186:189], v[26:29]
	v_mfma_f32_16x16x32_bf16 v[18:21], v[162:165], v[194:197], v[18:21]
	v_mfma_f32_16x16x32_bf16 v[8:11], v[170:173], v[194:197], v[8:11]
	v_mfma_f32_16x16x32_bf16 v[4:7], v[162:165], v[202:205], v[4:7]
	v_mfma_f32_16x16x32_bf16 v[0:3], v[170:173], v[202:205], v[0:3]
	v_mfma_f32_16x16x32_bf16 v[50:53], v[166:169], v[182:185], v[50:53]
	v_mfma_f32_16x16x32_bf16 v[42:45], v[174:177], v[182:185], v[42:45]
	v_mfma_f32_16x16x32_bf16 v[34:37], v[166:169], v[190:193], v[34:37]
	v_mfma_f32_16x16x32_bf16 v[26:29], v[174:177], v[190:193], v[26:29]
	v_mfma_f32_16x16x32_bf16 v[18:21], v[166:169], v[198:201], v[18:21]
	v_mfma_f32_16x16x32_bf16 v[8:11], v[174:177], v[198:201], v[8:11]
	v_mfma_f32_16x16x32_bf16 v[4:7], v[166:169], v[224:227], v[4:7]
	v_mfma_f32_16x16x32_bf16 v[0:3], v[174:177], v[224:227], v[0:3]
	s_setprio 0
	s_barrier
	s_add_i32 s88, s88, 2
	s_add_u32 s50, s50, 0x100
	s_addc_u32 s51, s51, 0
	s_add_u32 s86, s86, 0x100
	s_addc_u32 s87, s87, 0
	s_cmp_gt_u32 s88, 29
	s_cbranch_scc0 .LBB0_216

.LBB0_648:
	s_ashr_i32 s19, s18, 31
	s_lshl_b64 s[28:29], s[18:19], 18
	v_readlane_b32 s19, v255, 10
	s_add_u32 s42, s19, s28
	v_readlane_b32 s19, v255, 11
	s_addc_u32 s43, s19, s29
	s_and_b64 s[28:29], s[40:41], exec
	s_cselect_b32 s19, s43, s47
	s_cselect_b32 s23, s42, s46
	s_add_u32 s40, s48, 0x80080
	s_addc_u32 s41, s49, 0
	s_add_u32 s48, s46, 0x100
	s_addc_u32 s49, s47, 0
	s_mov_b32 s87, -2
	s_add_u32 s28, s40, 0xfff80080
	s_addc_u32 s29, s41, -1
	s_add_i32 s88, 0, 0x10000
	s_cmp_eq_u32 s87, 4
	s_cselect_b32 s47, s27, s29
	s_cselect_b32 s46, s26, s28
	v_add_u32_e32 v140, s88, v143
	s_cselect_b32 s29, s19, s49
	s_cselect_b32 s28, s23, s48
	s_add_i32 s90, 0, 0x14000
	ds_read_b128 v[146:149], v140
	ds_read_b128 v[150:153], v140 offset:1024
	ds_read_b128 v[154:157], v140 offset:2048
	ds_read_b128 v[158:161], v140 offset:3072
	v_add_u32_e32 v140, s90, v143
	ds_read_b128 v[162:165], v140
	ds_read_b128 v[166:169], v140 offset:1024
	ds_read_b128 v[170:173], v140 offset:2048
	ds_read_b128 v[174:177], v140 offset:3072
	s_add_i32 m0, s45, 0xc000
	ds_read_b128 v[178:181], v145
	ds_read_b128 v[182:185], v145 offset:1024
	ds_read_b128 v[186:189], v145 offset:2048
	ds_read_b128 v[190:193], v145 offset:3072
	ds_read_b128 v[194:197], v145 offset:4096
	ds_read_b128 v[198:201], v145 offset:5120
	ds_read_b128 v[202:205], v145 offset:6144
	ds_read_b128 v[224:227], v145 offset:7168
	global_load_lds_dwordx4 v136, s[40:41]
	s_add_i32 m0, s45, 0xe000
	s_nop 0
	global_load_lds_dwordx4 v138, s[40:41]
	s_waitcnt vmcnt(8)
	s_waitcnt lgkmcnt(0)
	s_barrier
	s_setprio 1
	s_waitcnt lgkmcnt(0)
	v_mfma_f32_16x16x32_bf16 v[126:129], v[146:149], v[178:181], 0
	v_mfma_f32_16x16x32_bf16 v[122:125], v[154:157], v[178:181], 0
	v_mfma_f32_16x16x32_bf16 v[118:121], v[146:149], v[186:189], 0
	v_mfma_f32_16x16x32_bf16 v[110:113], v[154:157], v[186:189], 0
	v_mfma_f32_16x16x32_bf16 v[102:105], v[146:149], v[194:197], 0
	v_mfma_f32_16x16x32_bf16 v[94:97], v[154:157], v[194:197], 0
	v_mfma_f32_16x16x32_bf16 v[86:89], v[146:149], v[202:205], 0
	v_mfma_f32_16x16x32_bf16 v[78:81], v[154:157], v[202:205], 0
	v_mfma_f32_16x16x32_bf16 v[126:129], v[150:153], v[182:185], v[126:129]
	v_mfma_f32_16x16x32_bf16 v[122:125], v[158:161], v[182:185], v[122:125]
	v_mfma_f32_16x16x32_bf16 v[118:121], v[150:153], v[190:193], v[118:121]
	v_mfma_f32_16x16x32_bf16 v[110:113], v[158:161], v[190:193], v[110:113]
	v_mfma_f32_16x16x32_bf16 v[102:105], v[150:153], v[198:201], v[102:105]
	v_mfma_f32_16x16x32_bf16 v[94:97], v[158:161], v[198:201], v[94:97]
	v_mfma_f32_16x16x32_bf16 v[86:89], v[150:153], v[224:227], v[86:89]
	v_mfma_f32_16x16x32_bf16 v[78:81], v[158:161], v[224:227], v[78:81]
	s_setprio 0
	s_setprio 1
	v_mfma_f32_16x16x32_bf16 v[114:117], v[162:165], v[178:181], 0
	v_mfma_f32_16x16x32_bf16 v[106:109], v[170:173], v[178:181], 0
	v_mfma_f32_16x16x32_bf16 v[98:101], v[162:165], v[186:189], 0
	v_mfma_f32_16x16x32_bf16 v[90:93], v[170:173], v[186:189], 0
	v_mfma_f32_16x16x32_bf16 v[82:85], v[162:165], v[194:197], 0
	v_mfma_f32_16x16x32_bf16 v[74:77], v[170:173], v[194:197], 0
	v_mfma_f32_16x16x32_bf16 v[70:73], v[162:165], v[202:205], 0
	v_mfma_f32_16x16x32_bf16 v[66:69], v[170:173], v[202:205], 0
	v_mfma_f32_16x16x32_bf16 v[114:117], v[166:169], v[182:185], v[114:117]
	v_mfma_f32_16x16x32_bf16 v[106:109], v[174:177], v[182:185], v[106:109]
	v_mfma_f32_16x16x32_bf16 v[98:101], v[166:169], v[190:193], v[98:101]
	v_mfma_f32_16x16x32_bf16 v[90:93], v[174:177], v[190:193], v[90:93]
	v_mfma_f32_16x16x32_bf16 v[82:85], v[166:169], v[198:201], v[82:85]
	v_mfma_f32_16x16x32_bf16 v[74:77], v[174:177], v[198:201], v[74:77]
	v_mfma_f32_16x16x32_bf16 v[70:73], v[166:169], v[224:227], v[70:73]
	v_mfma_f32_16x16x32_bf16 v[66:69], v[174:177], v[224:227], v[66:69]
	s_setprio 0
	s_barrier
	s_add_i32 s88, s88, s37
	s_mov_b32 m0, s88
	ds_read_b128 v[178:181], v145 offset:16384
	ds_read_b128 v[182:185], v145 offset:17408
	ds_read_b128 v[186:189], v145 offset:18432
	ds_read_b128 v[190:193], v145 offset:19456
	ds_read_b128 v[194:197], v145 offset:20480
	ds_read_b128 v[198:201], v145 offset:21504
	ds_read_b128 v[202:205], v145 offset:22528
	ds_read_b128 v[224:227], v145 offset:23552
	global_load_lds_dwordx4 v16, s[28:29]
	s_add_i32 m0, s88, 0x2000
	s_add_u32 s88, s28, 0x20000
	s_addc_u32 s89, s29, 0
	s_add_i32 s90, s90, s37
	global_load_lds_dwordx4 v130, s[28:29]
	s_mov_b32 m0, s90
	v_lshl_add_u64 v[230:231], s[46:47], 0, v[132:133]
	global_load_lds_dwordx4 v16, s[88:89]
	s_add_i32 m0, s90, 0x2000
	s_nop 0
	global_load_lds_dwordx4 v130, s[88:89]
	v_lshl_add_u64 v[228:229], s[46:47], 0, v[134:135]
	s_mov_b32 m0, s45
	s_nop 0
	global_load_lds_dwordx4 v[228:229], off
	s_mov_b32 m0, s53
	s_nop 0
	global_load_lds_dwordx4 v[230:231], off
	s_waitcnt vmcnt(8)
	s_waitcnt lgkmcnt(0)
	s_barrier
	s_setprio 1
	s_waitcnt lgkmcnt(0)
	s_nop 0
	v_mfma_f32_16x16x32_bf16 v[62:65], v[146:149], v[178:181], 0
	v_mfma_f32_16x16x32_bf16 v[58:61], v[154:157], v[178:181], 0
	v_mfma_f32_16x16x32_bf16 v[54:57], v[146:149], v[186:189], 0
	v_mfma_f32_16x16x32_bf16 v[46:49], v[154:157], v[186:189], 0
	v_mfma_f32_16x16x32_bf16 v[38:41], v[146:149], v[194:197], 0
	v_mfma_f32_16x16x32_bf16 v[30:33], v[154:157], v[194:197], 0
	v_mfma_f32_16x16x32_bf16 v[22:25], v[146:149], v[202:205], 0
	v_mfma_f32_16x16x32_bf16 v[12:15], v[154:157], v[202:205], 0
	v_mfma_f32_16x16x32_bf16 v[62:65], v[150:153], v[182:185], v[62:65]
	v_mfma_f32_16x16x32_bf16 v[58:61], v[158:161], v[182:185], v[58:61]
	v_mfma_f32_16x16x32_bf16 v[54:57], v[150:153], v[190:193], v[54:57]
	v_mfma_f32_16x16x32_bf16 v[46:49], v[158:161], v[190:193], v[46:49]
	v_mfma_f32_16x16x32_bf16 v[38:41], v[150:153], v[198:201], v[38:41]
	v_mfma_f32_16x16x32_bf16 v[30:33], v[158:161], v[198:201], v[30:33]
	v_mfma_f32_16x16x32_bf16 v[22:25], v[150:153], v[224:227], v[22:25]
	v_mfma_f32_16x16x32_bf16 v[12:15], v[158:161], v[224:227], v[12:15]
	s_setprio 0
	s_setprio 1
	v_mfma_f32_16x16x32_bf16 v[50:53], v[162:165], v[178:181], 0
	v_mfma_f32_16x16x32_bf16 v[42:45], v[170:173], v[178:181], 0
	v_mfma_f32_16x16x32_bf16 v[34:37], v[162:165], v[186:189], 0
	v_mfma_f32_16x16x32_bf16 v[26:29], v[170:173], v[186:189], 0
	v_mfma_f32_16x16x32_bf16 v[18:21], v[162:165], v[194:197], 0
	v_mfma_f32_16x16x32_bf16 v[8:11], v[170:173], v[194:197], 0
	v_mfma_f32_16x16x32_bf16 v[4:7], v[162:165], v[202:205], 0
	v_mfma_f32_16x16x32_bf16 v[0:3], v[170:173], v[202:205], 0
	v_mfma_f32_16x16x32_bf16 v[50:53], v[166:169], v[182:185], v[50:53]
	v_mfma_f32_16x16x32_bf16 v[42:45], v[174:177], v[182:185], v[42:45]
	v_mfma_f32_16x16x32_bf16 v[34:37], v[166:169], v[190:193], v[34:37]
	v_mfma_f32_16x16x32_bf16 v[26:29], v[174:177], v[190:193], v[26:29]
	v_mfma_f32_16x16x32_bf16 v[18:21], v[166:169], v[198:201], v[18:21]
	v_mfma_f32_16x16x32_bf16 v[8:11], v[174:177], v[198:201], v[8:11]
	v_mfma_f32_16x16x32_bf16 v[4:7], v[166:169], v[224:227], v[4:7]
	v_mfma_f32_16x16x32_bf16 v[0:3], v[174:177], v[224:227], v[0:3]
	s_setprio 0
	s_barrier
	s_add_i32 s88, 0, 0x18000
	s_add_i32 s89, 0, 0x1c000
	v_add_u32_e32 v158, s88, v143
	v_add_u32_e32 v174, s89, v143
	ds_read_b128 v[146:149], v158
	ds_read_b128 v[150:153], v158 offset:1024
	ds_read_b128 v[154:157], v158 offset:2048
	ds_read_b128 v[158:161], v158 offset:3072
	ds_read_b128 v[162:165], v174
	ds_read_b128 v[166:169], v174 offset:1024
	ds_read_b128 v[170:173], v174 offset:2048
	ds_read_b128 v[174:177], v174 offset:3072
	s_add_u32 s46, s46, 0x80000
	s_addc_u32 s47, s47, 0
	s_mov_b32 m0, s58
	ds_read_b128 v[178:181], v145 offset:32768
	ds_read_b128 v[182:185], v145 offset:33792
	ds_read_b128 v[186:189], v145 offset:34816
	ds_read_b128 v[190:193], v145 offset:35840
	ds_read_b128 v[194:197], v145 offset:36864
	ds_read_b128 v[198:201], v145 offset:37888
	ds_read_b128 v[202:205], v145 offset:38912
	ds_read_b128 v[224:227], v145 offset:39936
	global_load_lds_dwordx4 v134, s[46:47]
	s_mov_b32 m0, s59
	s_nop 0
	global_load_lds_dwordx4 v132, s[46:47]
	s_waitcnt vmcnt(8)
	s_waitcnt lgkmcnt(0)
	s_barrier
	s_setprio 1
	s_waitcnt lgkmcnt(0)
	s_nop 0
	v_mfma_f32_16x16x32_bf16 v[126:129], v[146:149], v[178:181], v[126:129]
	v_mfma_f32_16x16x32_bf16 v[122:125], v[154:157], v[178:181], v[122:125]
	v_mfma_f32_16x16x32_bf16 v[118:121], v[146:149], v[186:189], v[118:121]
	v_mfma_f32_16x16x32_bf16 v[110:113], v[154:157], v[186:189], v[110:113]
	v_mfma_f32_16x16x32_bf16 v[102:105], v[146:149], v[194:197], v[102:105]
	v_mfma_f32_16x16x32_bf16 v[94:97], v[154:157], v[194:197], v[94:97]
	v_mfma_f32_16x16x32_bf16 v[86:89], v[146:149], v[202:205], v[86:89]
	v_mfma_f32_16x16x32_bf16 v[78:81], v[154:157], v[202:205], v[78:81]
	v_mfma_f32_16x16x32_bf16 v[126:129], v[150:153], v[182:185], v[126:129]
	v_mfma_f32_16x16x32_bf16 v[122:125], v[158:161], v[182:185], v[122:125]
	v_mfma_f32_16x16x32_bf16 v[118:121], v[150:153], v[190:193], v[118:121]
	v_mfma_f32_16x16x32_bf16 v[110:113], v[158:161], v[190:193], v[110:113]
	v_mfma_f32_16x16x32_bf16 v[102:105], v[150:153], v[198:201], v[102:105]
	v_mfma_f32_16x16x32_bf16 v[94:97], v[158:161], v[198:201], v[94:97]
	v_mfma_f32_16x16x32_bf16 v[86:89], v[150:153], v[224:227], v[86:89]
	v_mfma_f32_16x16x32_bf16 v[78:81], v[158:161], v[224:227], v[78:81]
	s_setprio 0
	s_setprio 1
	v_mfma_f32_16x16x32_bf16 v[114:117], v[162:165], v[178:181], v[114:117]
	v_mfma_f32_16x16x32_bf16 v[106:109], v[170:173], v[178:181], v[106:109]
	v_mfma_f32_16x16x32_bf16 v[98:101], v[162:165], v[186:189], v[98:101]
	v_mfma_f32_16x16x32_bf16 v[90:93], v[170:173], v[186:189], v[90:93]
	v_mfma_f32_16x16x32_bf16 v[82:85], v[162:165], v[194:197], v[82:85]
	v_mfma_f32_16x16x32_bf16 v[74:77], v[170:173], v[194:197], v[74:77]
	v_mfma_f32_16x16x32_bf16 v[70:73], v[162:165], v[202:205], v[70:73]
	v_mfma_f32_16x16x32_bf16 v[66:69], v[170:173], v[202:205], v[66:69]
	v_mfma_f32_16x16x32_bf16 v[114:117], v[166:169], v[182:185], v[114:117]
	v_mfma_f32_16x16x32_bf16 v[106:109], v[174:177], v[182:185], v[106:109]
	v_mfma_f32_16x16x32_bf16 v[98:101], v[166:169], v[190:193], v[98:101]
	v_mfma_f32_16x16x32_bf16 v[90:93], v[174:177], v[190:193], v[90:93]
	v_mfma_f32_16x16x32_bf16 v[82:85], v[166:169], v[198:201], v[82:85]
	v_mfma_f32_16x16x32_bf16 v[74:77], v[174:177], v[198:201], v[74:77]
	v_mfma_f32_16x16x32_bf16 v[70:73], v[166:169], v[224:227], v[70:73]
	v_mfma_f32_16x16x32_bf16 v[66:69], v[174:177], v[224:227], v[66:69]
	s_setprio 0
	s_barrier
	s_add_i32 s46, s88, s37
	s_add_u32 s28, s28, 0x80
	s_addc_u32 s29, s29, 0
	s_mov_b32 m0, s46
	ds_read_b128 v[178:181], v145 offset:49152
	ds_read_b128 v[182:185], v145 offset:50176
	ds_read_b128 v[186:189], v145 offset:51200
	ds_read_b128 v[190:193], v145 offset:52224
	ds_read_b128 v[194:197], v145 offset:53248
	ds_read_b128 v[198:201], v145 offset:54272
	ds_read_b128 v[202:205], v145 offset:55296
	ds_read_b128 v[224:227], v145 offset:56320
	global_load_lds_dwordx4 v16, s[28:29]
	s_add_i32 m0, s46, 0x2000
	s_add_i32 s46, s89, s37
	global_load_lds_dwordx4 v130, s[28:29]
	s_add_u32 s28, s28, 0x20000
	s_addc_u32 s29, s29, 0
	s_mov_b32 m0, s46
	s_nop 0
	global_load_lds_dwordx4 v16, s[28:29]
	s_add_i32 m0, s46, 0x2000
	s_nop 0
	global_load_lds_dwordx4 v130, s[28:29]
	v_lshl_add_u64 v[140:141], v[228:229], 0, s[34:35]
	s_mov_b32 m0, s83
	s_nop 0
	global_load_lds_dwordx4 v[140:141], off
	v_lshl_add_u64 v[140:141], v[230:231], 0, s[34:35]
	s_mov_b32 m0, s84
	s_nop 0
	global_load_lds_dwordx4 v[140:141], off
	s_waitcnt vmcnt(8)
	s_waitcnt lgkmcnt(0)
	s_barrier
	s_setprio 1
	s_waitcnt lgkmcnt(0)
	s_nop 0
	v_mfma_f32_16x16x32_bf16 v[62:65], v[146:149], v[178:181], v[62:65]
	v_mfma_f32_16x16x32_bf16 v[58:61], v[154:157], v[178:181], v[58:61]
	v_mfma_f32_16x16x32_bf16 v[54:57], v[146:149], v[186:189], v[54:57]
	v_mfma_f32_16x16x32_bf16 v[46:49], v[154:157], v[186:189], v[46:49]
	v_mfma_f32_16x16x32_bf16 v[38:41], v[146:149], v[194:197], v[38:41]
	v_mfma_f32_16x16x32_bf16 v[30:33], v[154:157], v[194:197], v[30:33]
	v_mfma_f32_16x16x32_bf16 v[22:25], v[146:149], v[202:205], v[22:25]
	v_mfma_f32_16x16x32_bf16 v[12:15], v[154:157], v[202:205], v[12:15]
	v_mfma_f32_16x16x32_bf16 v[62:65], v[150:153], v[182:185], v[62:65]
	v_mfma_f32_16x16x32_bf16 v[58:61], v[158:161], v[182:185], v[58:61]
	v_mfma_f32_16x16x32_bf16 v[54:57], v[150:153], v[190:193], v[54:57]
	v_mfma_f32_16x16x32_bf16 v[46:49], v[158:161], v[190:193], v[46:49]
	v_mfma_f32_16x16x32_bf16 v[38:41], v[150:153], v[198:201], v[38:41]
	v_mfma_f32_16x16x32_bf16 v[30:33], v[158:161], v[198:201], v[30:33]
	v_mfma_f32_16x16x32_bf16 v[22:25], v[150:153], v[224:227], v[22:25]
	v_mfma_f32_16x16x32_bf16 v[12:15], v[158:161], v[224:227], v[12:15]
	s_setprio 0
	s_setprio 1
	v_mfma_f32_16x16x32_bf16 v[50:53], v[162:165], v[178:181], v[50:53]
	v_mfma_f32_16x16x32_bf16 v[42:45], v[170:173], v[178:181], v[42:45]
	v_mfma_f32_16x16x32_bf16 v[34:37], v[162:165], v[186:189], v[34:37]
	v_mfma_f32_16x16x32_bf16 v[26:29], v[170:173], v[186:189], v[26:29]
	v_mfma_f32_16x16x32_bf16 v[18:21], v[162:165], v[194:197], v[18:21]
	v_mfma_f32_16x16x32_bf16 v[8:11], v[170:173], v[194:197], v[8:11]
	v_mfma_f32_16x16x32_bf16 v[4:7], v[162:165], v[202:205], v[4:7]
	v_mfma_f32_16x16x32_bf16 v[0:3], v[170:173], v[202:205], v[0:3]
	v_mfma_f32_16x16x32_bf16 v[50:53], v[166:169], v[182:185], v[50:53]
	v_mfma_f32_16x16x32_bf16 v[42:45], v[174:177], v[182:185], v[42:45]
	v_mfma_f32_16x16x32_bf16 v[34:37], v[166:169], v[190:193], v[34:37]
	v_mfma_f32_16x16x32_bf16 v[26:29], v[174:177], v[190:193], v[26:29]
	v_mfma_f32_16x16x32_bf16 v[18:21], v[166:169], v[198:201], v[18:21]
	v_mfma_f32_16x16x32_bf16 v[8:11], v[174:177], v[198:201], v[8:11]
	v_mfma_f32_16x16x32_bf16 v[4:7], v[166:169], v[224:227], v[4:7]
	v_mfma_f32_16x16x32_bf16 v[0:3], v[174:177], v[224:227], v[0:3]
	s_setprio 0
	s_barrier
	s_add_i32 s87, s87, 2
	s_add_u32 s40, s40, 0x100
	s_addc_u32 s41, s41, 0
	s_add_u32 s48, s48, 0x100
	s_addc_u32 s49, s49, 0
	s_cmp_gt_u32 s87, 5
	s_cbranch_scc1 .Lpz_E_exit
.LBB0_649:
	s_add_u32 s28, s40, 0xfff80080
	s_addc_u32 s29, s41, -1
	s_add_i32 s88, 0, 0x10000
	s_cmp_eq_u32 s87, 4
	s_cselect_b32 s47, s27, s29
	s_cselect_b32 s46, s26, s28
	v_add_u32_e32 v140, s88, v143
	s_cselect_b32 s29, s19, s49
	s_cselect_b32 s28, s23, s48
	s_add_i32 s90, 0, 0x14000
	ds_read_b128 v[146:149], v140
	ds_read_b128 v[150:153], v140 offset:1024
	ds_read_b128 v[154:157], v140 offset:2048
	ds_read_b128 v[158:161], v140 offset:3072
	v_add_u32_e32 v140, s90, v143
	ds_read_b128 v[162:165], v140
	ds_read_b128 v[166:169], v140 offset:1024
	ds_read_b128 v[170:173], v140 offset:2048
	ds_read_b128 v[174:177], v140 offset:3072
	s_add_i32 m0, s45, 0xc000
	ds_read_b128 v[178:181], v145
	ds_read_b128 v[182:185], v145 offset:1024
	ds_read_b128 v[186:189], v145 offset:2048
	ds_read_b128 v[190:193], v145 offset:3072
	ds_read_b128 v[194:197], v145 offset:4096
	ds_read_b128 v[198:201], v145 offset:5120
	ds_read_b128 v[202:205], v145 offset:6144
	ds_read_b128 v[224:227], v145 offset:7168
	global_load_lds_dwordx4 v136, s[40:41]
	s_add_i32 m0, s45, 0xe000
	s_nop 0
	global_load_lds_dwordx4 v138, s[40:41]
	s_waitcnt vmcnt(8)
	s_waitcnt lgkmcnt(0)
	s_barrier
	s_setprio 1
	s_waitcnt lgkmcnt(0)
	s_nop 0
	v_mfma_f32_16x16x32_bf16 v[126:129], v[146:149], v[178:181], v[126:129]
	v_mfma_f32_16x16x32_bf16 v[122:125], v[154:157], v[178:181], v[122:125]
	v_mfma_f32_16x16x32_bf16 v[118:121], v[146:149], v[186:189], v[118:121]
	v_mfma_f32_16x16x32_bf16 v[110:113], v[154:157], v[186:189], v[110:113]
	v_mfma_f32_16x16x32_bf16 v[102:105], v[146:149], v[194:197], v[102:105]
	v_mfma_f32_16x16x32_bf16 v[94:97], v[154:157], v[194:197], v[94:97]
	v_mfma_f32_16x16x32_bf16 v[86:89], v[146:149], v[202:205], v[86:89]
	v_mfma_f32_16x16x32_bf16 v[78:81], v[154:157], v[202:205], v[78:81]
	v_mfma_f32_16x16x32_bf16 v[126:129], v[150:153], v[182:185], v[126:129]
	v_mfma_f32_16x16x32_bf16 v[122:125], v[158:161], v[182:185], v[122:125]
	v_mfma_f32_16x16x32_bf16 v[118:121], v[150:153], v[190:193], v[118:121]
	v_mfma_f32_16x16x32_bf16 v[110:113], v[158:161], v[190:193], v[110:113]
	v_mfma_f32_16x16x32_bf16 v[102:105], v[150:153], v[198:201], v[102:105]
	v_mfma_f32_16x16x32_bf16 v[94:97], v[158:161], v[198:201], v[94:97]
	v_mfma_f32_16x16x32_bf16 v[86:89], v[150:153], v[224:227], v[86:89]
	v_mfma_f32_16x16x32_bf16 v[78:81], v[158:161], v[224:227], v[78:81]
	s_setprio 0
	s_setprio 1
	v_mfma_f32_16x16x32_bf16 v[114:117], v[162:165], v[178:181], v[114:117]
	v_mfma_f32_16x16x32_bf16 v[106:109], v[170:173], v[178:181], v[106:109]
	v_mfma_f32_16x16x32_bf16 v[98:101], v[162:165], v[186:189], v[98:101]
	v_mfma_f32_16x16x32_bf16 v[90:93], v[170:173], v[186:189], v[90:93]
	v_mfma_f32_16x16x32_bf16 v[82:85], v[162:165], v[194:197], v[82:85]
	v_mfma_f32_16x16x32_bf16 v[74:77], v[170:173], v[194:197], v[74:77]
	v_mfma_f32_16x16x32_bf16 v[70:73], v[162:165], v[202:205], v[70:73]
	v_mfma_f32_16x16x32_bf16 v[66:69], v[170:173], v[202:205], v[66:69]
	v_mfma_f32_16x16x32_bf16 v[114:117], v[166:169], v[182:185], v[114:117]
	v_mfma_f32_16x16x32_bf16 v[106:109], v[174:177], v[182:185], v[106:109]
	v_mfma_f32_16x16x32_bf16 v[98:101], v[166:169], v[190:193], v[98:101]
	v_mfma_f32_16x16x32_bf16 v[90:93], v[174:177], v[190:193], v[90:93]
	v_mfma_f32_16x16x32_bf16 v[82:85], v[166:169], v[198:201], v[82:85]
	v_mfma_f32_16x16x32_bf16 v[74:77], v[174:177], v[198:201], v[74:77]
	v_mfma_f32_16x16x32_bf16 v[70:73], v[166:169], v[224:227], v[70:73]
	v_mfma_f32_16x16x32_bf16 v[66:69], v[174:177], v[224:227], v[66:69]
	s_setprio 0
	s_barrier
	s_add_i32 s88, s88, s37
	s_mov_b32 m0, s88
	ds_read_b128 v[178:181], v145 offset:16384
	ds_read_b128 v[182:185], v145 offset:17408
	ds_read_b128 v[186:189], v145 offset:18432
	ds_read_b128 v[190:193], v145 offset:19456
	ds_read_b128 v[194:197], v145 offset:20480
	ds_read_b128 v[198:201], v145 offset:21504
	ds_read_b128 v[202:205], v145 offset:22528
	ds_read_b128 v[224:227], v145 offset:23552
	global_load_lds_dwordx4 v16, s[28:29]
	s_add_i32 m0, s88, 0x2000
	s_add_u32 s88, s28, 0x20000
	s_addc_u32 s89, s29, 0
	s_add_i32 s90, s90, s37
	global_load_lds_dwordx4 v130, s[28:29]
	s_mov_b32 m0, s90
	v_lshl_add_u64 v[230:231], s[46:47], 0, v[132:133]
	global_load_lds_dwordx4 v16, s[88:89]
	s_add_i32 m0, s90, 0x2000
	s_nop 0
	global_load_lds_dwordx4 v130, s[88:89]
	v_lshl_add_u64 v[228:229], s[46:47], 0, v[134:135]
	s_mov_b32 m0, s45
	s_nop 0
	global_load_lds_dwordx4 v[228:229], off
	s_mov_b32 m0, s53
	s_nop 0
	global_load_lds_dwordx4 v[230:231], off
	s_waitcnt vmcnt(8)
	s_waitcnt lgkmcnt(0)
	s_barrier
	s_setprio 1
	s_waitcnt lgkmcnt(0)
	s_nop 0
	v_mfma_f32_16x16x32_bf16 v[62:65], v[146:149], v[178:181], v[62:65]
	v_mfma_f32_16x16x32_bf16 v[58:61], v[154:157], v[178:181], v[58:61]
	v_mfma_f32_16x16x32_bf16 v[54:57], v[146:149], v[186:189], v[54:57]
	v_mfma_f32_16x16x32_bf16 v[46:49], v[154:157], v[186:189], v[46:49]
	v_mfma_f32_16x16x32_bf16 v[38:41], v[146:149], v[194:197], v[38:41]
	v_mfma_f32_16x16x32_bf16 v[30:33], v[154:157], v[194:197], v[30:33]
	v_mfma_f32_16x16x32_bf16 v[22:25], v[146:149], v[202:205], v[22:25]
	v_mfma_f32_16x16x32_bf16 v[12:15], v[154:157], v[202:205], v[12:15]
	v_mfma_f32_16x16x32_bf16 v[62:65], v[150:153], v[182:185], v[62:65]
	v_mfma_f32_16x16x32_bf16 v[58:61], v[158:161], v[182:185], v[58:61]
	v_mfma_f32_16x16x32_bf16 v[54:57], v[150:153], v[190:193], v[54:57]
	v_mfma_f32_16x16x32_bf16 v[46:49], v[158:161], v[190:193], v[46:49]
	v_mfma_f32_16x16x32_bf16 v[38:41], v[150:153], v[198:201], v[38:41]
	v_mfma_f32_16x16x32_bf16 v[30:33], v[158:161], v[198:201], v[30:33]
	v_mfma_f32_16x16x32_bf16 v[22:25], v[150:153], v[224:227], v[22:25]
	v_mfma_f32_16x16x32_bf16 v[12:15], v[158:161], v[224:227], v[12:15]
	s_setprio 0
	s_setprio 1
	v_mfma_f32_16x16x32_bf16 v[50:53], v[162:165], v[178:181], v[50:53]
	v_mfma_f32_16x16x32_bf16 v[42:45], v[170:173], v[178:181], v[42:45]
	v_mfma_f32_16x16x32_bf16 v[34:37], v[162:165], v[186:189], v[34:37]
	v_mfma_f32_16x16x32_bf16 v[26:29], v[170:173], v[186:189], v[26:29]
	v_mfma_f32_16x16x32_bf16 v[18:21], v[162:165], v[194:197], v[18:21]
	v_mfma_f32_16x16x32_bf16 v[8:11], v[170:173], v[194:197], v[8:11]
	v_mfma_f32_16x16x32_bf16 v[4:7], v[162:165], v[202:205], v[4:7]
	v_mfma_f32_16x16x32_bf16 v[0:3], v[170:173], v[202:205], v[0:3]
	v_mfma_f32_16x16x32_bf16 v[50:53], v[166:169], v[182:185], v[50:53]
	v_mfma_f32_16x16x32_bf16 v[42:45], v[174:177], v[182:185], v[42:45]
	v_mfma_f32_16x16x32_bf16 v[34:37], v[166:169], v[190:193], v[34:37]
	v_mfma_f32_16x16x32_bf16 v[26:29], v[174:177], v[190:193], v[26:29]
	v_mfma_f32_16x16x32_bf16 v[18:21], v[166:169], v[198:201], v[18:21]
	v_mfma_f32_16x16x32_bf16 v[8:11], v[174:177], v[198:201], v[8:11]
	v_mfma_f32_16x16x32_bf16 v[4:7], v[166:169], v[224:227], v[4:7]
	v_mfma_f32_16x16x32_bf16 v[0:3], v[174:177], v[224:227], v[0:3]
	s_setprio 0
	s_barrier
	s_add_i32 s88, 0, 0x18000
	s_add_i32 s89, 0, 0x1c000
	v_add_u32_e32 v158, s88, v143
	v_add_u32_e32 v174, s89, v143
	ds_read_b128 v[146:149], v158
	ds_read_b128 v[150:153], v158 offset:1024
	ds_read_b128 v[154:157], v158 offset:2048
	ds_read_b128 v[158:161], v158 offset:3072
	ds_read_b128 v[162:165], v174
	ds_read_b128 v[166:169], v174 offset:1024
	ds_read_b128 v[170:173], v174 offset:2048
	ds_read_b128 v[174:177], v174 offset:3072
	s_add_u32 s46, s46, 0x80000
	s_addc_u32 s47, s47, 0
	s_mov_b32 m0, s58
	ds_read_b128 v[178:181], v145 offset:32768
	ds_read_b128 v[182:185], v145 offset:33792
	ds_read_b128 v[186:189], v145 offset:34816
	ds_read_b128 v[190:193], v145 offset:35840
	ds_read_b128 v[194:197], v145 offset:36864
	ds_read_b128 v[198:201], v145 offset:37888
	ds_read_b128 v[202:205], v145 offset:38912
	ds_read_b128 v[224:227], v145 offset:39936
	global_load_lds_dwordx4 v134, s[46:47]
	s_mov_b32 m0, s59
	s_nop 0
	global_load_lds_dwordx4 v132, s[46:47]
	s_waitcnt vmcnt(8)
	s_waitcnt lgkmcnt(0)
	s_barrier
	s_setprio 1
	s_waitcnt lgkmcnt(0)
	s_nop 0
	v_mfma_f32_16x16x32_bf16 v[126:129], v[146:149], v[178:181], v[126:129]
	v_mfma_f32_16x16x32_bf16 v[122:125], v[154:157], v[178:181], v[122:125]
	v_mfma_f32_16x16x32_bf16 v[118:121], v[146:149], v[186:189], v[118:121]
	v_mfma_f32_16x16x32_bf16 v[110:113], v[154:157], v[186:189], v[110:113]
	v_mfma_f32_16x16x32_bf16 v[102:105], v[146:149], v[194:197], v[102:105]
	v_mfma_f32_16x16x32_bf16 v[94:97], v[154:157], v[194:197], v[94:97]
	v_mfma_f32_16x16x32_bf16 v[86:89], v[146:149], v[202:205], v[86:89]
	v_mfma_f32_16x16x32_bf16 v[78:81], v[154:157], v[202:205], v[78:81]
	v_mfma_f32_16x16x32_bf16 v[126:129], v[150:153], v[182:185], v[126:129]
	v_mfma_f32_16x16x32_bf16 v[122:125], v[158:161], v[182:185], v[122:125]
	v_mfma_f32_16x16x32_bf16 v[118:121], v[150:153], v[190:193], v[118:121]
	v_mfma_f32_16x16x32_bf16 v[110:113], v[158:161], v[190:193], v[110:113]
	v_mfma_f32_16x16x32_bf16 v[102:105], v[150:153], v[198:201], v[102:105]
	v_mfma_f32_16x16x32_bf16 v[94:97], v[158:161], v[198:201], v[94:97]
	v_mfma_f32_16x16x32_bf16 v[86:89], v[150:153], v[224:227], v[86:89]
	v_mfma_f32_16x16x32_bf16 v[78:81], v[158:161], v[224:227], v[78:81]
	s_setprio 0
	s_setprio 1
	v_mfma_f32_16x16x32_bf16 v[114:117], v[162:165], v[178:181], v[114:117]
	v_mfma_f32_16x16x32_bf16 v[106:109], v[170:173], v[178:181], v[106:109]
	v_mfma_f32_16x16x32_bf16 v[98:101], v[162:165], v[186:189], v[98:101]
	v_mfma_f32_16x16x32_bf16 v[90:93], v[170:173], v[186:189], v[90:93]
	v_mfma_f32_16x16x32_bf16 v[82:85], v[162:165], v[194:197], v[82:85]
	v_mfma_f32_16x16x32_bf16 v[74:77], v[170:173], v[194:197], v[74:77]
	v_mfma_f32_16x16x32_bf16 v[70:73], v[162:165], v[202:205], v[70:73]
	v_mfma_f32_16x16x32_bf16 v[66:69], v[170:173], v[202:205], v[66:69]
	v_mfma_f32_16x16x32_bf16 v[114:117], v[166:169], v[182:185], v[114:117]
	v_mfma_f32_16x16x32_bf16 v[106:109], v[174:177], v[182:185], v[106:109]
	v_mfma_f32_16x16x32_bf16 v[98:101], v[166:169], v[190:193], v[98:101]
	v_mfma_f32_16x16x32_bf16 v[90:93], v[174:177], v[190:193], v[90:93]
	v_mfma_f32_16x16x32_bf16 v[82:85], v[166:169], v[198:201], v[82:85]
	v_mfma_f32_16x16x32_bf16 v[74:77], v[174:177], v[198:201], v[74:77]
	v_mfma_f32_16x16x32_bf16 v[70:73], v[166:169], v[224:227], v[70:73]
	v_mfma_f32_16x16x32_bf16 v[66:69], v[174:177], v[224:227], v[66:69]
	s_setprio 0
	s_barrier
	s_add_i32 s46, s88, s37
	s_add_u32 s28, s28, 0x80
	s_addc_u32 s29, s29, 0
	s_mov_b32 m0, s46
	ds_read_b128 v[178:181], v145 offset:49152
	ds_read_b128 v[182:185], v145 offset:50176
	ds_read_b128 v[186:189], v145 offset:51200
	ds_read_b128 v[190:193], v145 offset:52224
	ds_read_b128 v[194:197], v145 offset:53248
	ds_read_b128 v[198:201], v145 offset:54272
	ds_read_b128 v[202:205], v145 offset:55296
	ds_read_b128 v[224:227], v145 offset:56320
	global_load_lds_dwordx4 v16, s[28:29]
	s_add_i32 m0, s46, 0x2000
	s_add_i32 s46, s89, s37
	global_load_lds_dwordx4 v130, s[28:29]
	s_add_u32 s28, s28, 0x20000
	s_addc_u32 s29, s29, 0
	s_mov_b32 m0, s46
	s_nop 0
	global_load_lds_dwordx4 v16, s[28:29]
	s_add_i32 m0, s46, 0x2000
	s_nop 0
	global_load_lds_dwordx4 v130, s[28:29]
	v_lshl_add_u64 v[140:141], v[228:229], 0, s[34:35]
	s_mov_b32 m0, s83
	s_nop 0
	global_load_lds_dwordx4 v[140:141], off
	v_lshl_add_u64 v[140:141], v[230:231], 0, s[34:35]
	s_mov_b32 m0, s84
	s_nop 0
	global_load_lds_dwordx4 v[140:141], off
	s_waitcnt vmcnt(8)
	s_waitcnt lgkmcnt(0)
	s_barrier
	s_setprio 1
	s_waitcnt lgkmcnt(0)
	s_nop 0
	v_mfma_f32_16x16x32_bf16 v[62:65], v[146:149], v[178:181], v[62:65]
	v_mfma_f32_16x16x32_bf16 v[58:61], v[154:157], v[178:181], v[58:61]
	v_mfma_f32_16x16x32_bf16 v[54:57], v[146:149], v[186:189], v[54:57]
	v_mfma_f32_16x16x32_bf16 v[46:49], v[154:157], v[186:189], v[46:49]
	v_mfma_f32_16x16x32_bf16 v[38:41], v[146:149], v[194:197], v[38:41]
	v_mfma_f32_16x16x32_bf16 v[30:33], v[154:157], v[194:197], v[30:33]
	v_mfma_f32_16x16x32_bf16 v[22:25], v[146:149], v[202:205], v[22:25]
	v_mfma_f32_16x16x32_bf16 v[12:15], v[154:157], v[202:205], v[12:15]
	v_mfma_f32_16x16x32_bf16 v[62:65], v[150:153], v[182:185], v[62:65]
	v_mfma_f32_16x16x32_bf16 v[58:61], v[158:161], v[182:185], v[58:61]
	v_mfma_f32_16x16x32_bf16 v[54:57], v[150:153], v[190:193], v[54:57]
	v_mfma_f32_16x16x32_bf16 v[46:49], v[158:161], v[190:193], v[46:49]
	v_mfma_f32_16x16x32_bf16 v[38:41], v[150:153], v[198:201], v[38:41]
	v_mfma_f32_16x16x32_bf16 v[30:33], v[158:161], v[198:201], v[30:33]
	v_mfma_f32_16x16x32_bf16 v[22:25], v[150:153], v[224:227], v[22:25]
	v_mfma_f32_16x16x32_bf16 v[12:15], v[158:161], v[224:227], v[12:15]
	s_setprio 0
	s_setprio 1
	v_mfma_f32_16x16x32_bf16 v[50:53], v[162:165], v[178:181], v[50:53]
	v_mfma_f32_16x16x32_bf16 v[42:45], v[170:173], v[178:181], v[42:45]
	v_mfma_f32_16x16x32_bf16 v[34:37], v[162:165], v[186:189], v[34:37]
	v_mfma_f32_16x16x32_bf16 v[26:29], v[170:173], v[186:189], v[26:29]
	v_mfma_f32_16x16x32_bf16 v[18:21], v[162:165], v[194:197], v[18:21]
	v_mfma_f32_16x16x32_bf16 v[8:11], v[170:173], v[194:197], v[8:11]
	v_mfma_f32_16x16x32_bf16 v[4:7], v[162:165], v[202:205], v[4:7]
	v_mfma_f32_16x16x32_bf16 v[0:3], v[170:173], v[202:205], v[0:3]
	v_mfma_f32_16x16x32_bf16 v[50:53], v[166:169], v[182:185], v[50:53]
	v_mfma_f32_16x16x32_bf16 v[42:45], v[174:177], v[182:185], v[42:45]
	v_mfma_f32_16x16x32_bf16 v[34:37], v[166:169], v[190:193], v[34:37]
	v_mfma_f32_16x16x32_bf16 v[26:29], v[174:177], v[190:193], v[26:29]
	v_mfma_f32_16x16x32_bf16 v[18:21], v[166:169], v[198:201], v[18:21]
	v_mfma_f32_16x16x32_bf16 v[8:11], v[174:177], v[198:201], v[8:11]
	v_mfma_f32_16x16x32_bf16 v[4:7], v[166:169], v[224:227], v[4:7]
	v_mfma_f32_16x16x32_bf16 v[0:3], v[174:177], v[224:227], v[0:3]
	s_setprio 0
	s_barrier
	s_add_i32 s87, s87, 2
	s_add_u32 s40, s40, 0x100
	s_addc_u32 s41, s41, 0
	s_add_u32 s48, s48, 0x100
	s_addc_u32 s49, s49, 0
	s_cmp_gt_u32 s87, 5
	s_cbranch_scc0 .LBB0_649

.LBB0_716:
	s_ashr_i32 s23, s22, 31
	s_lshl_b64 s[26:27], s[22:23], 20
	s_add_u32 s26, s68, s26
	s_addc_u32 s27, s69, s27
	s_and_b64 s[28:29], s[38:39], exec
	s_cselect_b32 s23, s27, s45
	s_cselect_b32 s84, s26, s44
	s_ashr_i32 s19, s18, 31
	s_lshl_b64 s[28:29], s[18:19], 20
	v_readlane_b32 s19, v255, 12
	s_add_u32 s40, s19, s28
	v_readlane_b32 s19, v255, 13
	s_addc_u32 s41, s19, s29
	s_and_b64 s[28:29], s[38:39], exec
	s_cselect_b32 s19, s41, s47
	s_cselect_b32 s85, s40, s46
	s_add_u32 s44, s44, 0x80080
	s_addc_u32 s45, s45, 0
	s_add_u32 s86, s46, 0x100
	s_addc_u32 s87, s47, 0
	s_mov_b32 s88, -2
	s_add_u32 s28, s44, 0xfff80080
	s_addc_u32 s29, s45, -1
	s_add_i32 s89, 0, 0x10000
	s_cmp_eq_u32 s88, 28
	s_cselect_b32 s47, s23, s29
	s_cselect_b32 s46, s84, s28
	s_cselect_b32 s29, s19, s87
	s_cselect_b32 s28, s85, s86
	s_add_i32 s92, 0, 0x14000
	v_add_u32_e32 v148, s89, v224
	v_add_u32_e32 v164, s92, v224
	ds_read_b128 v[136:139], v148
	ds_read_b128 v[140:143], v148 offset:1024
	ds_read_b128 v[144:147], v148 offset:2048
	ds_read_b128 v[148:151], v148 offset:3072
	ds_read_b128 v[152:155], v164
	ds_read_b128 v[156:159], v164 offset:1024
	ds_read_b128 v[160:163], v164 offset:2048
	ds_read_b128 v[164:167], v164 offset:3072
	s_add_i32 m0, s43, 0xc000
	ds_read_b128 v[168:171], v226
	ds_read_b128 v[172:175], v226 offset:1024
	ds_read_b128 v[176:179], v226 offset:2048
	ds_read_b128 v[180:183], v226 offset:3072
	ds_read_b128 v[184:187], v226 offset:4096
	ds_read_b128 v[188:191], v226 offset:5120
	ds_read_b128 v[192:195], v226 offset:6144
	ds_read_b128 v[196:199], v226 offset:7168
	global_load_lds_dwordx4 v132, s[44:45]
	s_add_i32 m0, s43, 0xe000
	s_nop 0
	global_load_lds_dwordx4 v134, s[44:45]
	s_waitcnt vmcnt(8)
	s_waitcnt lgkmcnt(0)
	s_barrier
	s_setprio 1
	s_waitcnt lgkmcnt(0)
	v_mfma_f32_16x16x32_bf16 v[126:129], v[136:139], v[168:171], 0
	v_mfma_f32_16x16x32_bf16 v[122:125], v[144:147], v[168:171], 0
	v_mfma_f32_16x16x32_bf16 v[118:121], v[136:139], v[176:179], 0
	v_mfma_f32_16x16x32_bf16 v[114:117], v[144:147], v[176:179], 0
	v_mfma_f32_16x16x32_bf16 v[110:113], v[136:139], v[184:187], 0
	v_mfma_f32_16x16x32_bf16 v[106:109], v[144:147], v[184:187], 0
	v_mfma_f32_16x16x32_bf16 v[102:105], v[136:139], v[192:195], 0
	v_mfma_f32_16x16x32_bf16 v[98:101], v[144:147], v[192:195], 0
	v_mfma_f32_16x16x32_bf16 v[126:129], v[140:143], v[172:175], v[126:129]
	v_mfma_f32_16x16x32_bf16 v[122:125], v[148:151], v[172:175], v[122:125]
	v_mfma_f32_16x16x32_bf16 v[118:121], v[140:143], v[180:183], v[118:121]
	v_mfma_f32_16x16x32_bf16 v[114:117], v[148:151], v[180:183], v[114:117]
	v_mfma_f32_16x16x32_bf16 v[110:113], v[140:143], v[188:191], v[110:113]
	v_mfma_f32_16x16x32_bf16 v[106:109], v[148:151], v[188:191], v[106:109]
	v_mfma_f32_16x16x32_bf16 v[102:105], v[140:143], v[196:199], v[102:105]
	v_mfma_f32_16x16x32_bf16 v[98:101], v[148:151], v[196:199], v[98:101]
	s_setprio 0
	s_setprio 1
	v_mfma_f32_16x16x32_bf16 v[94:97], v[152:155], v[168:171], 0
	v_mfma_f32_16x16x32_bf16 v[90:93], v[160:163], v[168:171], 0
	v_mfma_f32_16x16x32_bf16 v[86:89], v[152:155], v[176:179], 0
	v_mfma_f32_16x16x32_bf16 v[82:85], v[160:163], v[176:179], 0
	v_mfma_f32_16x16x32_bf16 v[78:81], v[152:155], v[184:187], 0
	v_mfma_f32_16x16x32_bf16 v[74:77], v[160:163], v[184:187], 0
	v_mfma_f32_16x16x32_bf16 v[70:73], v[152:155], v[192:195], 0
	v_mfma_f32_16x16x32_bf16 v[66:69], v[160:163], v[192:195], 0
	v_mfma_f32_16x16x32_bf16 v[94:97], v[156:159], v[172:175], v[94:97]
	v_mfma_f32_16x16x32_bf16 v[90:93], v[164:167], v[172:175], v[90:93]
	v_mfma_f32_16x16x32_bf16 v[86:89], v[156:159], v[180:183], v[86:89]
	v_mfma_f32_16x16x32_bf16 v[82:85], v[164:167], v[180:183], v[82:85]
	v_mfma_f32_16x16x32_bf16 v[78:81], v[156:159], v[188:191], v[78:81]
	v_mfma_f32_16x16x32_bf16 v[74:77], v[164:167], v[188:191], v[74:77]
	v_mfma_f32_16x16x32_bf16 v[70:73], v[156:159], v[196:199], v[70:73]
	v_mfma_f32_16x16x32_bf16 v[66:69], v[164:167], v[196:199], v[66:69]
	s_setprio 0
	s_barrier
	s_add_i32 s89, s89, s37
	s_mov_b32 m0, s89
	ds_read_b128 v[168:171], v226 offset:16384
	ds_read_b128 v[172:175], v226 offset:17408
	ds_read_b128 v[176:179], v226 offset:18432
	ds_read_b128 v[180:183], v226 offset:19456
	ds_read_b128 v[184:187], v226 offset:20480
	ds_read_b128 v[188:191], v226 offset:21504
	ds_read_b128 v[192:195], v226 offset:22528
	ds_read_b128 v[196:199], v226 offset:23552
	global_load_lds_dwordx4 v16, s[28:29]
	s_add_i32 m0, s89, 0x2000
	s_add_u32 s90, s28, 0x80000
	s_addc_u32 s91, s29, 0
	s_add_i32 s89, s92, s37
	global_load_lds_dwordx4 v130, s[28:29]
	s_mov_b32 m0, s89
	v_lshl_add_u64 v[206:207], s[46:47], 0, v[130:131]
	global_load_lds_dwordx4 v16, s[90:91]
	s_add_i32 m0, s89, 0x2000
	s_nop 0
	global_load_lds_dwordx4 v130, s[90:91]
	v_lshl_add_u64 v[204:205], s[46:47], 0, v[16:17]
	s_mov_b32 m0, s43
	s_nop 0
	global_load_lds_dwordx4 v[204:205], off
	s_mov_b32 m0, s50
	s_nop 0
	global_load_lds_dwordx4 v[206:207], off
	s_waitcnt vmcnt(8)
	s_waitcnt lgkmcnt(0)
	s_barrier
	s_setprio 1
	s_waitcnt lgkmcnt(0)
	s_nop 0
	v_mfma_f32_16x16x32_bf16 v[62:65], v[136:139], v[168:171], 0
	v_mfma_f32_16x16x32_bf16 v[58:61], v[144:147], v[168:171], 0
	v_mfma_f32_16x16x32_bf16 v[54:57], v[136:139], v[176:179], 0
	v_mfma_f32_16x16x32_bf16 v[50:53], v[144:147], v[176:179], 0
	v_mfma_f32_16x16x32_bf16 v[46:49], v[136:139], v[184:187], 0
	v_mfma_f32_16x16x32_bf16 v[42:45], v[144:147], v[184:187], 0
	v_mfma_f32_16x16x32_bf16 v[38:41], v[136:139], v[192:195], 0
	v_mfma_f32_16x16x32_bf16 v[34:37], v[144:147], v[192:195], 0
	v_mfma_f32_16x16x32_bf16 v[62:65], v[140:143], v[172:175], v[62:65]
	v_mfma_f32_16x16x32_bf16 v[58:61], v[148:151], v[172:175], v[58:61]
	v_mfma_f32_16x16x32_bf16 v[54:57], v[140:143], v[180:183], v[54:57]
	v_mfma_f32_16x16x32_bf16 v[50:53], v[148:151], v[180:183], v[50:53]
	v_mfma_f32_16x16x32_bf16 v[46:49], v[140:143], v[188:191], v[46:49]
	v_mfma_f32_16x16x32_bf16 v[42:45], v[148:151], v[188:191], v[42:45]
	v_mfma_f32_16x16x32_bf16 v[38:41], v[140:143], v[196:199], v[38:41]
	v_mfma_f32_16x16x32_bf16 v[34:37], v[148:151], v[196:199], v[34:37]
	s_setprio 0
	s_setprio 1
	v_mfma_f32_16x16x32_bf16 v[30:33], v[152:155], v[168:171], 0
	v_mfma_f32_16x16x32_bf16 v[26:29], v[160:163], v[168:171], 0
	v_mfma_f32_16x16x32_bf16 v[22:25], v[152:155], v[176:179], 0
	v_mfma_f32_16x16x32_bf16 v[18:21], v[160:163], v[176:179], 0
	v_mfma_f32_16x16x32_bf16 v[12:15], v[152:155], v[184:187], 0
	v_mfma_f32_16x16x32_bf16 v[8:11], v[160:163], v[184:187], 0
	v_mfma_f32_16x16x32_bf16 v[4:7], v[152:155], v[192:195], 0
	v_mfma_f32_16x16x32_bf16 v[0:3], v[160:163], v[192:195], 0
	v_mfma_f32_16x16x32_bf16 v[30:33], v[156:159], v[172:175], v[30:33]
	v_mfma_f32_16x16x32_bf16 v[26:29], v[164:167], v[172:175], v[26:29]
	v_mfma_f32_16x16x32_bf16 v[22:25], v[156:159], v[180:183], v[22:25]
	v_mfma_f32_16x16x32_bf16 v[18:21], v[164:167], v[180:183], v[18:21]
	v_mfma_f32_16x16x32_bf16 v[12:15], v[156:159], v[188:191], v[12:15]
	v_mfma_f32_16x16x32_bf16 v[8:11], v[164:167], v[188:191], v[8:11]
	v_mfma_f32_16x16x32_bf16 v[4:7], v[156:159], v[196:199], v[4:7]
	v_mfma_f32_16x16x32_bf16 v[0:3], v[164:167], v[196:199], v[0:3]
	s_setprio 0
	s_barrier
	s_add_i32 s89, 0, 0x18000
	s_add_i32 s90, 0, 0x1c000
	v_add_u32_e32 v148, s89, v224
	v_add_u32_e32 v164, s90, v224
	ds_read_b128 v[136:139], v148
	ds_read_b128 v[140:143], v148 offset:1024
	ds_read_b128 v[144:147], v148 offset:2048
	ds_read_b128 v[148:151], v148 offset:3072
	ds_read_b128 v[152:155], v164
	ds_read_b128 v[156:159], v164 offset:1024
	ds_read_b128 v[160:163], v164 offset:2048
	ds_read_b128 v[164:167], v164 offset:3072
	s_add_u32 s46, s46, 0x80000
	s_addc_u32 s47, s47, 0
	s_mov_b32 m0, s51
	ds_read_b128 v[168:171], v226 offset:32768
	ds_read_b128 v[172:175], v226 offset:33792
	ds_read_b128 v[176:179], v226 offset:34816
	ds_read_b128 v[180:183], v226 offset:35840
	ds_read_b128 v[184:187], v226 offset:36864
	ds_read_b128 v[188:191], v226 offset:37888
	ds_read_b128 v[192:195], v226 offset:38912
	ds_read_b128 v[196:199], v226 offset:39936
	global_load_lds_dwordx4 v16, s[46:47]
	s_mov_b32 m0, s52
	s_nop 0
	global_load_lds_dwordx4 v130, s[46:47]
	s_waitcnt vmcnt(8)
	s_waitcnt lgkmcnt(0)
	s_barrier
	s_setprio 1
	s_waitcnt lgkmcnt(0)
	s_nop 0
	v_mfma_f32_16x16x32_bf16 v[126:129], v[136:139], v[168:171], v[126:129]
	v_mfma_f32_16x16x32_bf16 v[122:125], v[144:147], v[168:171], v[122:125]
	v_mfma_f32_16x16x32_bf16 v[118:121], v[136:139], v[176:179], v[118:121]
	v_mfma_f32_16x16x32_bf16 v[114:117], v[144:147], v[176:179], v[114:117]
	v_mfma_f32_16x16x32_bf16 v[110:113], v[136:139], v[184:187], v[110:113]
	v_mfma_f32_16x16x32_bf16 v[106:109], v[144:147], v[184:187], v[106:109]
	v_mfma_f32_16x16x32_bf16 v[102:105], v[136:139], v[192:195], v[102:105]
	v_mfma_f32_16x16x32_bf16 v[98:101], v[144:147], v[192:195], v[98:101]
	v_mfma_f32_16x16x32_bf16 v[126:129], v[140:143], v[172:175], v[126:129]
	v_mfma_f32_16x16x32_bf16 v[122:125], v[148:151], v[172:175], v[122:125]
	v_mfma_f32_16x16x32_bf16 v[118:121], v[140:143], v[180:183], v[118:121]
	v_mfma_f32_16x16x32_bf16 v[114:117], v[148:151], v[180:183], v[114:117]
	v_mfma_f32_16x16x32_bf16 v[110:113], v[140:143], v[188:191], v[110:113]
	v_mfma_f32_16x16x32_bf16 v[106:109], v[148:151], v[188:191], v[106:109]
	v_mfma_f32_16x16x32_bf16 v[102:105], v[140:143], v[196:199], v[102:105]
	v_mfma_f32_16x16x32_bf16 v[98:101], v[148:151], v[196:199], v[98:101]
	s_setprio 0
	s_setprio 1
	v_mfma_f32_16x16x32_bf16 v[94:97], v[152:155], v[168:171], v[94:97]
	v_mfma_f32_16x16x32_bf16 v[90:93], v[160:163], v[168:171], v[90:93]
	v_mfma_f32_16x16x32_bf16 v[86:89], v[152:155], v[176:179], v[86:89]
	v_mfma_f32_16x16x32_bf16 v[82:85], v[160:163], v[176:179], v[82:85]
	v_mfma_f32_16x16x32_bf16 v[78:81], v[152:155], v[184:187], v[78:81]
	v_mfma_f32_16x16x32_bf16 v[74:77], v[160:163], v[184:187], v[74:77]
	v_mfma_f32_16x16x32_bf16 v[70:73], v[152:155], v[192:195], v[70:73]
	v_mfma_f32_16x16x32_bf16 v[66:69], v[160:163], v[192:195], v[66:69]
	v_mfma_f32_16x16x32_bf16 v[94:97], v[156:159], v[172:175], v[94:97]
	v_mfma_f32_16x16x32_bf16 v[90:93], v[164:167], v[172:175], v[90:93]
	v_mfma_f32_16x16x32_bf16 v[86:89], v[156:159], v[180:183], v[86:89]
	v_mfma_f32_16x16x32_bf16 v[82:85], v[164:167], v[180:183], v[82:85]
	v_mfma_f32_16x16x32_bf16 v[78:81], v[156:159], v[188:191], v[78:81]
	v_mfma_f32_16x16x32_bf16 v[74:77], v[164:167], v[188:191], v[74:77]
	v_mfma_f32_16x16x32_bf16 v[70:73], v[156:159], v[196:199], v[70:73]
	v_mfma_f32_16x16x32_bf16 v[66:69], v[164:167], v[196:199], v[66:69]
	s_setprio 0
	s_barrier
	s_add_i32 s46, s89, s37
	s_add_u32 s28, s28, 0x80
	s_addc_u32 s29, s29, 0
	s_mov_b32 m0, s46
	ds_read_b128 v[168:171], v226 offset:49152
	ds_read_b128 v[172:175], v226 offset:50176
	ds_read_b128 v[176:179], v226 offset:51200
	ds_read_b128 v[180:183], v226 offset:52224
	ds_read_b128 v[184:187], v226 offset:53248
	ds_read_b128 v[188:191], v226 offset:54272
	ds_read_b128 v[192:195], v226 offset:55296
	ds_read_b128 v[196:199], v226 offset:56320
	global_load_lds_dwordx4 v16, s[28:29]
	s_add_i32 m0, s46, 0x2000
	s_add_i32 s46, s90, s37
	global_load_lds_dwordx4 v130, s[28:29]
	s_add_u32 s28, s28, 0x80000
	s_addc_u32 s29, s29, 0
	s_mov_b32 m0, s46
	s_nop 0
	global_load_lds_dwordx4 v16, s[28:29]
	s_add_i32 m0, s46, 0x2000
	s_nop 0
	global_load_lds_dwordx4 v130, s[28:29]
	v_lshl_add_u64 v[200:201], v[204:205], 0, s[34:35]
	s_mov_b32 m0, s53
	s_nop 0
	global_load_lds_dwordx4 v[200:201], off
	v_lshl_add_u64 v[200:201], v[206:207], 0, s[34:35]
	s_mov_b32 m0, s58
	s_nop 0
	global_load_lds_dwordx4 v[200:201], off
	s_waitcnt vmcnt(8)
	s_waitcnt lgkmcnt(0)
	s_barrier
	s_setprio 1
	s_waitcnt lgkmcnt(0)
	s_nop 0
	v_mfma_f32_16x16x32_bf16 v[62:65], v[136:139], v[168:171], v[62:65]
	v_mfma_f32_16x16x32_bf16 v[58:61], v[144:147], v[168:171], v[58:61]
	v_mfma_f32_16x16x32_bf16 v[54:57], v[136:139], v[176:179], v[54:57]
	v_mfma_f32_16x16x32_bf16 v[50:53], v[144:147], v[176:179], v[50:53]
	v_mfma_f32_16x16x32_bf16 v[46:49], v[136:139], v[184:187], v[46:49]
	v_mfma_f32_16x16x32_bf16 v[42:45], v[144:147], v[184:187], v[42:45]
	v_mfma_f32_16x16x32_bf16 v[38:41], v[136:139], v[192:195], v[38:41]
	v_mfma_f32_16x16x32_bf16 v[34:37], v[144:147], v[192:195], v[34:37]
	v_mfma_f32_16x16x32_bf16 v[62:65], v[140:143], v[172:175], v[62:65]
	v_mfma_f32_16x16x32_bf16 v[58:61], v[148:151], v[172:175], v[58:61]
	v_mfma_f32_16x16x32_bf16 v[54:57], v[140:143], v[180:183], v[54:57]
	v_mfma_f32_16x16x32_bf16 v[50:53], v[148:151], v[180:183], v[50:53]
	v_mfma_f32_16x16x32_bf16 v[46:49], v[140:143], v[188:191], v[46:49]
	v_mfma_f32_16x16x32_bf16 v[42:45], v[148:151], v[188:191], v[42:45]
	v_mfma_f32_16x16x32_bf16 v[38:41], v[140:143], v[196:199], v[38:41]
	v_mfma_f32_16x16x32_bf16 v[34:37], v[148:151], v[196:199], v[34:37]
	s_setprio 0
	s_setprio 1
	v_mfma_f32_16x16x32_bf16 v[30:33], v[152:155], v[168:171], v[30:33]
	v_mfma_f32_16x16x32_bf16 v[26:29], v[160:163], v[168:171], v[26:29]
	v_mfma_f32_16x16x32_bf16 v[22:25], v[152:155], v[176:179], v[22:25]
	v_mfma_f32_16x16x32_bf16 v[18:21], v[160:163], v[176:179], v[18:21]
	v_mfma_f32_16x16x32_bf16 v[12:15], v[152:155], v[184:187], v[12:15]
	v_mfma_f32_16x16x32_bf16 v[8:11], v[160:163], v[184:187], v[8:11]
	v_mfma_f32_16x16x32_bf16 v[4:7], v[152:155], v[192:195], v[4:7]
	v_mfma_f32_16x16x32_bf16 v[0:3], v[160:163], v[192:195], v[0:3]
	v_mfma_f32_16x16x32_bf16 v[30:33], v[156:159], v[172:175], v[30:33]
	v_mfma_f32_16x16x32_bf16 v[26:29], v[164:167], v[172:175], v[26:29]
	v_mfma_f32_16x16x32_bf16 v[22:25], v[156:159], v[180:183], v[22:25]
	v_mfma_f32_16x16x32_bf16 v[18:21], v[164:167], v[180:183], v[18:21]
	v_mfma_f32_16x16x32_bf16 v[12:15], v[156:159], v[188:191], v[12:15]
	v_mfma_f32_16x16x32_bf16 v[8:11], v[164:167], v[188:191], v[8:11]
	v_mfma_f32_16x16x32_bf16 v[4:7], v[156:159], v[196:199], v[4:7]
	v_mfma_f32_16x16x32_bf16 v[0:3], v[164:167], v[196:199], v[0:3]
	s_setprio 0
	s_barrier
	s_add_i32 s88, s88, 2
	s_add_u32 s44, s44, 0x100
	s_addc_u32 s45, s45, 0
	s_add_u32 s86, s86, 0x100
	s_addc_u32 s87, s87, 0
	s_cmp_gt_u32 s88, 29
	s_cbranch_scc1 .Lpz_F_exit
.LBB0_717:
	s_add_u32 s28, s44, 0xfff80080
	s_addc_u32 s29, s45, -1
	s_add_i32 s89, 0, 0x10000
	s_cmp_eq_u32 s88, 28
	s_cselect_b32 s47, s23, s29
	s_cselect_b32 s46, s84, s28
	s_cselect_b32 s29, s19, s87
	s_cselect_b32 s28, s85, s86
	s_add_i32 s92, 0, 0x14000
	v_add_u32_e32 v148, s89, v224
	v_add_u32_e32 v164, s92, v224
	ds_read_b128 v[136:139], v148
	ds_read_b128 v[140:143], v148 offset:1024
	ds_read_b128 v[144:147], v148 offset:2048
	ds_read_b128 v[148:151], v148 offset:3072
	ds_read_b128 v[152:155], v164
	ds_read_b128 v[156:159], v164 offset:1024
	ds_read_b128 v[160:163], v164 offset:2048
	ds_read_b128 v[164:167], v164 offset:3072
	s_add_i32 m0, s43, 0xc000
	ds_read_b128 v[168:171], v226
	ds_read_b128 v[172:175], v226 offset:1024
	ds_read_b128 v[176:179], v226 offset:2048
	ds_read_b128 v[180:183], v226 offset:3072
	ds_read_b128 v[184:187], v226 offset:4096
	ds_read_b128 v[188:191], v226 offset:5120
	ds_read_b128 v[192:195], v226 offset:6144
	ds_read_b128 v[196:199], v226 offset:7168
	global_load_lds_dwordx4 v132, s[44:45]
	s_add_i32 m0, s43, 0xe000
	s_nop 0
	global_load_lds_dwordx4 v134, s[44:45]
	s_waitcnt vmcnt(8)
	s_waitcnt lgkmcnt(0)
	s_barrier
	s_setprio 1
	s_waitcnt lgkmcnt(0)
	s_nop 0
	v_mfma_f32_16x16x32_bf16 v[126:129], v[136:139], v[168:171], v[126:129]
	v_mfma_f32_16x16x32_bf16 v[122:125], v[144:147], v[168:171], v[122:125]
	v_mfma_f32_16x16x32_bf16 v[118:121], v[136:139], v[176:179], v[118:121]
	v_mfma_f32_16x16x32_bf16 v[114:117], v[144:147], v[176:179], v[114:117]
	v_mfma_f32_16x16x32_bf16 v[110:113], v[136:139], v[184:187], v[110:113]
	v_mfma_f32_16x16x32_bf16 v[106:109], v[144:147], v[184:187], v[106:109]
	v_mfma_f32_16x16x32_bf16 v[102:105], v[136:139], v[192:195], v[102:105]
	v_mfma_f32_16x16x32_bf16 v[98:101], v[144:147], v[192:195], v[98:101]
	v_mfma_f32_16x16x32_bf16 v[126:129], v[140:143], v[172:175], v[126:129]
	v_mfma_f32_16x16x32_bf16 v[122:125], v[148:151], v[172:175], v[122:125]
	v_mfma_f32_16x16x32_bf16 v[118:121], v[140:143], v[180:183], v[118:121]
	v_mfma_f32_16x16x32_bf16 v[114:117], v[148:151], v[180:183], v[114:117]
	v_mfma_f32_16x16x32_bf16 v[110:113], v[140:143], v[188:191], v[110:113]
	v_mfma_f32_16x16x32_bf16 v[106:109], v[148:151], v[188:191], v[106:109]
	v_mfma_f32_16x16x32_bf16 v[102:105], v[140:143], v[196:199], v[102:105]
	v_mfma_f32_16x16x32_bf16 v[98:101], v[148:151], v[196:199], v[98:101]
	s_setprio 0
	s_setprio 1
	v_mfma_f32_16x16x32_bf16 v[94:97], v[152:155], v[168:171], v[94:97]
	v_mfma_f32_16x16x32_bf16 v[90:93], v[160:163], v[168:171], v[90:93]
	v_mfma_f32_16x16x32_bf16 v[86:89], v[152:155], v[176:179], v[86:89]
	v_mfma_f32_16x16x32_bf16 v[82:85], v[160:163], v[176:179], v[82:85]
	v_mfma_f32_16x16x32_bf16 v[78:81], v[152:155], v[184:187], v[78:81]
	v_mfma_f32_16x16x32_bf16 v[74:77], v[160:163], v[184:187], v[74:77]
	v_mfma_f32_16x16x32_bf16 v[70:73], v[152:155], v[192:195], v[70:73]
	v_mfma_f32_16x16x32_bf16 v[66:69], v[160:163], v[192:195], v[66:69]
	v_mfma_f32_16x16x32_bf16 v[94:97], v[156:159], v[172:175], v[94:97]
	v_mfma_f32_16x16x32_bf16 v[90:93], v[164:167], v[172:175], v[90:93]
	v_mfma_f32_16x16x32_bf16 v[86:89], v[156:159], v[180:183], v[86:89]
	v_mfma_f32_16x16x32_bf16 v[82:85], v[164:167], v[180:183], v[82:85]
	v_mfma_f32_16x16x32_bf16 v[78:81], v[156:159], v[188:191], v[78:81]
	v_mfma_f32_16x16x32_bf16 v[74:77], v[164:167], v[188:191], v[74:77]
	v_mfma_f32_16x16x32_bf16 v[70:73], v[156:159], v[196:199], v[70:73]
	v_mfma_f32_16x16x32_bf16 v[66:69], v[164:167], v[196:199], v[66:69]
	s_setprio 0
	s_barrier
	s_add_i32 s89, s89, s37
	s_mov_b32 m0, s89
	ds_read_b128 v[168:171], v226 offset:16384
	ds_read_b128 v[172:175], v226 offset:17408
	ds_read_b128 v[176:179], v226 offset:18432
	ds_read_b128 v[180:183], v226 offset:19456
	ds_read_b128 v[184:187], v226 offset:20480
	ds_read_b128 v[188:191], v226 offset:21504
	ds_read_b128 v[192:195], v226 offset:22528
	ds_read_b128 v[196:199], v226 offset:23552
	global_load_lds_dwordx4 v16, s[28:29]
	s_add_i32 m0, s89, 0x2000
	s_add_u32 s90, s28, 0x80000
	s_addc_u32 s91, s29, 0
	s_add_i32 s89, s92, s37
	global_load_lds_dwordx4 v130, s[28:29]
	s_mov_b32 m0, s89
	v_lshl_add_u64 v[206:207], s[46:47], 0, v[130:131]
	global_load_lds_dwordx4 v16, s[90:91]
	s_add_i32 m0, s89, 0x2000
	s_nop 0
	global_load_lds_dwordx4 v130, s[90:91]
	v_lshl_add_u64 v[204:205], s[46:47], 0, v[16:17]
	s_mov_b32 m0, s43
	s_nop 0
	global_load_lds_dwordx4 v[204:205], off
	s_mov_b32 m0, s50
	s_nop 0
	global_load_lds_dwordx4 v[206:207], off
	s_waitcnt vmcnt(8)
	s_waitcnt lgkmcnt(0)
	s_barrier
	s_setprio 1
	s_waitcnt lgkmcnt(0)
	s_nop 0
	v_mfma_f32_16x16x32_bf16 v[62:65], v[136:139], v[168:171], v[62:65]
	v_mfma_f32_16x16x32_bf16 v[58:61], v[144:147], v[168:171], v[58:61]
	v_mfma_f32_16x16x32_bf16 v[54:57], v[136:139], v[176:179], v[54:57]
	v_mfma_f32_16x16x32_bf16 v[50:53], v[144:147], v[176:179], v[50:53]
	v_mfma_f32_16x16x32_bf16 v[46:49], v[136:139], v[184:187], v[46:49]
	v_mfma_f32_16x16x32_bf16 v[42:45], v[144:147], v[184:187], v[42:45]
	v_mfma_f32_16x16x32_bf16 v[38:41], v[136:139], v[192:195], v[38:41]
	v_mfma_f32_16x16x32_bf16 v[34:37], v[144:147], v[192:195], v[34:37]
	v_mfma_f32_16x16x32_bf16 v[62:65], v[140:143], v[172:175], v[62:65]
	v_mfma_f32_16x16x32_bf16 v[58:61], v[148:151], v[172:175], v[58:61]
	v_mfma_f32_16x16x32_bf16 v[54:57], v[140:143], v[180:183], v[54:57]
	v_mfma_f32_16x16x32_bf16 v[50:53], v[148:151], v[180:183], v[50:53]
	v_mfma_f32_16x16x32_bf16 v[46:49], v[140:143], v[188:191], v[46:49]
	v_mfma_f32_16x16x32_bf16 v[42:45], v[148:151], v[188:191], v[42:45]
	v_mfma_f32_16x16x32_bf16 v[38:41], v[140:143], v[196:199], v[38:41]
	v_mfma_f32_16x16x32_bf16 v[34:37], v[148:151], v[196:199], v[34:37]
	s_setprio 0
	s_setprio 1
	v_mfma_f32_16x16x32_bf16 v[30:33], v[152:155], v[168:171], v[30:33]
	v_mfma_f32_16x16x32_bf16 v[26:29], v[160:163], v[168:171], v[26:29]
	v_mfma_f32_16x16x32_bf16 v[22:25], v[152:155], v[176:179], v[22:25]
	v_mfma_f32_16x16x32_bf16 v[18:21], v[160:163], v[176:179], v[18:21]
	v_mfma_f32_16x16x32_bf16 v[12:15], v[152:155], v[184:187], v[12:15]
	v_mfma_f32_16x16x32_bf16 v[8:11], v[160:163], v[184:187], v[8:11]
	v_mfma_f32_16x16x32_bf16 v[4:7], v[152:155], v[192:195], v[4:7]
	v_mfma_f32_16x16x32_bf16 v[0:3], v[160:163], v[192:195], v[0:3]
	v_mfma_f32_16x16x32_bf16 v[30:33], v[156:159], v[172:175], v[30:33]
	v_mfma_f32_16x16x32_bf16 v[26:29], v[164:167], v[172:175], v[26:29]
	v_mfma_f32_16x16x32_bf16 v[22:25], v[156:159], v[180:183], v[22:25]
	v_mfma_f32_16x16x32_bf16 v[18:21], v[164:167], v[180:183], v[18:21]
	v_mfma_f32_16x16x32_bf16 v[12:15], v[156:159], v[188:191], v[12:15]
	v_mfma_f32_16x16x32_bf16 v[8:11], v[164:167], v[188:191], v[8:11]
	v_mfma_f32_16x16x32_bf16 v[4:7], v[156:159], v[196:199], v[4:7]
	v_mfma_f32_16x16x32_bf16 v[0:3], v[164:167], v[196:199], v[0:3]
	s_setprio 0
	s_barrier
	s_add_i32 s89, 0, 0x18000
	s_add_i32 s90, 0, 0x1c000
	v_add_u32_e32 v148, s89, v224
	v_add_u32_e32 v164, s90, v224
	ds_read_b128 v[136:139], v148
	ds_read_b128 v[140:143], v148 offset:1024
	ds_read_b128 v[144:147], v148 offset:2048
	ds_read_b128 v[148:151], v148 offset:3072
	ds_read_b128 v[152:155], v164
	ds_read_b128 v[156:159], v164 offset:1024
	ds_read_b128 v[160:163], v164 offset:2048
	ds_read_b128 v[164:167], v164 offset:3072
	s_add_u32 s46, s46, 0x80000
	s_addc_u32 s47, s47, 0
	s_mov_b32 m0, s51
	ds_read_b128 v[168:171], v226 offset:32768
	ds_read_b128 v[172:175], v226 offset:33792
	ds_read_b128 v[176:179], v226 offset:34816
	ds_read_b128 v[180:183], v226 offset:35840
	ds_read_b128 v[184:187], v226 offset:36864
	ds_read_b128 v[188:191], v226 offset:37888
	ds_read_b128 v[192:195], v226 offset:38912
	ds_read_b128 v[196:199], v226 offset:39936
	global_load_lds_dwordx4 v16, s[46:47]
	s_mov_b32 m0, s52
	s_nop 0
	global_load_lds_dwordx4 v130, s[46:47]
	s_waitcnt vmcnt(8)
	s_waitcnt lgkmcnt(0)
	s_barrier
	s_setprio 1
	s_waitcnt lgkmcnt(0)
	s_nop 0
	v_mfma_f32_16x16x32_bf16 v[126:129], v[136:139], v[168:171], v[126:129]
	v_mfma_f32_16x16x32_bf16 v[122:125], v[144:147], v[168:171], v[122:125]
	v_mfma_f32_16x16x32_bf16 v[118:121], v[136:139], v[176:179], v[118:121]
	v_mfma_f32_16x16x32_bf16 v[114:117], v[144:147], v[176:179], v[114:117]
	v_mfma_f32_16x16x32_bf16 v[110:113], v[136:139], v[184:187], v[110:113]
	v_mfma_f32_16x16x32_bf16 v[106:109], v[144:147], v[184:187], v[106:109]
	v_mfma_f32_16x16x32_bf16 v[102:105], v[136:139], v[192:195], v[102:105]
	v_mfma_f32_16x16x32_bf16 v[98:101], v[144:147], v[192:195], v[98:101]
	v_mfma_f32_16x16x32_bf16 v[126:129], v[140:143], v[172:175], v[126:129]
	v_mfma_f32_16x16x32_bf16 v[122:125], v[148:151], v[172:175], v[122:125]
	v_mfma_f32_16x16x32_bf16 v[118:121], v[140:143], v[180:183], v[118:121]
	v_mfma_f32_16x16x32_bf16 v[114:117], v[148:151], v[180:183], v[114:117]
	v_mfma_f32_16x16x32_bf16 v[110:113], v[140:143], v[188:191], v[110:113]
	v_mfma_f32_16x16x32_bf16 v[106:109], v[148:151], v[188:191], v[106:109]
	v_mfma_f32_16x16x32_bf16 v[102:105], v[140:143], v[196:199], v[102:105]
	v_mfma_f32_16x16x32_bf16 v[98:101], v[148:151], v[196:199], v[98:101]
	s_setprio 0
	s_setprio 1
	v_mfma_f32_16x16x32_bf16 v[94:97], v[152:155], v[168:171], v[94:97]
	v_mfma_f32_16x16x32_bf16 v[90:93], v[160:163], v[168:171], v[90:93]
	v_mfma_f32_16x16x32_bf16 v[86:89], v[152:155], v[176:179], v[86:89]
	v_mfma_f32_16x16x32_bf16 v[82:85], v[160:163], v[176:179], v[82:85]
	v_mfma_f32_16x16x32_bf16 v[78:81], v[152:155], v[184:187], v[78:81]
	v_mfma_f32_16x16x32_bf16 v[74:77], v[160:163], v[184:187], v[74:77]
	v_mfma_f32_16x16x32_bf16 v[70:73], v[152:155], v[192:195], v[70:73]
	v_mfma_f32_16x16x32_bf16 v[66:69], v[160:163], v[192:195], v[66:69]
	v_mfma_f32_16x16x32_bf16 v[94:97], v[156:159], v[172:175], v[94:97]
	v_mfma_f32_16x16x32_bf16 v[90:93], v[164:167], v[172:175], v[90:93]
	v_mfma_f32_16x16x32_bf16 v[86:89], v[156:159], v[180:183], v[86:89]
	v_mfma_f32_16x16x32_bf16 v[82:85], v[164:167], v[180:183], v[82:85]
	v_mfma_f32_16x16x32_bf16 v[78:81], v[156:159], v[188:191], v[78:81]
	v_mfma_f32_16x16x32_bf16 v[74:77], v[164:167], v[188:191], v[74:77]
	v_mfma_f32_16x16x32_bf16 v[70:73], v[156:159], v[196:199], v[70:73]
	v_mfma_f32_16x16x32_bf16 v[66:69], v[164:167], v[196:199], v[66:69]
	s_setprio 0
	s_barrier
	s_add_i32 s46, s89, s37
	s_add_u32 s28, s28, 0x80
	s_addc_u32 s29, s29, 0
	s_mov_b32 m0, s46
	ds_read_b128 v[168:171], v226 offset:49152
	ds_read_b128 v[172:175], v226 offset:50176
	ds_read_b128 v[176:179], v226 offset:51200
	ds_read_b128 v[180:183], v226 offset:52224
	ds_read_b128 v[184:187], v226 offset:53248
	ds_read_b128 v[188:191], v226 offset:54272
	ds_read_b128 v[192:195], v226 offset:55296
	ds_read_b128 v[196:199], v226 offset:56320
	global_load_lds_dwordx4 v16, s[28:29]
	s_add_i32 m0, s46, 0x2000
	s_add_i32 s46, s90, s37
	global_load_lds_dwordx4 v130, s[28:29]
	s_add_u32 s28, s28, 0x80000
	s_addc_u32 s29, s29, 0
	s_mov_b32 m0, s46
	s_nop 0
	global_load_lds_dwordx4 v16, s[28:29]
	s_add_i32 m0, s46, 0x2000
	s_nop 0
	global_load_lds_dwordx4 v130, s[28:29]
	v_lshl_add_u64 v[200:201], v[204:205], 0, s[34:35]
	s_mov_b32 m0, s53
	s_nop 0
	global_load_lds_dwordx4 v[200:201], off
	v_lshl_add_u64 v[200:201], v[206:207], 0, s[34:35]
	s_mov_b32 m0, s58
	s_nop 0
	global_load_lds_dwordx4 v[200:201], off
	s_waitcnt vmcnt(8)
	s_waitcnt lgkmcnt(0)
	s_barrier
	s_setprio 1
	s_waitcnt lgkmcnt(0)
	s_nop 0
	v_mfma_f32_16x16x32_bf16 v[62:65], v[136:139], v[168:171], v[62:65]
	v_mfma_f32_16x16x32_bf16 v[58:61], v[144:147], v[168:171], v[58:61]
	v_mfma_f32_16x16x32_bf16 v[54:57], v[136:139], v[176:179], v[54:57]
	v_mfma_f32_16x16x32_bf16 v[50:53], v[144:147], v[176:179], v[50:53]
	v_mfma_f32_16x16x32_bf16 v[46:49], v[136:139], v[184:187], v[46:49]
	v_mfma_f32_16x16x32_bf16 v[42:45], v[144:147], v[184:187], v[42:45]
	v_mfma_f32_16x16x32_bf16 v[38:41], v[136:139], v[192:195], v[38:41]
	v_mfma_f32_16x16x32_bf16 v[34:37], v[144:147], v[192:195], v[34:37]
	v_mfma_f32_16x16x32_bf16 v[62:65], v[140:143], v[172:175], v[62:65]
	v_mfma_f32_16x16x32_bf16 v[58:61], v[148:151], v[172:175], v[58:61]
	v_mfma_f32_16x16x32_bf16 v[54:57], v[140:143], v[180:183], v[54:57]
	v_mfma_f32_16x16x32_bf16 v[50:53], v[148:151], v[180:183], v[50:53]
	v_mfma_f32_16x16x32_bf16 v[46:49], v[140:143], v[188:191], v[46:49]
	v_mfma_f32_16x16x32_bf16 v[42:45], v[148:151], v[188:191], v[42:45]
	v_mfma_f32_16x16x32_bf16 v[38:41], v[140:143], v[196:199], v[38:41]
	v_mfma_f32_16x16x32_bf16 v[34:37], v[148:151], v[196:199], v[34:37]
	s_setprio 0
	s_setprio 1
	v_mfma_f32_16x16x32_bf16 v[30:33], v[152:155], v[168:171], v[30:33]
	v_mfma_f32_16x16x32_bf16 v[26:29], v[160:163], v[168:171], v[26:29]
	v_mfma_f32_16x16x32_bf16 v[22:25], v[152:155], v[176:179], v[22:25]
	v_mfma_f32_16x16x32_bf16 v[18:21], v[160:163], v[176:179], v[18:21]
	v_mfma_f32_16x16x32_bf16 v[12:15], v[152:155], v[184:187], v[12:15]
	v_mfma_f32_16x16x32_bf16 v[8:11], v[160:163], v[184:187], v[8:11]
	v_mfma_f32_16x16x32_bf16 v[4:7], v[152:155], v[192:195], v[4:7]
	v_mfma_f32_16x16x32_bf16 v[0:3], v[160:163], v[192:195], v[0:3]
	v_mfma_f32_16x16x32_bf16 v[30:33], v[156:159], v[172:175], v[30:33]
	v_mfma_f32_16x16x32_bf16 v[26:29], v[164:167], v[172:175], v[26:29]
	v_mfma_f32_16x16x32_bf16 v[22:25], v[156:159], v[180:183], v[22:25]
	v_mfma_f32_16x16x32_bf16 v[18:21], v[164:167], v[180:183], v[18:21]
	v_mfma_f32_16x16x32_bf16 v[12:15], v[156:159], v[188:191], v[12:15]
	v_mfma_f32_16x16x32_bf16 v[8:11], v[164:167], v[188:191], v[8:11]
	v_mfma_f32_16x16x32_bf16 v[4:7], v[156:159], v[196:199], v[4:7]
	v_mfma_f32_16x16x32_bf16 v[0:3], v[164:167], v[196:199], v[0:3]
	s_setprio 0
	s_barrier
	s_add_i32 s88, s88, 2
	s_add_u32 s44, s44, 0x100
	s_addc_u32 s45, s45, 0
	s_add_u32 s86, s86, 0x100
	s_addc_u32 s87, s87, 0
	s_cmp_gt_u32 s88, 29
	s_cbranch_scc0 .LBB0_717

.LBB0_786:
	s_ashr_i32 s43, s42, 31
	s_lshl_b64 s[28:29], s[42:43], 20
	s_add_u32 s44, s72, s28
	s_addc_u32 s45, s73, s29
	s_and_b64 s[28:29], s[38:39], exec
	s_cselect_b32 s43, s45, s51
	s_cselect_b32 s91, s44, s50
	s_ashr_i32 s41, s40, 31
	s_lshl_b64 s[28:29], s[40:41], 20
	v_readlane_b32 s41, v255, 14
	s_add_u32 s46, s41, s28
	v_readlane_b32 s28, v255, 15
	s_addc_u32 s47, s28, s29
	s_and_b64 s[28:29], s[38:39], exec
	s_cselect_b32 s41, s47, s53
	s_cselect_b32 vcc_lo, s46, s52
	s_add_u32 s50, s50, 0x80080
	s_addc_u32 s51, s51, 0
	s_add_u32 vcc_hi, s52, 0x100
	s_addc_u32 s92, s53, 0
	s_mov_b32 s93, -2
	s_add_u32 s28, s50, 0xfff80080
	s_addc_u32 s29, s51, -1
	s_add_i32 s94, 0, 0x10000
	s_cmp_eq_u32 s93, 28
	s_cselect_b32 s53, s43, s29
	s_cselect_b32 s52, s91, s28
	s_cselect_b32 s29, s41, s92
	s_cselect_b32 s28, vcc_lo, vcc_hi
	s_add_i32 s96, 0, 0x14000
	s_waitcnt vmcnt(0)
	v_add_u32_e32 v142, s94, v207
	v_add_u32_e32 v158, s96, v207
	ds_read_b128 v[130:133], v142
	ds_read_b128 v[134:137], v142 offset:1024
	ds_read_b128 v[138:141], v142 offset:2048
	ds_read_b128 v[142:145], v142 offset:3072
	ds_read_b128 v[146:149], v158
	ds_read_b128 v[150:153], v158 offset:1024
	ds_read_b128 v[154:157], v158 offset:2048
	ds_read_b128 v[158:161], v158 offset:3072
	s_add_i32 m0, s59, 0xc000
	ds_read_b128 v[162:165], v224
	ds_read_b128 v[166:169], v224 offset:1024
	ds_read_b128 v[170:173], v224 offset:2048
	ds_read_b128 v[174:177], v224 offset:3072
	ds_read_b128 v[178:181], v224 offset:4096
	ds_read_b128 v[182:185], v224 offset:5120
	ds_read_b128 v[196:199], v224 offset:6144
	ds_read_b128 v[200:203], v224 offset:7168
	global_load_lds_dwordx4 v192, s[50:51]
	s_add_i32 m0, s59, 0xe000
	s_nop 0
	global_load_lds_dwordx4 v194, s[50:51]
	s_waitcnt vmcnt(8)
	s_waitcnt lgkmcnt(0)
	s_barrier
	s_setprio 1
	s_waitcnt lgkmcnt(0)
	s_nop 0
	v_mfma_f32_16x16x32_bf16 v[126:129], v[130:133], v[162:165], 0
	v_mfma_f32_16x16x32_bf16 v[122:125], v[138:141], v[162:165], 0
	v_mfma_f32_16x16x32_bf16 v[114:117], v[130:133], v[170:173], 0
	v_mfma_f32_16x16x32_bf16 v[106:109], v[138:141], v[170:173], 0
	v_mfma_f32_16x16x32_bf16 v[98:101], v[130:133], v[178:181], 0
	v_mfma_f32_16x16x32_bf16 v[90:93], v[138:141], v[178:181], 0
	v_mfma_f32_16x16x32_bf16 v[82:85], v[130:133], v[196:199], 0
	v_mfma_f32_16x16x32_bf16 v[74:77], v[138:141], v[196:199], 0
	v_mfma_f32_16x16x32_bf16 v[126:129], v[134:137], v[166:169], v[126:129]
	v_mfma_f32_16x16x32_bf16 v[122:125], v[142:145], v[166:169], v[122:125]
	v_mfma_f32_16x16x32_bf16 v[114:117], v[134:137], v[174:177], v[114:117]
	v_mfma_f32_16x16x32_bf16 v[106:109], v[142:145], v[174:177], v[106:109]
	v_mfma_f32_16x16x32_bf16 v[98:101], v[134:137], v[182:185], v[98:101]
	v_mfma_f32_16x16x32_bf16 v[90:93], v[142:145], v[182:185], v[90:93]
	v_mfma_f32_16x16x32_bf16 v[82:85], v[134:137], v[200:203], v[82:85]
	v_mfma_f32_16x16x32_bf16 v[74:77], v[142:145], v[200:203], v[74:77]
	s_setprio 0
	s_setprio 1
	v_mfma_f32_16x16x32_bf16 v[118:121], v[146:149], v[162:165], 0
	v_mfma_f32_16x16x32_bf16 v[110:113], v[154:157], v[162:165], 0
	v_mfma_f32_16x16x32_bf16 v[102:105], v[146:149], v[170:173], 0
	v_mfma_f32_16x16x32_bf16 v[94:97], v[154:157], v[170:173], 0
	v_mfma_f32_16x16x32_bf16 v[86:89], v[146:149], v[178:181], 0
	v_mfma_f32_16x16x32_bf16 v[78:81], v[154:157], v[178:181], 0
	v_mfma_f32_16x16x32_bf16 v[70:73], v[146:149], v[196:199], 0
	v_mfma_f32_16x16x32_bf16 v[66:69], v[154:157], v[196:199], 0
	v_mfma_f32_16x16x32_bf16 v[118:121], v[150:153], v[166:169], v[118:121]
	v_mfma_f32_16x16x32_bf16 v[110:113], v[158:161], v[166:169], v[110:113]
	v_mfma_f32_16x16x32_bf16 v[102:105], v[150:153], v[174:177], v[102:105]
	v_mfma_f32_16x16x32_bf16 v[94:97], v[158:161], v[174:177], v[94:97]
	v_mfma_f32_16x16x32_bf16 v[86:89], v[150:153], v[182:185], v[86:89]
	v_mfma_f32_16x16x32_bf16 v[78:81], v[158:161], v[182:185], v[78:81]
	v_mfma_f32_16x16x32_bf16 v[70:73], v[150:153], v[200:203], v[70:73]
	v_mfma_f32_16x16x32_bf16 v[66:69], v[158:161], v[200:203], v[66:69]
	s_setprio 0
	s_barrier
	s_add_i32 s94, s94, s37
	s_mov_b32 m0, s94
	ds_read_b128 v[162:165], v224 offset:16384
	ds_read_b128 v[166:169], v224 offset:17408
	ds_read_b128 v[170:173], v224 offset:18432
	ds_read_b128 v[174:177], v224 offset:19456
	ds_read_b128 v[178:181], v224 offset:20480
	ds_read_b128 v[182:185], v224 offset:21504
	ds_read_b128 v[196:199], v224 offset:22528
	ds_read_b128 v[200:203], v224 offset:23552
	global_load_lds_dwordx4 v16, s[28:29]
	s_add_i32 m0, s94, 0x2000
	s_add_u32 s94, s28, 0x80000
	s_addc_u32 s95, s29, 0
	s_add_i32 s96, s96, s37
	global_load_lds_dwordx4 v186, s[28:29]
	s_mov_b32 m0, s96
	v_lshl_add_u64 v[230:231], s[52:53], 0, v[188:189]
	global_load_lds_dwordx4 v16, s[94:95]
	s_add_i32 m0, s96, 0x2000
	s_nop 0
	global_load_lds_dwordx4 v186, s[94:95]
	v_lshl_add_u64 v[228:229], s[52:53], 0, v[190:191]
	s_mov_b32 m0, s59
	s_nop 0
	global_load_lds_dwordx4 v[228:229], off
	s_mov_b32 m0, s83
	s_nop 0
	global_load_lds_dwordx4 v[230:231], off
	s_waitcnt vmcnt(8)
	s_waitcnt lgkmcnt(0)
	s_barrier
	s_setprio 1
	s_waitcnt lgkmcnt(0)
	s_nop 0
	v_mfma_f32_16x16x32_bf16 v[62:65], v[130:133], v[162:165], 0
	v_mfma_f32_16x16x32_bf16 v[58:61], v[138:141], v[162:165], 0
	v_mfma_f32_16x16x32_bf16 v[50:53], v[130:133], v[170:173], 0
	v_mfma_f32_16x16x32_bf16 v[42:45], v[138:141], v[170:173], 0
	v_mfma_f32_16x16x32_bf16 v[34:37], v[130:133], v[178:181], 0
	v_mfma_f32_16x16x32_bf16 v[26:29], v[138:141], v[178:181], 0
	v_mfma_f32_16x16x32_bf16 v[18:21], v[130:133], v[196:199], 0
	v_mfma_f32_16x16x32_bf16 v[8:11], v[138:141], v[196:199], 0
	v_mfma_f32_16x16x32_bf16 v[62:65], v[134:137], v[166:169], v[62:65]
	v_mfma_f32_16x16x32_bf16 v[58:61], v[142:145], v[166:169], v[58:61]
	v_mfma_f32_16x16x32_bf16 v[50:53], v[134:137], v[174:177], v[50:53]
	v_mfma_f32_16x16x32_bf16 v[42:45], v[142:145], v[174:177], v[42:45]
	v_mfma_f32_16x16x32_bf16 v[34:37], v[134:137], v[182:185], v[34:37]
	v_mfma_f32_16x16x32_bf16 v[26:29], v[142:145], v[182:185], v[26:29]
	v_mfma_f32_16x16x32_bf16 v[18:21], v[134:137], v[200:203], v[18:21]
	v_mfma_f32_16x16x32_bf16 v[8:11], v[142:145], v[200:203], v[8:11]
	s_setprio 0
	s_setprio 1
	v_mfma_f32_16x16x32_bf16 v[54:57], v[146:149], v[162:165], 0
	v_mfma_f32_16x16x32_bf16 v[46:49], v[154:157], v[162:165], 0
	v_mfma_f32_16x16x32_bf16 v[38:41], v[146:149], v[170:173], 0
	v_mfma_f32_16x16x32_bf16 v[30:33], v[154:157], v[170:173], 0
	v_mfma_f32_16x16x32_bf16 v[22:25], v[146:149], v[178:181], 0
	v_mfma_f32_16x16x32_bf16 v[12:15], v[154:157], v[178:181], 0
	v_mfma_f32_16x16x32_bf16 v[4:7], v[146:149], v[196:199], 0
	v_mfma_f32_16x16x32_bf16 v[0:3], v[154:157], v[196:199], 0
	v_mfma_f32_16x16x32_bf16 v[54:57], v[150:153], v[166:169], v[54:57]
	v_mfma_f32_16x16x32_bf16 v[46:49], v[158:161], v[166:169], v[46:49]
	v_mfma_f32_16x16x32_bf16 v[38:41], v[150:153], v[174:177], v[38:41]
	v_mfma_f32_16x16x32_bf16 v[30:33], v[158:161], v[174:177], v[30:33]
	v_mfma_f32_16x16x32_bf16 v[22:25], v[150:153], v[182:185], v[22:25]
	v_mfma_f32_16x16x32_bf16 v[12:15], v[158:161], v[182:185], v[12:15]
	v_mfma_f32_16x16x32_bf16 v[4:7], v[150:153], v[200:203], v[4:7]
	v_mfma_f32_16x16x32_bf16 v[0:3], v[158:161], v[200:203], v[0:3]
	s_setprio 0
	s_barrier
	s_add_i32 s94, 0, 0x18000
	s_add_i32 s95, 0, 0x1c000
	v_add_u32_e32 v142, s94, v207
	v_add_u32_e32 v158, s95, v207
	ds_read_b128 v[130:133], v142
	ds_read_b128 v[134:137], v142 offset:1024
	ds_read_b128 v[138:141], v142 offset:2048
	ds_read_b128 v[142:145], v142 offset:3072
	ds_read_b128 v[146:149], v158
	ds_read_b128 v[150:153], v158 offset:1024
	ds_read_b128 v[154:157], v158 offset:2048
	ds_read_b128 v[158:161], v158 offset:3072
	s_add_u32 s52, s52, 0x80000
	s_addc_u32 s53, s53, 0
	s_mov_b32 m0, s84
	ds_read_b128 v[162:165], v224 offset:32768
	ds_read_b128 v[166:169], v224 offset:33792
	ds_read_b128 v[170:173], v224 offset:34816
	ds_read_b128 v[174:177], v224 offset:35840
	ds_read_b128 v[178:181], v224 offset:36864
	ds_read_b128 v[182:185], v224 offset:37888
	ds_read_b128 v[196:199], v224 offset:38912
	ds_read_b128 v[200:203], v224 offset:39936
	global_load_lds_dwordx4 v190, s[52:53]
	s_mov_b32 m0, s85
	s_nop 0
	global_load_lds_dwordx4 v188, s[52:53]
	s_waitcnt vmcnt(8)
	s_waitcnt lgkmcnt(0)
	s_barrier
	s_setprio 1
	s_waitcnt lgkmcnt(0)
	s_nop 0
	v_mfma_f32_16x16x32_bf16 v[126:129], v[130:133], v[162:165], v[126:129]
	v_mfma_f32_16x16x32_bf16 v[122:125], v[138:141], v[162:165], v[122:125]
	v_mfma_f32_16x16x32_bf16 v[114:117], v[130:133], v[170:173], v[114:117]
	v_mfma_f32_16x16x32_bf16 v[106:109], v[138:141], v[170:173], v[106:109]
	v_mfma_f32_16x16x32_bf16 v[98:101], v[130:133], v[178:181], v[98:101]
	v_mfma_f32_16x16x32_bf16 v[90:93], v[138:141], v[178:181], v[90:93]
	v_mfma_f32_16x16x32_bf16 v[82:85], v[130:133], v[196:199], v[82:85]
	v_mfma_f32_16x16x32_bf16 v[74:77], v[138:141], v[196:199], v[74:77]
	v_mfma_f32_16x16x32_bf16 v[126:129], v[134:137], v[166:169], v[126:129]
	v_mfma_f32_16x16x32_bf16 v[122:125], v[142:145], v[166:169], v[122:125]
	v_mfma_f32_16x16x32_bf16 v[114:117], v[134:137], v[174:177], v[114:117]
	v_mfma_f32_16x16x32_bf16 v[106:109], v[142:145], v[174:177], v[106:109]
	v_mfma_f32_16x16x32_bf16 v[98:101], v[134:137], v[182:185], v[98:101]
	v_mfma_f32_16x16x32_bf16 v[90:93], v[142:145], v[182:185], v[90:93]
	v_mfma_f32_16x16x32_bf16 v[82:85], v[134:137], v[200:203], v[82:85]
	v_mfma_f32_16x16x32_bf16 v[74:77], v[142:145], v[200:203], v[74:77]
	s_setprio 0
	s_setprio 1
	v_mfma_f32_16x16x32_bf16 v[118:121], v[146:149], v[162:165], v[118:121]
	v_mfma_f32_16x16x32_bf16 v[110:113], v[154:157], v[162:165], v[110:113]
	v_mfma_f32_16x16x32_bf16 v[102:105], v[146:149], v[170:173], v[102:105]
	v_mfma_f32_16x16x32_bf16 v[94:97], v[154:157], v[170:173], v[94:97]
	v_mfma_f32_16x16x32_bf16 v[86:89], v[146:149], v[178:181], v[86:89]
	v_mfma_f32_16x16x32_bf16 v[78:81], v[154:157], v[178:181], v[78:81]
	v_mfma_f32_16x16x32_bf16 v[70:73], v[146:149], v[196:199], v[70:73]
	v_mfma_f32_16x16x32_bf16 v[66:69], v[154:157], v[196:199], v[66:69]
	v_mfma_f32_16x16x32_bf16 v[118:121], v[150:153], v[166:169], v[118:121]
	v_mfma_f32_16x16x32_bf16 v[110:113], v[158:161], v[166:169], v[110:113]
	v_mfma_f32_16x16x32_bf16 v[102:105], v[150:153], v[174:177], v[102:105]
	v_mfma_f32_16x16x32_bf16 v[94:97], v[158:161], v[174:177], v[94:97]
	v_mfma_f32_16x16x32_bf16 v[86:89], v[150:153], v[182:185], v[86:89]
	v_mfma_f32_16x16x32_bf16 v[78:81], v[158:161], v[182:185], v[78:81]
	v_mfma_f32_16x16x32_bf16 v[70:73], v[150:153], v[200:203], v[70:73]
	v_mfma_f32_16x16x32_bf16 v[66:69], v[158:161], v[200:203], v[66:69]
	s_setprio 0
	s_barrier
	s_add_i32 s52, s94, s37
	s_add_u32 s28, s28, 0x80
	s_addc_u32 s29, s29, 0
	s_mov_b32 m0, s52
	ds_read_b128 v[162:165], v224 offset:49152
	ds_read_b128 v[166:169], v224 offset:50176
	ds_read_b128 v[170:173], v224 offset:51200
	ds_read_b128 v[174:177], v224 offset:52224
	ds_read_b128 v[178:181], v224 offset:53248
	ds_read_b128 v[182:185], v224 offset:54272
	ds_read_b128 v[196:199], v224 offset:55296
	ds_read_b128 v[200:203], v224 offset:56320
	global_load_lds_dwordx4 v16, s[28:29]
	s_add_i32 m0, s52, 0x2000
	s_add_i32 s52, s95, s37
	global_load_lds_dwordx4 v186, s[28:29]
	s_add_u32 s28, s28, 0x80000
	s_addc_u32 s29, s29, 0
	s_mov_b32 m0, s52
	s_nop 0
	global_load_lds_dwordx4 v16, s[28:29]
	s_add_i32 m0, s52, 0x2000
	s_nop 0
	global_load_lds_dwordx4 v186, s[28:29]
	v_lshl_add_u64 v[204:205], v[228:229], 0, s[34:35]
	s_mov_b32 m0, s88
	s_nop 0
	global_load_lds_dwordx4 v[204:205], off
	v_lshl_add_u64 v[204:205], v[230:231], 0, s[34:35]
	s_mov_b32 m0, s89
	s_nop 0
	global_load_lds_dwordx4 v[204:205], off
	s_waitcnt vmcnt(8)
	s_waitcnt lgkmcnt(0)
	s_barrier
	s_setprio 1
	s_waitcnt lgkmcnt(0)
	s_nop 0
	v_mfma_f32_16x16x32_bf16 v[62:65], v[130:133], v[162:165], v[62:65]
	v_mfma_f32_16x16x32_bf16 v[58:61], v[138:141], v[162:165], v[58:61]
	v_mfma_f32_16x16x32_bf16 v[50:53], v[130:133], v[170:173], v[50:53]
	v_mfma_f32_16x16x32_bf16 v[42:45], v[138:141], v[170:173], v[42:45]
	v_mfma_f32_16x16x32_bf16 v[34:37], v[130:133], v[178:181], v[34:37]
	v_mfma_f32_16x16x32_bf16 v[26:29], v[138:141], v[178:181], v[26:29]
	v_mfma_f32_16x16x32_bf16 v[18:21], v[130:133], v[196:199], v[18:21]
	v_mfma_f32_16x16x32_bf16 v[8:11], v[138:141], v[196:199], v[8:11]
	v_mfma_f32_16x16x32_bf16 v[62:65], v[134:137], v[166:169], v[62:65]
	v_mfma_f32_16x16x32_bf16 v[58:61], v[142:145], v[166:169], v[58:61]
	v_mfma_f32_16x16x32_bf16 v[50:53], v[134:137], v[174:177], v[50:53]
	v_mfma_f32_16x16x32_bf16 v[42:45], v[142:145], v[174:177], v[42:45]
	v_mfma_f32_16x16x32_bf16 v[34:37], v[134:137], v[182:185], v[34:37]
	v_mfma_f32_16x16x32_bf16 v[26:29], v[142:145], v[182:185], v[26:29]
	v_mfma_f32_16x16x32_bf16 v[18:21], v[134:137], v[200:203], v[18:21]
	v_mfma_f32_16x16x32_bf16 v[8:11], v[142:145], v[200:203], v[8:11]
	s_setprio 0
	s_setprio 1
	v_mfma_f32_16x16x32_bf16 v[54:57], v[146:149], v[162:165], v[54:57]
	v_mfma_f32_16x16x32_bf16 v[46:49], v[154:157], v[162:165], v[46:49]
	v_mfma_f32_16x16x32_bf16 v[38:41], v[146:149], v[170:173], v[38:41]
	v_mfma_f32_16x16x32_bf16 v[30:33], v[154:157], v[170:173], v[30:33]
	v_mfma_f32_16x16x32_bf16 v[22:25], v[146:149], v[178:181], v[22:25]
	v_mfma_f32_16x16x32_bf16 v[12:15], v[154:157], v[178:181], v[12:15]
	v_mfma_f32_16x16x32_bf16 v[4:7], v[146:149], v[196:199], v[4:7]
	v_mfma_f32_16x16x32_bf16 v[0:3], v[154:157], v[196:199], v[0:3]
	v_mfma_f32_16x16x32_bf16 v[54:57], v[150:153], v[166:169], v[54:57]
	v_mfma_f32_16x16x32_bf16 v[46:49], v[158:161], v[166:169], v[46:49]
	v_mfma_f32_16x16x32_bf16 v[38:41], v[150:153], v[174:177], v[38:41]
	v_mfma_f32_16x16x32_bf16 v[30:33], v[158:161], v[174:177], v[30:33]
	v_mfma_f32_16x16x32_bf16 v[22:25], v[150:153], v[182:185], v[22:25]
	v_mfma_f32_16x16x32_bf16 v[12:15], v[158:161], v[182:185], v[12:15]
	v_mfma_f32_16x16x32_bf16 v[4:7], v[150:153], v[200:203], v[4:7]
	v_mfma_f32_16x16x32_bf16 v[0:3], v[158:161], v[200:203], v[0:3]
	s_setprio 0
	s_barrier
	s_add_i32 s93, s93, 2
	s_add_u32 s50, s50, 0x100
	s_addc_u32 s51, s51, 0
	s_add_u32 vcc_hi, vcc_hi, 0x100
	s_addc_u32 s92, s92, 0
	s_cmp_gt_u32 s93, 29
	s_cbranch_scc1 .Lpz_G_exit
.LBB0_787:
	s_add_u32 s28, s50, 0xfff80080
	s_addc_u32 s29, s51, -1
	s_add_i32 s94, 0, 0x10000
	s_cmp_eq_u32 s93, 28
	s_cselect_b32 s53, s43, s29
	s_cselect_b32 s52, s91, s28
	s_cselect_b32 s29, s41, s92
	s_cselect_b32 s28, vcc_lo, vcc_hi
	s_add_i32 s96, 0, 0x14000
	s_waitcnt vmcnt(0)
	v_add_u32_e32 v142, s94, v207
	v_add_u32_e32 v158, s96, v207
	ds_read_b128 v[130:133], v142
	ds_read_b128 v[134:137], v142 offset:1024
	ds_read_b128 v[138:141], v142 offset:2048
	ds_read_b128 v[142:145], v142 offset:3072
	ds_read_b128 v[146:149], v158
	ds_read_b128 v[150:153], v158 offset:1024
	ds_read_b128 v[154:157], v158 offset:2048
	ds_read_b128 v[158:161], v158 offset:3072
	s_add_i32 m0, s59, 0xc000
	ds_read_b128 v[162:165], v224
	ds_read_b128 v[166:169], v224 offset:1024
	ds_read_b128 v[170:173], v224 offset:2048
	ds_read_b128 v[174:177], v224 offset:3072
	ds_read_b128 v[178:181], v224 offset:4096
	ds_read_b128 v[182:185], v224 offset:5120
	ds_read_b128 v[196:199], v224 offset:6144
	ds_read_b128 v[200:203], v224 offset:7168
	global_load_lds_dwordx4 v192, s[50:51]
	s_add_i32 m0, s59, 0xe000
	s_nop 0
	global_load_lds_dwordx4 v194, s[50:51]
	s_waitcnt vmcnt(8)
	s_waitcnt lgkmcnt(0)
	s_barrier
	s_setprio 1
	s_waitcnt lgkmcnt(0)
	v_mfma_f32_16x16x32_bf16 v[126:129], v[130:133], v[162:165], v[126:129]
	v_mfma_f32_16x16x32_bf16 v[122:125], v[138:141], v[162:165], v[122:125]
	v_mfma_f32_16x16x32_bf16 v[114:117], v[130:133], v[170:173], v[114:117]
	v_mfma_f32_16x16x32_bf16 v[106:109], v[138:141], v[170:173], v[106:109]
	v_mfma_f32_16x16x32_bf16 v[98:101], v[130:133], v[178:181], v[98:101]
	v_mfma_f32_16x16x32_bf16 v[90:93], v[138:141], v[178:181], v[90:93]
	v_mfma_f32_16x16x32_bf16 v[82:85], v[130:133], v[196:199], v[82:85]
	v_mfma_f32_16x16x32_bf16 v[74:77], v[138:141], v[196:199], v[74:77]
	v_mfma_f32_16x16x32_bf16 v[126:129], v[134:137], v[166:169], v[126:129]
	v_mfma_f32_16x16x32_bf16 v[122:125], v[142:145], v[166:169], v[122:125]
	v_mfma_f32_16x16x32_bf16 v[114:117], v[134:137], v[174:177], v[114:117]
	v_mfma_f32_16x16x32_bf16 v[106:109], v[142:145], v[174:177], v[106:109]
	v_mfma_f32_16x16x32_bf16 v[98:101], v[134:137], v[182:185], v[98:101]
	v_mfma_f32_16x16x32_bf16 v[90:93], v[142:145], v[182:185], v[90:93]
	v_mfma_f32_16x16x32_bf16 v[82:85], v[134:137], v[200:203], v[82:85]
	v_mfma_f32_16x16x32_bf16 v[74:77], v[142:145], v[200:203], v[74:77]
	s_setprio 0
	s_setprio 1
	v_mfma_f32_16x16x32_bf16 v[118:121], v[146:149], v[162:165], v[118:121]
	v_mfma_f32_16x16x32_bf16 v[110:113], v[154:157], v[162:165], v[110:113]
	v_mfma_f32_16x16x32_bf16 v[102:105], v[146:149], v[170:173], v[102:105]
	v_mfma_f32_16x16x32_bf16 v[94:97], v[154:157], v[170:173], v[94:97]
	v_mfma_f32_16x16x32_bf16 v[86:89], v[146:149], v[178:181], v[86:89]
	v_mfma_f32_16x16x32_bf16 v[78:81], v[154:157], v[178:181], v[78:81]
	v_mfma_f32_16x16x32_bf16 v[70:73], v[146:149], v[196:199], v[70:73]
	v_mfma_f32_16x16x32_bf16 v[66:69], v[154:157], v[196:199], v[66:69]
	v_mfma_f32_16x16x32_bf16 v[118:121], v[150:153], v[166:169], v[118:121]
	v_mfma_f32_16x16x32_bf16 v[110:113], v[158:161], v[166:169], v[110:113]
	v_mfma_f32_16x16x32_bf16 v[102:105], v[150:153], v[174:177], v[102:105]
	v_mfma_f32_16x16x32_bf16 v[94:97], v[158:161], v[174:177], v[94:97]
	v_mfma_f32_16x16x32_bf16 v[86:89], v[150:153], v[182:185], v[86:89]
	v_mfma_f32_16x16x32_bf16 v[78:81], v[158:161], v[182:185], v[78:81]
	v_mfma_f32_16x16x32_bf16 v[70:73], v[150:153], v[200:203], v[70:73]
	v_mfma_f32_16x16x32_bf16 v[66:69], v[158:161], v[200:203], v[66:69]
	s_setprio 0
	s_barrier
	s_add_i32 s94, s94, s37
	s_mov_b32 m0, s94
	ds_read_b128 v[162:165], v224 offset:16384
	ds_read_b128 v[166:169], v224 offset:17408
	ds_read_b128 v[170:173], v224 offset:18432
	ds_read_b128 v[174:177], v224 offset:19456
	ds_read_b128 v[178:181], v224 offset:20480
	ds_read_b128 v[182:185], v224 offset:21504
	ds_read_b128 v[196:199], v224 offset:22528
	ds_read_b128 v[200:203], v224 offset:23552
	global_load_lds_dwordx4 v16, s[28:29]
	s_add_i32 m0, s94, 0x2000
	s_add_u32 s94, s28, 0x80000
	s_addc_u32 s95, s29, 0
	s_add_i32 s96, s96, s37
	global_load_lds_dwordx4 v186, s[28:29]
	s_mov_b32 m0, s96
	v_lshl_add_u64 v[230:231], s[52:53], 0, v[188:189]
	global_load_lds_dwordx4 v16, s[94:95]
	s_add_i32 m0, s96, 0x2000
	s_nop 0
	global_load_lds_dwordx4 v186, s[94:95]
	v_lshl_add_u64 v[228:229], s[52:53], 0, v[190:191]
	s_mov_b32 m0, s59
	s_nop 0
	global_load_lds_dwordx4 v[228:229], off
	s_mov_b32 m0, s83
	s_nop 0
	global_load_lds_dwordx4 v[230:231], off
	s_waitcnt vmcnt(8)
	s_waitcnt lgkmcnt(0)
	s_barrier
	s_setprio 1
	s_waitcnt lgkmcnt(0)
	s_nop 0
	v_mfma_f32_16x16x32_bf16 v[62:65], v[130:133], v[162:165], v[62:65]
	v_mfma_f32_16x16x32_bf16 v[58:61], v[138:141], v[162:165], v[58:61]
	v_mfma_f32_16x16x32_bf16 v[50:53], v[130:133], v[170:173], v[50:53]
	v_mfma_f32_16x16x32_bf16 v[42:45], v[138:141], v[170:173], v[42:45]
	v_mfma_f32_16x16x32_bf16 v[34:37], v[130:133], v[178:181], v[34:37]
	v_mfma_f32_16x16x32_bf16 v[26:29], v[138:141], v[178:181], v[26:29]
	v_mfma_f32_16x16x32_bf16 v[18:21], v[130:133], v[196:199], v[18:21]
	v_mfma_f32_16x16x32_bf16 v[8:11], v[138:141], v[196:199], v[8:11]
	v_mfma_f32_16x16x32_bf16 v[62:65], v[134:137], v[166:169], v[62:65]
	v_mfma_f32_16x16x32_bf16 v[58:61], v[142:145], v[166:169], v[58:61]
	v_mfma_f32_16x16x32_bf16 v[50:53], v[134:137], v[174:177], v[50:53]
	v_mfma_f32_16x16x32_bf16 v[42:45], v[142:145], v[174:177], v[42:45]
	v_mfma_f32_16x16x32_bf16 v[34:37], v[134:137], v[182:185], v[34:37]
	v_mfma_f32_16x16x32_bf16 v[26:29], v[142:145], v[182:185], v[26:29]
	v_mfma_f32_16x16x32_bf16 v[18:21], v[134:137], v[200:203], v[18:21]
	v_mfma_f32_16x16x32_bf16 v[8:11], v[142:145], v[200:203], v[8:11]
	s_setprio 0
	s_setprio 1
	v_mfma_f32_16x16x32_bf16 v[54:57], v[146:149], v[162:165], v[54:57]
	v_mfma_f32_16x16x32_bf16 v[46:49], v[154:157], v[162:165], v[46:49]
	v_mfma_f32_16x16x32_bf16 v[38:41], v[146:149], v[170:173], v[38:41]
	v_mfma_f32_16x16x32_bf16 v[30:33], v[154:157], v[170:173], v[30:33]
	v_mfma_f32_16x16x32_bf16 v[22:25], v[146:149], v[178:181], v[22:25]
	v_mfma_f32_16x16x32_bf16 v[12:15], v[154:157], v[178:181], v[12:15]
	v_mfma_f32_16x16x32_bf16 v[4:7], v[146:149], v[196:199], v[4:7]
	v_mfma_f32_16x16x32_bf16 v[0:3], v[154:157], v[196:199], v[0:3]
	v_mfma_f32_16x16x32_bf16 v[54:57], v[150:153], v[166:169], v[54:57]
	v_mfma_f32_16x16x32_bf16 v[46:49], v[158:161], v[166:169], v[46:49]
	v_mfma_f32_16x16x32_bf16 v[38:41], v[150:153], v[174:177], v[38:41]
	v_mfma_f32_16x16x32_bf16 v[30:33], v[158:161], v[174:177], v[30:33]
	v_mfma_f32_16x16x32_bf16 v[22:25], v[150:153], v[182:185], v[22:25]
	v_mfma_f32_16x16x32_bf16 v[12:15], v[158:161], v[182:185], v[12:15]
	v_mfma_f32_16x16x32_bf16 v[4:7], v[150:153], v[200:203], v[4:7]
	v_mfma_f32_16x16x32_bf16 v[0:3], v[158:161], v[200:203], v[0:3]
	s_setprio 0
	s_barrier
	s_add_i32 s94, 0, 0x18000
	s_add_i32 s95, 0, 0x1c000
	v_add_u32_e32 v142, s94, v207
	v_add_u32_e32 v158, s95, v207
	ds_read_b128 v[130:133], v142
	ds_read_b128 v[134:137], v142 offset:1024
	ds_read_b128 v[138:141], v142 offset:2048
	ds_read_b128 v[142:145], v142 offset:3072
	ds_read_b128 v[146:149], v158
	ds_read_b128 v[150:153], v158 offset:1024
	ds_read_b128 v[154:157], v158 offset:2048
	ds_read_b128 v[158:161], v158 offset:3072
	s_add_u32 s52, s52, 0x80000
	s_addc_u32 s53, s53, 0
	s_mov_b32 m0, s84
	ds_read_b128 v[162:165], v224 offset:32768
	ds_read_b128 v[166:169], v224 offset:33792
	ds_read_b128 v[170:173], v224 offset:34816
	ds_read_b128 v[174:177], v224 offset:35840
	ds_read_b128 v[178:181], v224 offset:36864
	ds_read_b128 v[182:185], v224 offset:37888
	ds_read_b128 v[196:199], v224 offset:38912
	ds_read_b128 v[200:203], v224 offset:39936
	global_load_lds_dwordx4 v190, s[52:53]
	s_mov_b32 m0, s85
	s_nop 0
	global_load_lds_dwordx4 v188, s[52:53]
	s_waitcnt vmcnt(8)
	s_waitcnt lgkmcnt(0)
	s_barrier
	s_setprio 1
	s_waitcnt lgkmcnt(0)
	s_nop 0
	v_mfma_f32_16x16x32_bf16 v[126:129], v[130:133], v[162:165], v[126:129]
	v_mfma_f32_16x16x32_bf16 v[122:125], v[138:141], v[162:165], v[122:125]
	v_mfma_f32_16x16x32_bf16 v[114:117], v[130:133], v[170:173], v[114:117]
	v_mfma_f32_16x16x32_bf16 v[106:109], v[138:141], v[170:173], v[106:109]
	v_mfma_f32_16x16x32_bf16 v[98:101], v[130:133], v[178:181], v[98:101]
	v_mfma_f32_16x16x32_bf16 v[90:93], v[138:141], v[178:181], v[90:93]
	v_mfma_f32_16x16x32_bf16 v[82:85], v[130:133], v[196:199], v[82:85]
	v_mfma_f32_16x16x32_bf16 v[74:77], v[138:141], v[196:199], v[74:77]
	v_mfma_f32_16x16x32_bf16 v[126:129], v[134:137], v[166:169], v[126:129]
	v_mfma_f32_16x16x32_bf16 v[122:125], v[142:145], v[166:169], v[122:125]
	v_mfma_f32_16x16x32_bf16 v[114:117], v[134:137], v[174:177], v[114:117]
	v_mfma_f32_16x16x32_bf16 v[106:109], v[142:145], v[174:177], v[106:109]
	v_mfma_f32_16x16x32_bf16 v[98:101], v[134:137], v[182:185], v[98:101]
	v_mfma_f32_16x16x32_bf16 v[90:93], v[142:145], v[182:185], v[90:93]
	v_mfma_f32_16x16x32_bf16 v[82:85], v[134:137], v[200:203], v[82:85]
	v_mfma_f32_16x16x32_bf16 v[74:77], v[142:145], v[200:203], v[74:77]
	s_setprio 0
	s_setprio 1
	v_mfma_f32_16x16x32_bf16 v[118:121], v[146:149], v[162:165], v[118:121]
	v_mfma_f32_16x16x32_bf16 v[110:113], v[154:157], v[162:165], v[110:113]
	v_mfma_f32_16x16x32_bf16 v[102:105], v[146:149], v[170:173], v[102:105]
	v_mfma_f32_16x16x32_bf16 v[94:97], v[154:157], v[170:173], v[94:97]
	v_mfma_f32_16x16x32_bf16 v[86:89], v[146:149], v[178:181], v[86:89]
	v_mfma_f32_16x16x32_bf16 v[78:81], v[154:157], v[178:181], v[78:81]
	v_mfma_f32_16x16x32_bf16 v[70:73], v[146:149], v[196:199], v[70:73]
	v_mfma_f32_16x16x32_bf16 v[66:69], v[154:157], v[196:199], v[66:69]
	v_mfma_f32_16x16x32_bf16 v[118:121], v[150:153], v[166:169], v[118:121]
	v_mfma_f32_16x16x32_bf16 v[110:113], v[158:161], v[166:169], v[110:113]
	v_mfma_f32_16x16x32_bf16 v[102:105], v[150:153], v[174:177], v[102:105]
	v_mfma_f32_16x16x32_bf16 v[94:97], v[158:161], v[174:177], v[94:97]
	v_mfma_f32_16x16x32_bf16 v[86:89], v[150:153], v[182:185], v[86:89]
	v_mfma_f32_16x16x32_bf16 v[78:81], v[158:161], v[182:185], v[78:81]
	v_mfma_f32_16x16x32_bf16 v[70:73], v[150:153], v[200:203], v[70:73]
	v_mfma_f32_16x16x32_bf16 v[66:69], v[158:161], v[200:203], v[66:69]
	s_setprio 0
	s_barrier
	s_add_i32 s52, s94, s37
	s_add_u32 s28, s28, 0x80
	s_addc_u32 s29, s29, 0
	s_mov_b32 m0, s52
	ds_read_b128 v[162:165], v224 offset:49152
	ds_read_b128 v[166:169], v224 offset:50176
	ds_read_b128 v[170:173], v224 offset:51200
	ds_read_b128 v[174:177], v224 offset:52224
	ds_read_b128 v[178:181], v224 offset:53248
	ds_read_b128 v[182:185], v224 offset:54272
	ds_read_b128 v[196:199], v224 offset:55296
	ds_read_b128 v[200:203], v224 offset:56320
	global_load_lds_dwordx4 v16, s[28:29]
	s_add_i32 m0, s52, 0x2000
	s_add_i32 s52, s95, s37
	global_load_lds_dwordx4 v186, s[28:29]
	s_add_u32 s28, s28, 0x80000
	s_addc_u32 s29, s29, 0
	s_mov_b32 m0, s52
	s_nop 0
	global_load_lds_dwordx4 v16, s[28:29]
	s_add_i32 m0, s52, 0x2000
	s_nop 0
	global_load_lds_dwordx4 v186, s[28:29]
	v_lshl_add_u64 v[204:205], v[228:229], 0, s[34:35]
	s_mov_b32 m0, s88
	s_nop 0
	global_load_lds_dwordx4 v[204:205], off
	v_lshl_add_u64 v[204:205], v[230:231], 0, s[34:35]
	s_mov_b32 m0, s89
	s_nop 0
	global_load_lds_dwordx4 v[204:205], off
	s_waitcnt vmcnt(8)
	s_waitcnt lgkmcnt(0)
	s_barrier
	s_setprio 1
	s_waitcnt lgkmcnt(0)
	s_nop 0
	v_mfma_f32_16x16x32_bf16 v[62:65], v[130:133], v[162:165], v[62:65]
	v_mfma_f32_16x16x32_bf16 v[58:61], v[138:141], v[162:165], v[58:61]
	v_mfma_f32_16x16x32_bf16 v[50:53], v[130:133], v[170:173], v[50:53]
	v_mfma_f32_16x16x32_bf16 v[42:45], v[138:141], v[170:173], v[42:45]
	v_mfma_f32_16x16x32_bf16 v[34:37], v[130:133], v[178:181], v[34:37]
	v_mfma_f32_16x16x32_bf16 v[26:29], v[138:141], v[178:181], v[26:29]
	v_mfma_f32_16x16x32_bf16 v[18:21], v[130:133], v[196:199], v[18:21]
	v_mfma_f32_16x16x32_bf16 v[8:11], v[138:141], v[196:199], v[8:11]
	v_mfma_f32_16x16x32_bf16 v[62:65], v[134:137], v[166:169], v[62:65]
	v_mfma_f32_16x16x32_bf16 v[58:61], v[142:145], v[166:169], v[58:61]
	v_mfma_f32_16x16x32_bf16 v[50:53], v[134:137], v[174:177], v[50:53]
	v_mfma_f32_16x16x32_bf16 v[42:45], v[142:145], v[174:177], v[42:45]
	v_mfma_f32_16x16x32_bf16 v[34:37], v[134:137], v[182:185], v[34:37]
	v_mfma_f32_16x16x32_bf16 v[26:29], v[142:145], v[182:185], v[26:29]
	v_mfma_f32_16x16x32_bf16 v[18:21], v[134:137], v[200:203], v[18:21]
	v_mfma_f32_16x16x32_bf16 v[8:11], v[142:145], v[200:203], v[8:11]
	s_setprio 0
	s_setprio 1
	v_mfma_f32_16x16x32_bf16 v[54:57], v[146:149], v[162:165], v[54:57]
	v_mfma_f32_16x16x32_bf16 v[46:49], v[154:157], v[162:165], v[46:49]
	v_mfma_f32_16x16x32_bf16 v[38:41], v[146:149], v[170:173], v[38:41]
	v_mfma_f32_16x16x32_bf16 v[30:33], v[154:157], v[170:173], v[30:33]
	v_mfma_f32_16x16x32_bf16 v[22:25], v[146:149], v[178:181], v[22:25]
	v_mfma_f32_16x16x32_bf16 v[12:15], v[154:157], v[178:181], v[12:15]
	v_mfma_f32_16x16x32_bf16 v[4:7], v[146:149], v[196:199], v[4:7]
	v_mfma_f32_16x16x32_bf16 v[0:3], v[154:157], v[196:199], v[0:3]
	v_mfma_f32_16x16x32_bf16 v[54:57], v[150:153], v[166:169], v[54:57]
	v_mfma_f32_16x16x32_bf16 v[46:49], v[158:161], v[166:169], v[46:49]
	v_mfma_f32_16x16x32_bf16 v[38:41], v[150:153], v[174:177], v[38:41]
	v_mfma_f32_16x16x32_bf16 v[30:33], v[158:161], v[174:177], v[30:33]
	v_mfma_f32_16x16x32_bf16 v[22:25], v[150:153], v[182:185], v[22:25]
	v_mfma_f32_16x16x32_bf16 v[12:15], v[158:161], v[182:185], v[12:15]
	v_mfma_f32_16x16x32_bf16 v[4:7], v[150:153], v[200:203], v[4:7]
	v_mfma_f32_16x16x32_bf16 v[0:3], v[158:161], v[200:203], v[0:3]
	s_setprio 0
	s_barrier
	s_add_i32 s93, s93, 2
	s_add_u32 s50, s50, 0x100
	s_addc_u32 s51, s51, 0
	s_add_u32 vcc_hi, vcc_hi, 0x100
	s_addc_u32 s92, s92, 0
	s_cmp_gt_u32 s93, 29
	s_cbranch_scc0 .LBB0_787

.LBB0_919:
	s_ashr_i32 s27, s26, 31
	s_lshl_b64 s[28:29], s[26:27], 20
	s_add_u32 s40, s68, s28
	s_addc_u32 s41, s69, s29
	s_and_b64 s[28:29], s[38:39], exec
	s_cselect_b32 s27, s41, s47
	s_cselect_b32 s86, s40, s46
	s_ashr_i32 s23, s22, 31
	s_lshl_b64 s[28:29], s[22:23], 20
	v_readlane_b32 s23, v255, 16
	s_add_u32 s42, s23, s28
	v_readlane_b32 s23, v255, 17
	s_addc_u32 s43, s23, s29
	s_and_b64 s[28:29], s[38:39], exec
	s_cselect_b32 s23, s43, s49
	s_cselect_b32 s87, s42, s48
	s_add_u32 s46, s46, 0x80080
	s_addc_u32 s47, s47, 0
	s_add_u32 s88, s48, 0x100
	s_addc_u32 s89, s49, 0
	s_mov_b32 s90, -2
	s_add_u32 s28, s46, 0xfff80080
	s_addc_u32 s29, s47, -1
	s_add_i32 s91, 0, 0x10000
	s_cmp_eq_u32 s90, 28
	s_cselect_b32 s49, s27, s29
	s_cselect_b32 s48, s86, s28
	s_cselect_b32 s29, s23, s89
	s_cselect_b32 s28, s87, s88
	s_add_i32 s94, 0, 0x14000
	v_add_u32_e32 v156, s91, v141
	v_add_u32_e32 v172, s94, v141
	ds_read_b128 v[144:147], v156
	ds_read_b128 v[148:151], v156 offset:1024
	ds_read_b128 v[152:155], v156 offset:2048
	ds_read_b128 v[156:159], v156 offset:3072
	ds_read_b128 v[160:163], v172
	ds_read_b128 v[164:167], v172 offset:1024
	ds_read_b128 v[168:171], v172 offset:2048
	ds_read_b128 v[172:175], v172 offset:3072
	s_add_i32 m0, s45, 0xc000
	ds_read_b128 v[176:179], v143
	ds_read_b128 v[180:183], v143 offset:1024
	ds_read_b128 v[184:187], v143 offset:2048
	ds_read_b128 v[188:191], v143 offset:3072
	ds_read_b128 v[192:195], v143 offset:4096
	ds_read_b128 v[196:199], v143 offset:5120
	ds_read_b128 v[200:203], v143 offset:6144
	ds_read_b128 v[204:207], v143 offset:7168
	global_load_lds_dwordx4 v136, s[46:47]
	s_add_i32 m0, s45, 0xe000
	s_nop 0
	global_load_lds_dwordx4 v138, s[46:47]
	s_waitcnt vmcnt(8)
	s_waitcnt lgkmcnt(0)
	s_barrier
	s_setprio 1
	s_waitcnt lgkmcnt(0)
	v_mfma_f32_16x16x32_bf16 v[126:129], v[144:147], v[176:179], 0
	v_mfma_f32_16x16x32_bf16 v[118:121], v[152:155], v[176:179], 0
	v_mfma_f32_16x16x32_bf16 v[110:113], v[144:147], v[184:187], 0
	v_mfma_f32_16x16x32_bf16 v[102:105], v[152:155], v[184:187], 0
	v_mfma_f32_16x16x32_bf16 v[94:97], v[144:147], v[192:195], 0
	v_mfma_f32_16x16x32_bf16 v[86:89], v[152:155], v[192:195], 0
	v_mfma_f32_16x16x32_bf16 v[78:81], v[144:147], v[200:203], 0
	v_mfma_f32_16x16x32_bf16 v[70:73], v[152:155], v[200:203], 0
	v_mfma_f32_16x16x32_bf16 v[126:129], v[148:151], v[180:183], v[126:129]
	v_mfma_f32_16x16x32_bf16 v[118:121], v[156:159], v[180:183], v[118:121]
	v_mfma_f32_16x16x32_bf16 v[110:113], v[148:151], v[188:191], v[110:113]
	v_mfma_f32_16x16x32_bf16 v[102:105], v[156:159], v[188:191], v[102:105]
	v_mfma_f32_16x16x32_bf16 v[94:97], v[148:151], v[196:199], v[94:97]
	v_mfma_f32_16x16x32_bf16 v[86:89], v[156:159], v[196:199], v[86:89]
	v_mfma_f32_16x16x32_bf16 v[78:81], v[148:151], v[204:207], v[78:81]
	v_mfma_f32_16x16x32_bf16 v[70:73], v[156:159], v[204:207], v[70:73]
	s_setprio 0
	s_setprio 1
	v_mfma_f32_16x16x32_bf16 v[122:125], v[160:163], v[176:179], 0
	v_mfma_f32_16x16x32_bf16 v[114:117], v[168:171], v[176:179], 0
	v_mfma_f32_16x16x32_bf16 v[106:109], v[160:163], v[184:187], 0
	v_mfma_f32_16x16x32_bf16 v[98:101], v[168:171], v[184:187], 0
	v_mfma_f32_16x16x32_bf16 v[90:93], v[160:163], v[192:195], 0
	v_mfma_f32_16x16x32_bf16 v[82:85], v[168:171], v[192:195], 0
	v_mfma_f32_16x16x32_bf16 v[74:77], v[160:163], v[200:203], 0
	v_mfma_f32_16x16x32_bf16 v[66:69], v[168:171], v[200:203], 0
	v_mfma_f32_16x16x32_bf16 v[122:125], v[164:167], v[180:183], v[122:125]
	v_mfma_f32_16x16x32_bf16 v[114:117], v[172:175], v[180:183], v[114:117]
	v_mfma_f32_16x16x32_bf16 v[106:109], v[164:167], v[188:191], v[106:109]
	v_mfma_f32_16x16x32_bf16 v[98:101], v[172:175], v[188:191], v[98:101]
	v_mfma_f32_16x16x32_bf16 v[90:93], v[164:167], v[196:199], v[90:93]
	v_mfma_f32_16x16x32_bf16 v[82:85], v[172:175], v[196:199], v[82:85]
	v_mfma_f32_16x16x32_bf16 v[74:77], v[164:167], v[204:207], v[74:77]
	v_mfma_f32_16x16x32_bf16 v[66:69], v[172:175], v[204:207], v[66:69]
	s_setprio 0
	s_barrier
	s_add_i32 s91, s91, s37
	s_mov_b32 m0, s91
	ds_read_b128 v[176:179], v143 offset:16384
	ds_read_b128 v[180:183], v143 offset:17408
	ds_read_b128 v[184:187], v143 offset:18432
	ds_read_b128 v[188:191], v143 offset:19456
	ds_read_b128 v[192:195], v143 offset:20480
	ds_read_b128 v[196:199], v143 offset:21504
	ds_read_b128 v[200:203], v143 offset:22528
	ds_read_b128 v[204:207], v143 offset:23552
	global_load_lds_dwordx4 v16, s[28:29]
	s_add_i32 m0, s91, 0x2000
	s_add_u32 s92, s28, 0x80000
	s_addc_u32 s93, s29, 0
	s_add_i32 s91, s94, s37
	global_load_lds_dwordx4 v130, s[28:29]
	s_mov_b32 m0, s91
	v_lshl_add_u64 v[228:229], s[48:49], 0, v[132:133]
	global_load_lds_dwordx4 v16, s[92:93]
	s_add_i32 m0, s91, 0x2000
	s_nop 0
	global_load_lds_dwordx4 v130, s[92:93]
	v_lshl_add_u64 v[226:227], s[48:49], 0, v[134:135]
	s_mov_b32 m0, s45
	s_nop 0
	global_load_lds_dwordx4 v[226:227], off
	s_mov_b32 m0, s53
	s_nop 0
	global_load_lds_dwordx4 v[228:229], off
	s_waitcnt vmcnt(8)
	s_waitcnt lgkmcnt(0)
	s_barrier
	s_setprio 1
	s_waitcnt lgkmcnt(0)
	s_nop 0
	v_mfma_f32_16x16x32_bf16 v[62:65], v[144:147], v[176:179], 0
	v_mfma_f32_16x16x32_bf16 v[54:57], v[152:155], v[176:179], 0
	v_mfma_f32_16x16x32_bf16 v[46:49], v[144:147], v[184:187], 0
	v_mfma_f32_16x16x32_bf16 v[38:41], v[152:155], v[184:187], 0
	v_mfma_f32_16x16x32_bf16 v[30:33], v[144:147], v[192:195], 0
	v_mfma_f32_16x16x32_bf16 v[22:25], v[152:155], v[192:195], 0
	v_mfma_f32_16x16x32_bf16 v[12:15], v[144:147], v[200:203], 0
	v_mfma_f32_16x16x32_bf16 v[4:7], v[152:155], v[200:203], 0
	v_mfma_f32_16x16x32_bf16 v[62:65], v[148:151], v[180:183], v[62:65]
	v_mfma_f32_16x16x32_bf16 v[54:57], v[156:159], v[180:183], v[54:57]
	v_mfma_f32_16x16x32_bf16 v[46:49], v[148:151], v[188:191], v[46:49]
	v_mfma_f32_16x16x32_bf16 v[38:41], v[156:159], v[188:191], v[38:41]
	v_mfma_f32_16x16x32_bf16 v[30:33], v[148:151], v[196:199], v[30:33]
	v_mfma_f32_16x16x32_bf16 v[22:25], v[156:159], v[196:199], v[22:25]
	v_mfma_f32_16x16x32_bf16 v[12:15], v[148:151], v[204:207], v[12:15]
	v_mfma_f32_16x16x32_bf16 v[4:7], v[156:159], v[204:207], v[4:7]
	s_setprio 0
	s_setprio 1
	v_mfma_f32_16x16x32_bf16 v[58:61], v[160:163], v[176:179], 0
	v_mfma_f32_16x16x32_bf16 v[50:53], v[168:171], v[176:179], 0
	v_mfma_f32_16x16x32_bf16 v[42:45], v[160:163], v[184:187], 0
	v_mfma_f32_16x16x32_bf16 v[34:37], v[168:171], v[184:187], 0
	v_mfma_f32_16x16x32_bf16 v[26:29], v[160:163], v[192:195], 0
	v_mfma_f32_16x16x32_bf16 v[18:21], v[168:171], v[192:195], 0
	v_mfma_f32_16x16x32_bf16 v[8:11], v[160:163], v[200:203], 0
	v_mfma_f32_16x16x32_bf16 v[0:3], v[168:171], v[200:203], 0
	v_mfma_f32_16x16x32_bf16 v[58:61], v[164:167], v[180:183], v[58:61]
	v_mfma_f32_16x16x32_bf16 v[50:53], v[172:175], v[180:183], v[50:53]
	v_mfma_f32_16x16x32_bf16 v[42:45], v[164:167], v[188:191], v[42:45]
	v_mfma_f32_16x16x32_bf16 v[34:37], v[172:175], v[188:191], v[34:37]
	v_mfma_f32_16x16x32_bf16 v[26:29], v[164:167], v[196:199], v[26:29]
	v_mfma_f32_16x16x32_bf16 v[18:21], v[172:175], v[196:199], v[18:21]
	v_mfma_f32_16x16x32_bf16 v[8:11], v[164:167], v[204:207], v[8:11]
	v_mfma_f32_16x16x32_bf16 v[0:3], v[172:175], v[204:207], v[0:3]
	s_setprio 0
	s_barrier
	s_add_i32 s91, 0, 0x18000
	s_add_i32 s92, 0, 0x1c000
	v_add_u32_e32 v156, s91, v141
	v_add_u32_e32 v172, s92, v141
	ds_read_b128 v[144:147], v156
	ds_read_b128 v[148:151], v156 offset:1024
	ds_read_b128 v[152:155], v156 offset:2048
	ds_read_b128 v[156:159], v156 offset:3072
	ds_read_b128 v[160:163], v172
	ds_read_b128 v[164:167], v172 offset:1024
	ds_read_b128 v[168:171], v172 offset:2048
	ds_read_b128 v[172:175], v172 offset:3072
	s_add_u32 s48, s48, 0x80000
	s_addc_u32 s49, s49, 0
	s_mov_b32 m0, s57
	ds_read_b128 v[176:179], v143 offset:32768
	ds_read_b128 v[180:183], v143 offset:33792
	ds_read_b128 v[184:187], v143 offset:34816
	ds_read_b128 v[188:191], v143 offset:35840
	ds_read_b128 v[192:195], v143 offset:36864
	ds_read_b128 v[196:199], v143 offset:37888
	ds_read_b128 v[200:203], v143 offset:38912
	ds_read_b128 v[204:207], v143 offset:39936
	global_load_lds_dwordx4 v134, s[48:49]
	s_mov_b32 m0, s58
	s_nop 0
	global_load_lds_dwordx4 v132, s[48:49]
	s_waitcnt vmcnt(8)
	s_waitcnt lgkmcnt(0)
	s_barrier
	s_setprio 1
	s_waitcnt lgkmcnt(0)
	s_nop 0
	v_mfma_f32_16x16x32_bf16 v[126:129], v[144:147], v[176:179], v[126:129]
	v_mfma_f32_16x16x32_bf16 v[118:121], v[152:155], v[176:179], v[118:121]
	v_mfma_f32_16x16x32_bf16 v[110:113], v[144:147], v[184:187], v[110:113]
	v_mfma_f32_16x16x32_bf16 v[102:105], v[152:155], v[184:187], v[102:105]
	v_mfma_f32_16x16x32_bf16 v[94:97], v[144:147], v[192:195], v[94:97]
	v_mfma_f32_16x16x32_bf16 v[86:89], v[152:155], v[192:195], v[86:89]
	v_mfma_f32_16x16x32_bf16 v[78:81], v[144:147], v[200:203], v[78:81]
	v_mfma_f32_16x16x32_bf16 v[70:73], v[152:155], v[200:203], v[70:73]
	v_mfma_f32_16x16x32_bf16 v[126:129], v[148:151], v[180:183], v[126:129]
	v_mfma_f32_16x16x32_bf16 v[118:121], v[156:159], v[180:183], v[118:121]
	v_mfma_f32_16x16x32_bf16 v[110:113], v[148:151], v[188:191], v[110:113]
	v_mfma_f32_16x16x32_bf16 v[102:105], v[156:159], v[188:191], v[102:105]
	v_mfma_f32_16x16x32_bf16 v[94:97], v[148:151], v[196:199], v[94:97]
	v_mfma_f32_16x16x32_bf16 v[86:89], v[156:159], v[196:199], v[86:89]
	v_mfma_f32_16x16x32_bf16 v[78:81], v[148:151], v[204:207], v[78:81]
	v_mfma_f32_16x16x32_bf16 v[70:73], v[156:159], v[204:207], v[70:73]
	s_setprio 0
	s_setprio 1
	v_mfma_f32_16x16x32_bf16 v[122:125], v[160:163], v[176:179], v[122:125]
	v_mfma_f32_16x16x32_bf16 v[114:117], v[168:171], v[176:179], v[114:117]
	v_mfma_f32_16x16x32_bf16 v[106:109], v[160:163], v[184:187], v[106:109]
	v_mfma_f32_16x16x32_bf16 v[98:101], v[168:171], v[184:187], v[98:101]
	v_mfma_f32_16x16x32_bf16 v[90:93], v[160:163], v[192:195], v[90:93]
	v_mfma_f32_16x16x32_bf16 v[82:85], v[168:171], v[192:195], v[82:85]
	v_mfma_f32_16x16x32_bf16 v[74:77], v[160:163], v[200:203], v[74:77]
	v_mfma_f32_16x16x32_bf16 v[66:69], v[168:171], v[200:203], v[66:69]
	v_mfma_f32_16x16x32_bf16 v[122:125], v[164:167], v[180:183], v[122:125]
	v_mfma_f32_16x16x32_bf16 v[114:117], v[172:175], v[180:183], v[114:117]
	v_mfma_f32_16x16x32_bf16 v[106:109], v[164:167], v[188:191], v[106:109]
	v_mfma_f32_16x16x32_bf16 v[98:101], v[172:175], v[188:191], v[98:101]
	v_mfma_f32_16x16x32_bf16 v[90:93], v[164:167], v[196:199], v[90:93]
	v_mfma_f32_16x16x32_bf16 v[82:85], v[172:175], v[196:199], v[82:85]
	v_mfma_f32_16x16x32_bf16 v[74:77], v[164:167], v[204:207], v[74:77]
	v_mfma_f32_16x16x32_bf16 v[66:69], v[172:175], v[204:207], v[66:69]
	s_setprio 0
	s_barrier
	s_add_i32 s48, s91, s37
	s_add_u32 s28, s28, 0x80
	s_addc_u32 s29, s29, 0
	s_mov_b32 m0, s48
	ds_read_b128 v[176:179], v143 offset:49152
	ds_read_b128 v[180:183], v143 offset:50176
	ds_read_b128 v[184:187], v143 offset:51200
	ds_read_b128 v[188:191], v143 offset:52224
	ds_read_b128 v[192:195], v143 offset:53248
	ds_read_b128 v[196:199], v143 offset:54272
	ds_read_b128 v[200:203], v143 offset:55296
	ds_read_b128 v[204:207], v143 offset:56320
	global_load_lds_dwordx4 v16, s[28:29]
	s_add_i32 m0, s48, 0x2000
	s_add_i32 s48, s92, s37
	global_load_lds_dwordx4 v130, s[28:29]
	s_add_u32 s28, s28, 0x80000
	s_addc_u32 s29, s29, 0
	s_mov_b32 m0, s48
	s_nop 0
	global_load_lds_dwordx4 v16, s[28:29]
	s_add_i32 m0, s48, 0x2000
	s_nop 0
	global_load_lds_dwordx4 v130, s[28:29]
	v_lshl_add_u64 v[216:217], v[226:227], 0, s[34:35]
	s_mov_b32 m0, s59
	s_nop 0
	global_load_lds_dwordx4 v[216:217], off
	v_lshl_add_u64 v[216:217], v[228:229], 0, s[34:35]
	s_mov_b32 m0, s83
	s_nop 0
	global_load_lds_dwordx4 v[216:217], off
	s_waitcnt vmcnt(8)
	s_waitcnt lgkmcnt(0)
	s_barrier
	s_setprio 1
	s_waitcnt lgkmcnt(0)
	s_nop 0
	v_mfma_f32_16x16x32_bf16 v[62:65], v[144:147], v[176:179], v[62:65]
	v_mfma_f32_16x16x32_bf16 v[54:57], v[152:155], v[176:179], v[54:57]
	v_mfma_f32_16x16x32_bf16 v[46:49], v[144:147], v[184:187], v[46:49]
	v_mfma_f32_16x16x32_bf16 v[38:41], v[152:155], v[184:187], v[38:41]
	v_mfma_f32_16x16x32_bf16 v[30:33], v[144:147], v[192:195], v[30:33]
	v_mfma_f32_16x16x32_bf16 v[22:25], v[152:155], v[192:195], v[22:25]
	v_mfma_f32_16x16x32_bf16 v[12:15], v[144:147], v[200:203], v[12:15]
	v_mfma_f32_16x16x32_bf16 v[4:7], v[152:155], v[200:203], v[4:7]
	v_mfma_f32_16x16x32_bf16 v[62:65], v[148:151], v[180:183], v[62:65]
	v_mfma_f32_16x16x32_bf16 v[54:57], v[156:159], v[180:183], v[54:57]
	v_mfma_f32_16x16x32_bf16 v[46:49], v[148:151], v[188:191], v[46:49]
	v_mfma_f32_16x16x32_bf16 v[38:41], v[156:159], v[188:191], v[38:41]
	v_mfma_f32_16x16x32_bf16 v[30:33], v[148:151], v[196:199], v[30:33]
	v_mfma_f32_16x16x32_bf16 v[22:25], v[156:159], v[196:199], v[22:25]
	v_mfma_f32_16x16x32_bf16 v[12:15], v[148:151], v[204:207], v[12:15]
	v_mfma_f32_16x16x32_bf16 v[4:7], v[156:159], v[204:207], v[4:7]
	s_setprio 0
	s_setprio 1
	v_mfma_f32_16x16x32_bf16 v[58:61], v[160:163], v[176:179], v[58:61]
	v_mfma_f32_16x16x32_bf16 v[50:53], v[168:171], v[176:179], v[50:53]
	v_mfma_f32_16x16x32_bf16 v[42:45], v[160:163], v[184:187], v[42:45]
	v_mfma_f32_16x16x32_bf16 v[34:37], v[168:171], v[184:187], v[34:37]
	v_mfma_f32_16x16x32_bf16 v[26:29], v[160:163], v[192:195], v[26:29]
	v_mfma_f32_16x16x32_bf16 v[18:21], v[168:171], v[192:195], v[18:21]
	v_mfma_f32_16x16x32_bf16 v[8:11], v[160:163], v[200:203], v[8:11]
	v_mfma_f32_16x16x32_bf16 v[0:3], v[168:171], v[200:203], v[0:3]
	v_mfma_f32_16x16x32_bf16 v[58:61], v[164:167], v[180:183], v[58:61]
	v_mfma_f32_16x16x32_bf16 v[50:53], v[172:175], v[180:183], v[50:53]
	v_mfma_f32_16x16x32_bf16 v[42:45], v[164:167], v[188:191], v[42:45]
	v_mfma_f32_16x16x32_bf16 v[34:37], v[172:175], v[188:191], v[34:37]
	v_mfma_f32_16x16x32_bf16 v[26:29], v[164:167], v[196:199], v[26:29]
	v_mfma_f32_16x16x32_bf16 v[18:21], v[172:175], v[196:199], v[18:21]
	v_mfma_f32_16x16x32_bf16 v[8:11], v[164:167], v[204:207], v[8:11]
	v_mfma_f32_16x16x32_bf16 v[0:3], v[172:175], v[204:207], v[0:3]
	s_setprio 0
	s_barrier
	s_add_i32 s90, s90, 2
	s_add_u32 s46, s46, 0x100
	s_addc_u32 s47, s47, 0
	s_add_u32 s88, s88, 0x100
	s_addc_u32 s89, s89, 0
	s_cmp_gt_u32 s90, 29
	s_cbranch_scc1 .Lpz_I_exit
.LBB0_920:
	s_add_u32 s28, s46, 0xfff80080
	s_addc_u32 s29, s47, -1
	s_add_i32 s91, 0, 0x10000
	s_cmp_eq_u32 s90, 28
	s_cselect_b32 s49, s27, s29
	s_cselect_b32 s48, s86, s28
	s_cselect_b32 s29, s23, s89
	s_cselect_b32 s28, s87, s88
	s_add_i32 s94, 0, 0x14000
	v_add_u32_e32 v156, s91, v141
	v_add_u32_e32 v172, s94, v141
	ds_read_b128 v[144:147], v156
	ds_read_b128 v[148:151], v156 offset:1024
	ds_read_b128 v[152:155], v156 offset:2048
	ds_read_b128 v[156:159], v156 offset:3072
	ds_read_b128 v[160:163], v172
	ds_read_b128 v[164:167], v172 offset:1024
	ds_read_b128 v[168:171], v172 offset:2048
	ds_read_b128 v[172:175], v172 offset:3072
	s_add_i32 m0, s45, 0xc000
	ds_read_b128 v[176:179], v143
	ds_read_b128 v[180:183], v143 offset:1024
	ds_read_b128 v[184:187], v143 offset:2048
	ds_read_b128 v[188:191], v143 offset:3072
	ds_read_b128 v[192:195], v143 offset:4096
	ds_read_b128 v[196:199], v143 offset:5120
	ds_read_b128 v[200:203], v143 offset:6144
	ds_read_b128 v[204:207], v143 offset:7168
	global_load_lds_dwordx4 v136, s[46:47]
	s_add_i32 m0, s45, 0xe000
	s_nop 0
	global_load_lds_dwordx4 v138, s[46:47]
	s_waitcnt vmcnt(8)
	s_waitcnt lgkmcnt(0)
	s_barrier
	s_setprio 1
	s_waitcnt lgkmcnt(0)
	s_nop 0
	v_mfma_f32_16x16x32_bf16 v[126:129], v[144:147], v[176:179], v[126:129]
	v_mfma_f32_16x16x32_bf16 v[118:121], v[152:155], v[176:179], v[118:121]
	v_mfma_f32_16x16x32_bf16 v[110:113], v[144:147], v[184:187], v[110:113]
	v_mfma_f32_16x16x32_bf16 v[102:105], v[152:155], v[184:187], v[102:105]
	v_mfma_f32_16x16x32_bf16 v[94:97], v[144:147], v[192:195], v[94:97]
	v_mfma_f32_16x16x32_bf16 v[86:89], v[152:155], v[192:195], v[86:89]
	v_mfma_f32_16x16x32_bf16 v[78:81], v[144:147], v[200:203], v[78:81]
	v_mfma_f32_16x16x32_bf16 v[70:73], v[152:155], v[200:203], v[70:73]
	v_mfma_f32_16x16x32_bf16 v[126:129], v[148:151], v[180:183], v[126:129]
	v_mfma_f32_16x16x32_bf16 v[118:121], v[156:159], v[180:183], v[118:121]
	v_mfma_f32_16x16x32_bf16 v[110:113], v[148:151], v[188:191], v[110:113]
	v_mfma_f32_16x16x32_bf16 v[102:105], v[156:159], v[188:191], v[102:105]
	v_mfma_f32_16x16x32_bf16 v[94:97], v[148:151], v[196:199], v[94:97]
	v_mfma_f32_16x16x32_bf16 v[86:89], v[156:159], v[196:199], v[86:89]
	v_mfma_f32_16x16x32_bf16 v[78:81], v[148:151], v[204:207], v[78:81]
	v_mfma_f32_16x16x32_bf16 v[70:73], v[156:159], v[204:207], v[70:73]
	s_setprio 0
	s_setprio 1
	v_mfma_f32_16x16x32_bf16 v[122:125], v[160:163], v[176:179], v[122:125]
	v_mfma_f32_16x16x32_bf16 v[114:117], v[168:171], v[176:179], v[114:117]
	v_mfma_f32_16x16x32_bf16 v[106:109], v[160:163], v[184:187], v[106:109]
	v_mfma_f32_16x16x32_bf16 v[98:101], v[168:171], v[184:187], v[98:101]
	v_mfma_f32_16x16x32_bf16 v[90:93], v[160:163], v[192:195], v[90:93]
	v_mfma_f32_16x16x32_bf16 v[82:85], v[168:171], v[192:195], v[82:85]
	v_mfma_f32_16x16x32_bf16 v[74:77], v[160:163], v[200:203], v[74:77]
	v_mfma_f32_16x16x32_bf16 v[66:69], v[168:171], v[200:203], v[66:69]
	v_mfma_f32_16x16x32_bf16 v[122:125], v[164:167], v[180:183], v[122:125]
	v_mfma_f32_16x16x32_bf16 v[114:117], v[172:175], v[180:183], v[114:117]
	v_mfma_f32_16x16x32_bf16 v[106:109], v[164:167], v[188:191], v[106:109]
	v_mfma_f32_16x16x32_bf16 v[98:101], v[172:175], v[188:191], v[98:101]
	v_mfma_f32_16x16x32_bf16 v[90:93], v[164:167], v[196:199], v[90:93]
	v_mfma_f32_16x16x32_bf16 v[82:85], v[172:175], v[196:199], v[82:85]
	v_mfma_f32_16x16x32_bf16 v[74:77], v[164:167], v[204:207], v[74:77]
	v_mfma_f32_16x16x32_bf16 v[66:69], v[172:175], v[204:207], v[66:69]
	s_setprio 0
	s_barrier
	s_add_i32 s91, s91, s37
	s_mov_b32 m0, s91
	ds_read_b128 v[176:179], v143 offset:16384
	ds_read_b128 v[180:183], v143 offset:17408
	ds_read_b128 v[184:187], v143 offset:18432
	ds_read_b128 v[188:191], v143 offset:19456
	ds_read_b128 v[192:195], v143 offset:20480
	ds_read_b128 v[196:199], v143 offset:21504
	ds_read_b128 v[200:203], v143 offset:22528
	ds_read_b128 v[204:207], v143 offset:23552
	global_load_lds_dwordx4 v16, s[28:29]
	s_add_i32 m0, s91, 0x2000
	s_add_u32 s92, s28, 0x80000
	s_addc_u32 s93, s29, 0
	s_add_i32 s91, s94, s37
	global_load_lds_dwordx4 v130, s[28:29]
	s_mov_b32 m0, s91
	v_lshl_add_u64 v[228:229], s[48:49], 0, v[132:133]
	global_load_lds_dwordx4 v16, s[92:93]
	s_add_i32 m0, s91, 0x2000
	s_nop 0
	global_load_lds_dwordx4 v130, s[92:93]
	v_lshl_add_u64 v[226:227], s[48:49], 0, v[134:135]
	s_mov_b32 m0, s45
	s_nop 0
	global_load_lds_dwordx4 v[226:227], off
	s_mov_b32 m0, s53
	s_nop 0
	global_load_lds_dwordx4 v[228:229], off
	s_waitcnt vmcnt(8)
	s_waitcnt lgkmcnt(0)
	s_barrier
	s_setprio 1
	s_waitcnt lgkmcnt(0)
	s_nop 0
	v_mfma_f32_16x16x32_bf16 v[62:65], v[144:147], v[176:179], v[62:65]
	v_mfma_f32_16x16x32_bf16 v[54:57], v[152:155], v[176:179], v[54:57]
	v_mfma_f32_16x16x32_bf16 v[46:49], v[144:147], v[184:187], v[46:49]
	v_mfma_f32_16x16x32_bf16 v[38:41], v[152:155], v[184:187], v[38:41]
	v_mfma_f32_16x16x32_bf16 v[30:33], v[144:147], v[192:195], v[30:33]
	v_mfma_f32_16x16x32_bf16 v[22:25], v[152:155], v[192:195], v[22:25]
	v_mfma_f32_16x16x32_bf16 v[12:15], v[144:147], v[200:203], v[12:15]
	v_mfma_f32_16x16x32_bf16 v[4:7], v[152:155], v[200:203], v[4:7]
	v_mfma_f32_16x16x32_bf16 v[62:65], v[148:151], v[180:183], v[62:65]
	v_mfma_f32_16x16x32_bf16 v[54:57], v[156:159], v[180:183], v[54:57]
	v_mfma_f32_16x16x32_bf16 v[46:49], v[148:151], v[188:191], v[46:49]
	v_mfma_f32_16x16x32_bf16 v[38:41], v[156:159], v[188:191], v[38:41]
	v_mfma_f32_16x16x32_bf16 v[30:33], v[148:151], v[196:199], v[30:33]
	v_mfma_f32_16x16x32_bf16 v[22:25], v[156:159], v[196:199], v[22:25]
	v_mfma_f32_16x16x32_bf16 v[12:15], v[148:151], v[204:207], v[12:15]
	v_mfma_f32_16x16x32_bf16 v[4:7], v[156:159], v[204:207], v[4:7]
	s_setprio 0
	s_setprio 1
	v_mfma_f32_16x16x32_bf16 v[58:61], v[160:163], v[176:179], v[58:61]
	v_mfma_f32_16x16x32_bf16 v[50:53], v[168:171], v[176:179], v[50:53]
	v_mfma_f32_16x16x32_bf16 v[42:45], v[160:163], v[184:187], v[42:45]
	v_mfma_f32_16x16x32_bf16 v[34:37], v[168:171], v[184:187], v[34:37]
	v_mfma_f32_16x16x32_bf16 v[26:29], v[160:163], v[192:195], v[26:29]
	v_mfma_f32_16x16x32_bf16 v[18:21], v[168:171], v[192:195], v[18:21]
	v_mfma_f32_16x16x32_bf16 v[8:11], v[160:163], v[200:203], v[8:11]
	v_mfma_f32_16x16x32_bf16 v[0:3], v[168:171], v[200:203], v[0:3]
	v_mfma_f32_16x16x32_bf16 v[58:61], v[164:167], v[180:183], v[58:61]
	v_mfma_f32_16x16x32_bf16 v[50:53], v[172:175], v[180:183], v[50:53]
	v_mfma_f32_16x16x32_bf16 v[42:45], v[164:167], v[188:191], v[42:45]
	v_mfma_f32_16x16x32_bf16 v[34:37], v[172:175], v[188:191], v[34:37]
	v_mfma_f32_16x16x32_bf16 v[26:29], v[164:167], v[196:199], v[26:29]
	v_mfma_f32_16x16x32_bf16 v[18:21], v[172:175], v[196:199], v[18:21]
	v_mfma_f32_16x16x32_bf16 v[8:11], v[164:167], v[204:207], v[8:11]
	v_mfma_f32_16x16x32_bf16 v[0:3], v[172:175], v[204:207], v[0:3]
	s_setprio 0
	s_barrier
	s_add_i32 s91, 0, 0x18000
	s_add_i32 s92, 0, 0x1c000
	v_add_u32_e32 v156, s91, v141
	v_add_u32_e32 v172, s92, v141
	ds_read_b128 v[144:147], v156
	ds_read_b128 v[148:151], v156 offset:1024
	ds_read_b128 v[152:155], v156 offset:2048
	ds_read_b128 v[156:159], v156 offset:3072
	ds_read_b128 v[160:163], v172
	ds_read_b128 v[164:167], v172 offset:1024
	ds_read_b128 v[168:171], v172 offset:2048
	ds_read_b128 v[172:175], v172 offset:3072
	s_add_u32 s48, s48, 0x80000
	s_addc_u32 s49, s49, 0
	s_mov_b32 m0, s57
	ds_read_b128 v[176:179], v143 offset:32768
	ds_read_b128 v[180:183], v143 offset:33792
	ds_read_b128 v[184:187], v143 offset:34816
	ds_read_b128 v[188:191], v143 offset:35840
	ds_read_b128 v[192:195], v143 offset:36864
	ds_read_b128 v[196:199], v143 offset:37888
	ds_read_b128 v[200:203], v143 offset:38912
	ds_read_b128 v[204:207], v143 offset:39936
	global_load_lds_dwordx4 v134, s[48:49]
	s_mov_b32 m0, s58
	s_nop 0
	global_load_lds_dwordx4 v132, s[48:49]
	s_waitcnt vmcnt(8)
	s_waitcnt lgkmcnt(0)
	s_barrier
	s_setprio 1
	s_waitcnt lgkmcnt(0)
	s_nop 0
	v_mfma_f32_16x16x32_bf16 v[126:129], v[144:147], v[176:179], v[126:129]
	v_mfma_f32_16x16x32_bf16 v[118:121], v[152:155], v[176:179], v[118:121]
	v_mfma_f32_16x16x32_bf16 v[110:113], v[144:147], v[184:187], v[110:113]
	v_mfma_f32_16x16x32_bf16 v[102:105], v[152:155], v[184:187], v[102:105]
	v_mfma_f32_16x16x32_bf16 v[94:97], v[144:147], v[192:195], v[94:97]
	v_mfma_f32_16x16x32_bf16 v[86:89], v[152:155], v[192:195], v[86:89]
	v_mfma_f32_16x16x32_bf16 v[78:81], v[144:147], v[200:203], v[78:81]
	v_mfma_f32_16x16x32_bf16 v[70:73], v[152:155], v[200:203], v[70:73]
	v_mfma_f32_16x16x32_bf16 v[126:129], v[148:151], v[180:183], v[126:129]
	v_mfma_f32_16x16x32_bf16 v[118:121], v[156:159], v[180:183], v[118:121]
	v_mfma_f32_16x16x32_bf16 v[110:113], v[148:151], v[188:191], v[110:113]
	v_mfma_f32_16x16x32_bf16 v[102:105], v[156:159], v[188:191], v[102:105]
	v_mfma_f32_16x16x32_bf16 v[94:97], v[148:151], v[196:199], v[94:97]
	v_mfma_f32_16x16x32_bf16 v[86:89], v[156:159], v[196:199], v[86:89]
	v_mfma_f32_16x16x32_bf16 v[78:81], v[148:151], v[204:207], v[78:81]
	v_mfma_f32_16x16x32_bf16 v[70:73], v[156:159], v[204:207], v[70:73]
	s_setprio 0
	s_setprio 1
	v_mfma_f32_16x16x32_bf16 v[122:125], v[160:163], v[176:179], v[122:125]
	v_mfma_f32_16x16x32_bf16 v[114:117], v[168:171], v[176:179], v[114:117]
	v_mfma_f32_16x16x32_bf16 v[106:109], v[160:163], v[184:187], v[106:109]
	v_mfma_f32_16x16x32_bf16 v[98:101], v[168:171], v[184:187], v[98:101]
	v_mfma_f32_16x16x32_bf16 v[90:93], v[160:163], v[192:195], v[90:93]
	v_mfma_f32_16x16x32_bf16 v[82:85], v[168:171], v[192:195], v[82:85]
	v_mfma_f32_16x16x32_bf16 v[74:77], v[160:163], v[200:203], v[74:77]
	v_mfma_f32_16x16x32_bf16 v[66:69], v[168:171], v[200:203], v[66:69]
	v_mfma_f32_16x16x32_bf16 v[122:125], v[164:167], v[180:183], v[122:125]
	v_mfma_f32_16x16x32_bf16 v[114:117], v[172:175], v[180:183], v[114:117]
	v_mfma_f32_16x16x32_bf16 v[106:109], v[164:167], v[188:191], v[106:109]
	v_mfma_f32_16x16x32_bf16 v[98:101], v[172:175], v[188:191], v[98:101]
	v_mfma_f32_16x16x32_bf16 v[90:93], v[164:167], v[196:199], v[90:93]
	v_mfma_f32_16x16x32_bf16 v[82:85], v[172:175], v[196:199], v[82:85]
	v_mfma_f32_16x16x32_bf16 v[74:77], v[164:167], v[204:207], v[74:77]
	v_mfma_f32_16x16x32_bf16 v[66:69], v[172:175], v[204:207], v[66:69]
	s_setprio 0
	s_barrier
	s_add_i32 s48, s91, s37
	s_add_u32 s28, s28, 0x80
	s_addc_u32 s29, s29, 0
	s_mov_b32 m0, s48
	ds_read_b128 v[176:179], v143 offset:49152
	ds_read_b128 v[180:183], v143 offset:50176
	ds_read_b128 v[184:187], v143 offset:51200
	ds_read_b128 v[188:191], v143 offset:52224
	ds_read_b128 v[192:195], v143 offset:53248
	ds_read_b128 v[196:199], v143 offset:54272
	ds_read_b128 v[200:203], v143 offset:55296
	ds_read_b128 v[204:207], v143 offset:56320
	global_load_lds_dwordx4 v16, s[28:29]
	s_add_i32 m0, s48, 0x2000
	s_add_i32 s48, s92, s37
	global_load_lds_dwordx4 v130, s[28:29]
	s_add_u32 s28, s28, 0x80000
	s_addc_u32 s29, s29, 0
	s_mov_b32 m0, s48
	s_nop 0
	global_load_lds_dwordx4 v16, s[28:29]
	s_add_i32 m0, s48, 0x2000
	s_nop 0
	global_load_lds_dwordx4 v130, s[28:29]
	v_lshl_add_u64 v[216:217], v[226:227], 0, s[34:35]
	s_mov_b32 m0, s59
	s_nop 0
	global_load_lds_dwordx4 v[216:217], off
	v_lshl_add_u64 v[216:217], v[228:229], 0, s[34:35]
	s_mov_b32 m0, s83
	s_nop 0
	global_load_lds_dwordx4 v[216:217], off
	s_waitcnt vmcnt(8)
	s_waitcnt lgkmcnt(0)
	s_barrier
	s_setprio 1
	s_waitcnt lgkmcnt(0)
	s_nop 0
	v_mfma_f32_16x16x32_bf16 v[62:65], v[144:147], v[176:179], v[62:65]
	v_mfma_f32_16x16x32_bf16 v[54:57], v[152:155], v[176:179], v[54:57]
	v_mfma_f32_16x16x32_bf16 v[46:49], v[144:147], v[184:187], v[46:49]
	v_mfma_f32_16x16x32_bf16 v[38:41], v[152:155], v[184:187], v[38:41]
	v_mfma_f32_16x16x32_bf16 v[30:33], v[144:147], v[192:195], v[30:33]
	v_mfma_f32_16x16x32_bf16 v[22:25], v[152:155], v[192:195], v[22:25]
	v_mfma_f32_16x16x32_bf16 v[12:15], v[144:147], v[200:203], v[12:15]
	v_mfma_f32_16x16x32_bf16 v[4:7], v[152:155], v[200:203], v[4:7]
	v_mfma_f32_16x16x32_bf16 v[62:65], v[148:151], v[180:183], v[62:65]
	v_mfma_f32_16x16x32_bf16 v[54:57], v[156:159], v[180:183], v[54:57]
	v_mfma_f32_16x16x32_bf16 v[46:49], v[148:151], v[188:191], v[46:49]
	v_mfma_f32_16x16x32_bf16 v[38:41], v[156:159], v[188:191], v[38:41]
	v_mfma_f32_16x16x32_bf16 v[30:33], v[148:151], v[196:199], v[30:33]
	v_mfma_f32_16x16x32_bf16 v[22:25], v[156:159], v[196:199], v[22:25]
	v_mfma_f32_16x16x32_bf16 v[12:15], v[148:151], v[204:207], v[12:15]
	v_mfma_f32_16x16x32_bf16 v[4:7], v[156:159], v[204:207], v[4:7]
	s_setprio 0
	s_setprio 1
	v_mfma_f32_16x16x32_bf16 v[58:61], v[160:163], v[176:179], v[58:61]
	v_mfma_f32_16x16x32_bf16 v[50:53], v[168:171], v[176:179], v[50:53]
	v_mfma_f32_16x16x32_bf16 v[42:45], v[160:163], v[184:187], v[42:45]
	v_mfma_f32_16x16x32_bf16 v[34:37], v[168:171], v[184:187], v[34:37]
	v_mfma_f32_16x16x32_bf16 v[26:29], v[160:163], v[192:195], v[26:29]
	v_mfma_f32_16x16x32_bf16 v[18:21], v[168:171], v[192:195], v[18:21]
	v_mfma_f32_16x16x32_bf16 v[8:11], v[160:163], v[200:203], v[8:11]
	v_mfma_f32_16x16x32_bf16 v[0:3], v[168:171], v[200:203], v[0:3]
	v_mfma_f32_16x16x32_bf16 v[58:61], v[164:167], v[180:183], v[58:61]
	v_mfma_f32_16x16x32_bf16 v[50:53], v[172:175], v[180:183], v[50:53]
	v_mfma_f32_16x16x32_bf16 v[42:45], v[164:167], v[188:191], v[42:45]
	v_mfma_f32_16x16x32_bf16 v[34:37], v[172:175], v[188:191], v[34:37]
	v_mfma_f32_16x16x32_bf16 v[26:29], v[164:167], v[196:199], v[26:29]
	v_mfma_f32_16x16x32_bf16 v[18:21], v[172:175], v[196:199], v[18:21]
	v_mfma_f32_16x16x32_bf16 v[8:11], v[164:167], v[204:207], v[8:11]
	v_mfma_f32_16x16x32_bf16 v[0:3], v[172:175], v[204:207], v[0:3]
	s_setprio 0
	s_barrier
	s_add_i32 s90, s90, 2
	s_add_u32 s46, s46, 0x100
	s_addc_u32 s47, s47, 0
	s_add_u32 s88, s88, 0x100
	s_addc_u32 s89, s89, 0
	s_cmp_gt_u32 s90, 29
	s_cbranch_scc0 .LBB0_920

.LBB0_991:
	s_add_u32 s42, s42, 0x100
	s_addc_u32 s43, s43, 0
	s_mov_b32 s86, -2
	s_add_u32 s36, s26, 0x100
	s_addc_u32 s37, s27, 0
	s_add_i32 s87, 0, 0x10000
	s_cmpk_eq_i32 s86, 0x54
	s_cselect_b32 s41, s19, s37
	s_cselect_b32 s40, s18, s36
	s_cselect_b32 s29, s23, s43
	s_cselect_b32 s28, s22, s42
	s_add_i32 s88, 0, 0x14000
	v_add_u32_e32 v142, s87, v203
	v_add_u32_e32 v158, s88, v203
	ds_read_b128 v[130:133], v142
	ds_read_b128 v[134:137], v142 offset:1024
	ds_read_b128 v[138:141], v142 offset:2048
	ds_read_b128 v[142:145], v142 offset:3072
	ds_read_b128 v[146:149], v158
	ds_read_b128 v[150:153], v158 offset:1024
	ds_read_b128 v[154:157], v158 offset:2048
	ds_read_b128 v[158:161], v158 offset:3072
	s_add_i32 m0, s47, 0xc000
	ds_read_b128 v[162:165], v205
	ds_read_b128 v[166:169], v205 offset:1024
	ds_read_b128 v[170:173], v205 offset:2048
	ds_read_b128 v[174:177], v205 offset:3072
	ds_read_b128 v[178:181], v205 offset:4096
	ds_read_b128 v[192:195], v205 offset:5120
	ds_read_b128 v[196:199], v205 offset:6144
	ds_read_b128 v[224:227], v205 offset:7168
	global_load_lds_dwordx4 v188, s[26:27]
	s_add_i32 m0, s47, 0xe000
	s_nop 0
	global_load_lds_dwordx4 v190, s[26:27]
	s_waitcnt vmcnt(8)
	s_waitcnt lgkmcnt(0)
	s_barrier
	s_setprio 1
	s_waitcnt lgkmcnt(0)
	v_mfma_f32_16x16x32_bf16 v[126:129], v[130:133], v[162:165], 0
	v_mfma_f32_16x16x32_bf16 v[122:125], v[138:141], v[162:165], 0
	v_mfma_f32_16x16x32_bf16 v[114:117], v[130:133], v[170:173], 0
	v_mfma_f32_16x16x32_bf16 v[106:109], v[138:141], v[170:173], 0
	v_mfma_f32_16x16x32_bf16 v[98:101], v[130:133], v[178:181], 0
	v_mfma_f32_16x16x32_bf16 v[90:93], v[138:141], v[178:181], 0
	v_mfma_f32_16x16x32_bf16 v[82:85], v[130:133], v[196:199], 0
	v_mfma_f32_16x16x32_bf16 v[74:77], v[138:141], v[196:199], 0
	v_mfma_f32_16x16x32_bf16 v[126:129], v[134:137], v[166:169], v[126:129]
	v_mfma_f32_16x16x32_bf16 v[122:125], v[142:145], v[166:169], v[122:125]
	v_mfma_f32_16x16x32_bf16 v[114:117], v[134:137], v[174:177], v[114:117]
	v_mfma_f32_16x16x32_bf16 v[106:109], v[142:145], v[174:177], v[106:109]
	v_mfma_f32_16x16x32_bf16 v[98:101], v[134:137], v[192:195], v[98:101]
	v_mfma_f32_16x16x32_bf16 v[90:93], v[142:145], v[192:195], v[90:93]
	v_mfma_f32_16x16x32_bf16 v[82:85], v[134:137], v[224:227], v[82:85]
	v_mfma_f32_16x16x32_bf16 v[74:77], v[142:145], v[224:227], v[74:77]
	s_setprio 0
	s_setprio 1
	v_mfma_f32_16x16x32_bf16 v[118:121], v[146:149], v[162:165], 0
	v_mfma_f32_16x16x32_bf16 v[110:113], v[154:157], v[162:165], 0
	v_mfma_f32_16x16x32_bf16 v[102:105], v[146:149], v[170:173], 0
	v_mfma_f32_16x16x32_bf16 v[94:97], v[154:157], v[170:173], 0
	v_mfma_f32_16x16x32_bf16 v[86:89], v[146:149], v[178:181], 0
	v_mfma_f32_16x16x32_bf16 v[78:81], v[154:157], v[178:181], 0
	v_mfma_f32_16x16x32_bf16 v[70:73], v[146:149], v[196:199], 0
	v_mfma_f32_16x16x32_bf16 v[66:69], v[154:157], v[196:199], 0
	v_mfma_f32_16x16x32_bf16 v[118:121], v[150:153], v[166:169], v[118:121]
	v_mfma_f32_16x16x32_bf16 v[110:113], v[158:161], v[166:169], v[110:113]
	v_mfma_f32_16x16x32_bf16 v[102:105], v[150:153], v[174:177], v[102:105]
	v_mfma_f32_16x16x32_bf16 v[94:97], v[158:161], v[174:177], v[94:97]
	v_mfma_f32_16x16x32_bf16 v[86:89], v[150:153], v[192:195], v[86:89]
	v_mfma_f32_16x16x32_bf16 v[78:81], v[158:161], v[192:195], v[78:81]
	v_mfma_f32_16x16x32_bf16 v[70:73], v[150:153], v[224:227], v[70:73]
	v_mfma_f32_16x16x32_bf16 v[66:69], v[158:161], v[224:227], v[66:69]
	s_setprio 0
	s_barrier
	s_add_i32 s26, s87, s45
	v_lshl_add_u64 v[200:201], s[28:29], 0, v[16:17]
	s_mov_b32 m0, s26
	ds_read_b128 v[162:165], v205 offset:16384
	ds_read_b128 v[166:169], v205 offset:17408
	ds_read_b128 v[170:173], v205 offset:18432
	ds_read_b128 v[174:177], v205 offset:19456
	ds_read_b128 v[178:181], v205 offset:20480
	ds_read_b128 v[192:195], v205 offset:21504
	ds_read_b128 v[196:199], v205 offset:22528
	ds_read_b128 v[224:227], v205 offset:23552
	global_load_lds_dwordx4 v[200:201], off
	s_add_i32 m0, s26, 0x2000
	s_add_u32 s26, s28, 0x160000
	v_lshl_add_u64 v[206:207], s[28:29], 0, v[182:183]
	s_addc_u32 s27, s29, 0
	s_add_i32 s87, s88, s45
	global_load_lds_dwordx4 v[206:207], off
	s_mov_b32 m0, s87
	v_lshl_add_u64 v[228:229], s[40:41], 0, v[184:185]
	global_load_lds_dwordx4 v16, s[26:27]
	s_add_i32 m0, s87, 0x2000
	s_nop 0
	global_load_lds_dwordx4 v182, s[26:27]
	v_lshl_add_u64 v[216:217], s[40:41], 0, v[186:187]
	s_mov_b32 m0, s47
	s_nop 0
	global_load_lds_dwordx4 v[216:217], off
	s_mov_b32 m0, s48
	s_nop 0
	global_load_lds_dwordx4 v[228:229], off
	s_waitcnt vmcnt(8)
	s_waitcnt lgkmcnt(0)
	s_barrier
	s_setprio 1
	s_waitcnt lgkmcnt(0)
	s_nop 0
	v_mfma_f32_16x16x32_bf16 v[62:65], v[130:133], v[162:165], 0
	v_mfma_f32_16x16x32_bf16 v[58:61], v[138:141], v[162:165], 0
	v_mfma_f32_16x16x32_bf16 v[50:53], v[130:133], v[170:173], 0
	v_mfma_f32_16x16x32_bf16 v[42:45], v[138:141], v[170:173], 0
	v_mfma_f32_16x16x32_bf16 v[34:37], v[130:133], v[178:181], 0
	v_mfma_f32_16x16x32_bf16 v[26:29], v[138:141], v[178:181], 0
	v_mfma_f32_16x16x32_bf16 v[18:21], v[130:133], v[196:199], 0
	v_mfma_f32_16x16x32_bf16 v[8:11], v[138:141], v[196:199], 0
	v_mfma_f32_16x16x32_bf16 v[62:65], v[134:137], v[166:169], v[62:65]
	v_mfma_f32_16x16x32_bf16 v[58:61], v[142:145], v[166:169], v[58:61]
	v_mfma_f32_16x16x32_bf16 v[50:53], v[134:137], v[174:177], v[50:53]
	v_mfma_f32_16x16x32_bf16 v[42:45], v[142:145], v[174:177], v[42:45]
	v_mfma_f32_16x16x32_bf16 v[34:37], v[134:137], v[192:195], v[34:37]
	v_mfma_f32_16x16x32_bf16 v[26:29], v[142:145], v[192:195], v[26:29]
	v_mfma_f32_16x16x32_bf16 v[18:21], v[134:137], v[224:227], v[18:21]
	v_mfma_f32_16x16x32_bf16 v[8:11], v[142:145], v[224:227], v[8:11]
	s_setprio 0
	s_setprio 1
	v_mfma_f32_16x16x32_bf16 v[54:57], v[146:149], v[162:165], 0
	v_mfma_f32_16x16x32_bf16 v[46:49], v[154:157], v[162:165], 0
	v_mfma_f32_16x16x32_bf16 v[38:41], v[146:149], v[170:173], 0
	v_mfma_f32_16x16x32_bf16 v[30:33], v[154:157], v[170:173], 0
	v_mfma_f32_16x16x32_bf16 v[22:25], v[146:149], v[178:181], 0
	v_mfma_f32_16x16x32_bf16 v[12:15], v[154:157], v[178:181], 0
	v_mfma_f32_16x16x32_bf16 v[4:7], v[146:149], v[196:199], 0
	v_mfma_f32_16x16x32_bf16 v[0:3], v[154:157], v[196:199], 0
	v_mfma_f32_16x16x32_bf16 v[54:57], v[150:153], v[166:169], v[54:57]
	v_mfma_f32_16x16x32_bf16 v[46:49], v[158:161], v[166:169], v[46:49]
	v_mfma_f32_16x16x32_bf16 v[38:41], v[150:153], v[174:177], v[38:41]
	v_mfma_f32_16x16x32_bf16 v[30:33], v[158:161], v[174:177], v[30:33]
	v_mfma_f32_16x16x32_bf16 v[22:25], v[150:153], v[192:195], v[22:25]
	v_mfma_f32_16x16x32_bf16 v[12:15], v[158:161], v[192:195], v[12:15]
	v_mfma_f32_16x16x32_bf16 v[4:7], v[150:153], v[224:227], v[4:7]
	v_mfma_f32_16x16x32_bf16 v[0:3], v[158:161], v[224:227], v[0:3]
	s_setprio 0
	s_barrier
	s_add_i32 s87, 0, 0x18000
	s_add_i32 s88, 0, 0x1c000
	v_add_u32_e32 v142, s87, v203
	v_add_u32_e32 v158, s88, v203
	ds_read_b128 v[130:133], v142
	ds_read_b128 v[134:137], v142 offset:1024
	ds_read_b128 v[138:141], v142 offset:2048
	ds_read_b128 v[142:145], v142 offset:3072
	ds_read_b128 v[146:149], v158
	ds_read_b128 v[150:153], v158 offset:1024
	ds_read_b128 v[154:157], v158 offset:2048
	ds_read_b128 v[158:161], v158 offset:3072
	s_add_u32 s26, s40, 0x160000
	s_addc_u32 s27, s41, 0
	s_mov_b32 m0, s49
	ds_read_b128 v[162:165], v205 offset:32768
	ds_read_b128 v[166:169], v205 offset:33792
	ds_read_b128 v[170:173], v205 offset:34816
	ds_read_b128 v[174:177], v205 offset:35840
	ds_read_b128 v[178:181], v205 offset:36864
	ds_read_b128 v[192:195], v205 offset:37888
	ds_read_b128 v[196:199], v205 offset:38912
	ds_read_b128 v[224:227], v205 offset:39936
	global_load_lds_dwordx4 v186, s[26:27]
	s_mov_b32 m0, s50
	s_nop 0
	global_load_lds_dwordx4 v184, s[26:27]
	s_waitcnt vmcnt(8)
	s_waitcnt lgkmcnt(0)
	s_barrier
	s_setprio 1
	s_waitcnt lgkmcnt(0)
	s_nop 0
	v_mfma_f32_16x16x32_bf16 v[126:129], v[130:133], v[162:165], v[126:129]
	v_mfma_f32_16x16x32_bf16 v[122:125], v[138:141], v[162:165], v[122:125]
	v_mfma_f32_16x16x32_bf16 v[114:117], v[130:133], v[170:173], v[114:117]
	v_mfma_f32_16x16x32_bf16 v[106:109], v[138:141], v[170:173], v[106:109]
	v_mfma_f32_16x16x32_bf16 v[98:101], v[130:133], v[178:181], v[98:101]
	v_mfma_f32_16x16x32_bf16 v[90:93], v[138:141], v[178:181], v[90:93]
	v_mfma_f32_16x16x32_bf16 v[82:85], v[130:133], v[196:199], v[82:85]
	v_mfma_f32_16x16x32_bf16 v[74:77], v[138:141], v[196:199], v[74:77]
	v_mfma_f32_16x16x32_bf16 v[126:129], v[134:137], v[166:169], v[126:129]
	v_mfma_f32_16x16x32_bf16 v[122:125], v[142:145], v[166:169], v[122:125]
	v_mfma_f32_16x16x32_bf16 v[114:117], v[134:137], v[174:177], v[114:117]
	v_mfma_f32_16x16x32_bf16 v[106:109], v[142:145], v[174:177], v[106:109]
	v_mfma_f32_16x16x32_bf16 v[98:101], v[134:137], v[192:195], v[98:101]
	v_mfma_f32_16x16x32_bf16 v[90:93], v[142:145], v[192:195], v[90:93]
	v_mfma_f32_16x16x32_bf16 v[82:85], v[134:137], v[224:227], v[82:85]
	v_mfma_f32_16x16x32_bf16 v[74:77], v[142:145], v[224:227], v[74:77]
	s_setprio 0
	s_setprio 1
	v_mfma_f32_16x16x32_bf16 v[118:121], v[146:149], v[162:165], v[118:121]
	v_mfma_f32_16x16x32_bf16 v[110:113], v[154:157], v[162:165], v[110:113]
	v_mfma_f32_16x16x32_bf16 v[102:105], v[146:149], v[170:173], v[102:105]
	v_mfma_f32_16x16x32_bf16 v[94:97], v[154:157], v[170:173], v[94:97]
	v_mfma_f32_16x16x32_bf16 v[86:89], v[146:149], v[178:181], v[86:89]
	v_mfma_f32_16x16x32_bf16 v[78:81], v[154:157], v[178:181], v[78:81]
	v_mfma_f32_16x16x32_bf16 v[70:73], v[146:149], v[196:199], v[70:73]
	v_mfma_f32_16x16x32_bf16 v[66:69], v[154:157], v[196:199], v[66:69]
	v_mfma_f32_16x16x32_bf16 v[118:121], v[150:153], v[166:169], v[118:121]
	v_mfma_f32_16x16x32_bf16 v[110:113], v[158:161], v[166:169], v[110:113]
	v_mfma_f32_16x16x32_bf16 v[102:105], v[150:153], v[174:177], v[102:105]
	v_mfma_f32_16x16x32_bf16 v[94:97], v[158:161], v[174:177], v[94:97]
	v_mfma_f32_16x16x32_bf16 v[86:89], v[150:153], v[192:195], v[86:89]
	v_mfma_f32_16x16x32_bf16 v[78:81], v[158:161], v[192:195], v[78:81]
	v_mfma_f32_16x16x32_bf16 v[70:73], v[150:153], v[224:227], v[70:73]
	v_mfma_f32_16x16x32_bf16 v[66:69], v[158:161], v[224:227], v[66:69]
	s_setprio 0
	s_barrier
	s_add_i32 s26, s87, s45
	v_lshl_add_u64 v[200:201], v[200:201], 0, s[34:35]
	s_mov_b32 m0, s26
	ds_read_b128 v[162:165], v205 offset:49152
	ds_read_b128 v[166:169], v205 offset:50176
	ds_read_b128 v[170:173], v205 offset:51200
	ds_read_b128 v[174:177], v205 offset:52224
	ds_read_b128 v[178:181], v205 offset:53248
	ds_read_b128 v[192:195], v205 offset:54272
	ds_read_b128 v[196:199], v205 offset:55296
	ds_read_b128 v[224:227], v205 offset:56320
	global_load_lds_dwordx4 v[200:201], off
	s_add_i32 m0, s26, 0x2000
	s_add_u32 s26, s28, 0x160080
	v_lshl_add_u64 v[200:201], v[206:207], 0, s[34:35]
	s_addc_u32 s27, s29, 0
	s_add_i32 s28, s88, s45
	global_load_lds_dwordx4 v[200:201], off
	s_mov_b32 m0, s28
	s_nop 0
	global_load_lds_dwordx4 v16, s[26:27]
	s_add_i32 m0, s28, 0x2000
	s_nop 0
	global_load_lds_dwordx4 v182, s[26:27]
	v_lshl_add_u64 v[200:201], v[216:217], 0, s[34:35]
	s_mov_b32 m0, s53
	s_nop 0
	global_load_lds_dwordx4 v[200:201], off
	v_lshl_add_u64 v[200:201], v[228:229], 0, s[34:35]
	s_mov_b32 m0, s57
	s_nop 0
	global_load_lds_dwordx4 v[200:201], off
	s_waitcnt vmcnt(8)
	s_waitcnt lgkmcnt(0)
	s_barrier
	s_setprio 1
	s_waitcnt lgkmcnt(0)
	v_mfma_f32_16x16x32_bf16 v[62:65], v[130:133], v[162:165], v[62:65]
	v_mfma_f32_16x16x32_bf16 v[58:61], v[138:141], v[162:165], v[58:61]
	v_mfma_f32_16x16x32_bf16 v[50:53], v[130:133], v[170:173], v[50:53]
	v_mfma_f32_16x16x32_bf16 v[42:45], v[138:141], v[170:173], v[42:45]
	v_mfma_f32_16x16x32_bf16 v[34:37], v[130:133], v[178:181], v[34:37]
	v_mfma_f32_16x16x32_bf16 v[26:29], v[138:141], v[178:181], v[26:29]
	v_mfma_f32_16x16x32_bf16 v[18:21], v[130:133], v[196:199], v[18:21]
	v_mfma_f32_16x16x32_bf16 v[8:11], v[138:141], v[196:199], v[8:11]
	v_mfma_f32_16x16x32_bf16 v[62:65], v[134:137], v[166:169], v[62:65]
	v_mfma_f32_16x16x32_bf16 v[58:61], v[142:145], v[166:169], v[58:61]
	v_mfma_f32_16x16x32_bf16 v[50:53], v[134:137], v[174:177], v[50:53]
	v_mfma_f32_16x16x32_bf16 v[42:45], v[142:145], v[174:177], v[42:45]
	v_mfma_f32_16x16x32_bf16 v[34:37], v[134:137], v[192:195], v[34:37]
	v_mfma_f32_16x16x32_bf16 v[26:29], v[142:145], v[192:195], v[26:29]
	v_mfma_f32_16x16x32_bf16 v[18:21], v[134:137], v[224:227], v[18:21]
	v_mfma_f32_16x16x32_bf16 v[8:11], v[142:145], v[224:227], v[8:11]
	s_setprio 0
	s_setprio 1
	v_mfma_f32_16x16x32_bf16 v[54:57], v[146:149], v[162:165], v[54:57]
	v_mfma_f32_16x16x32_bf16 v[46:49], v[154:157], v[162:165], v[46:49]
	v_mfma_f32_16x16x32_bf16 v[38:41], v[146:149], v[170:173], v[38:41]
	v_mfma_f32_16x16x32_bf16 v[30:33], v[154:157], v[170:173], v[30:33]
	v_mfma_f32_16x16x32_bf16 v[22:25], v[146:149], v[178:181], v[22:25]
	v_mfma_f32_16x16x32_bf16 v[12:15], v[154:157], v[178:181], v[12:15]
	v_mfma_f32_16x16x32_bf16 v[4:7], v[146:149], v[196:199], v[4:7]
	v_mfma_f32_16x16x32_bf16 v[0:3], v[154:157], v[196:199], v[0:3]
	v_mfma_f32_16x16x32_bf16 v[54:57], v[150:153], v[166:169], v[54:57]
	v_mfma_f32_16x16x32_bf16 v[46:49], v[158:161], v[166:169], v[46:49]
	v_mfma_f32_16x16x32_bf16 v[38:41], v[150:153], v[174:177], v[38:41]
	v_mfma_f32_16x16x32_bf16 v[30:33], v[158:161], v[174:177], v[30:33]
	v_mfma_f32_16x16x32_bf16 v[22:25], v[150:153], v[192:195], v[22:25]
	v_mfma_f32_16x16x32_bf16 v[12:15], v[158:161], v[192:195], v[12:15]
	v_mfma_f32_16x16x32_bf16 v[4:7], v[150:153], v[224:227], v[4:7]
	v_mfma_f32_16x16x32_bf16 v[0:3], v[158:161], v[224:227], v[0:3]
	s_setprio 0
	s_barrier
	s_add_i32 s86, s86, 2
	s_add_u32 s42, s42, 0x100
	s_addc_u32 s43, s43, 0
	s_cmpk_gt_u32 s86, 0x55
	s_mov_b64 s[26:27], s[36:37]
	s_cbranch_scc1 .Lpz_J_exit
.LBB0_992:
	s_add_u32 s36, s26, 0x100
	s_addc_u32 s37, s27, 0
	s_add_i32 s87, 0, 0x10000
	s_cmpk_eq_i32 s86, 0x54
	s_cselect_b32 s41, s19, s37
	s_cselect_b32 s40, s18, s36
	s_cselect_b32 s29, s23, s43
	s_cselect_b32 s28, s22, s42
	s_add_i32 s88, 0, 0x14000
	v_add_u32_e32 v142, s87, v203
	v_add_u32_e32 v158, s88, v203
	ds_read_b128 v[130:133], v142
	ds_read_b128 v[134:137], v142 offset:1024
	ds_read_b128 v[138:141], v142 offset:2048
	ds_read_b128 v[142:145], v142 offset:3072
	ds_read_b128 v[146:149], v158
	ds_read_b128 v[150:153], v158 offset:1024
	ds_read_b128 v[154:157], v158 offset:2048
	ds_read_b128 v[158:161], v158 offset:3072
	s_add_i32 m0, s47, 0xc000
	ds_read_b128 v[162:165], v205
	ds_read_b128 v[166:169], v205 offset:1024
	ds_read_b128 v[170:173], v205 offset:2048
	ds_read_b128 v[174:177], v205 offset:3072
	ds_read_b128 v[178:181], v205 offset:4096
	ds_read_b128 v[192:195], v205 offset:5120
	ds_read_b128 v[196:199], v205 offset:6144
	ds_read_b128 v[224:227], v205 offset:7168
	global_load_lds_dwordx4 v188, s[26:27]
	s_add_i32 m0, s47, 0xe000
	s_nop 0
	global_load_lds_dwordx4 v190, s[26:27]
	s_waitcnt vmcnt(8)
	s_waitcnt lgkmcnt(0)
	s_barrier
	s_setprio 1
	s_waitcnt lgkmcnt(0)
	s_nop 0
	v_mfma_f32_16x16x32_bf16 v[126:129], v[130:133], v[162:165], v[126:129]
	v_mfma_f32_16x16x32_bf16 v[122:125], v[138:141], v[162:165], v[122:125]
	v_mfma_f32_16x16x32_bf16 v[114:117], v[130:133], v[170:173], v[114:117]
	v_mfma_f32_16x16x32_bf16 v[106:109], v[138:141], v[170:173], v[106:109]
	v_mfma_f32_16x16x32_bf16 v[98:101], v[130:133], v[178:181], v[98:101]
	v_mfma_f32_16x16x32_bf16 v[90:93], v[138:141], v[178:181], v[90:93]
	v_mfma_f32_16x16x32_bf16 v[82:85], v[130:133], v[196:199], v[82:85]
	v_mfma_f32_16x16x32_bf16 v[74:77], v[138:141], v[196:199], v[74:77]
	v_mfma_f32_16x16x32_bf16 v[126:129], v[134:137], v[166:169], v[126:129]
	v_mfma_f32_16x16x32_bf16 v[122:125], v[142:145], v[166:169], v[122:125]
	v_mfma_f32_16x16x32_bf16 v[114:117], v[134:137], v[174:177], v[114:117]
	v_mfma_f32_16x16x32_bf16 v[106:109], v[142:145], v[174:177], v[106:109]
	v_mfma_f32_16x16x32_bf16 v[98:101], v[134:137], v[192:195], v[98:101]
	v_mfma_f32_16x16x32_bf16 v[90:93], v[142:145], v[192:195], v[90:93]
	v_mfma_f32_16x16x32_bf16 v[82:85], v[134:137], v[224:227], v[82:85]
	v_mfma_f32_16x16x32_bf16 v[74:77], v[142:145], v[224:227], v[74:77]
	s_setprio 0
	s_setprio 1
	v_mfma_f32_16x16x32_bf16 v[118:121], v[146:149], v[162:165], v[118:121]
	v_mfma_f32_16x16x32_bf16 v[110:113], v[154:157], v[162:165], v[110:113]
	v_mfma_f32_16x16x32_bf16 v[102:105], v[146:149], v[170:173], v[102:105]
	v_mfma_f32_16x16x32_bf16 v[94:97], v[154:157], v[170:173], v[94:97]
	v_mfma_f32_16x16x32_bf16 v[86:89], v[146:149], v[178:181], v[86:89]
	v_mfma_f32_16x16x32_bf16 v[78:81], v[154:157], v[178:181], v[78:81]
	v_mfma_f32_16x16x32_bf16 v[70:73], v[146:149], v[196:199], v[70:73]
	v_mfma_f32_16x16x32_bf16 v[66:69], v[154:157], v[196:199], v[66:69]
	v_mfma_f32_16x16x32_bf16 v[118:121], v[150:153], v[166:169], v[118:121]
	v_mfma_f32_16x16x32_bf16 v[110:113], v[158:161], v[166:169], v[110:113]
	v_mfma_f32_16x16x32_bf16 v[102:105], v[150:153], v[174:177], v[102:105]
	v_mfma_f32_16x16x32_bf16 v[94:97], v[158:161], v[174:177], v[94:97]
	v_mfma_f32_16x16x32_bf16 v[86:89], v[150:153], v[192:195], v[86:89]
	v_mfma_f32_16x16x32_bf16 v[78:81], v[158:161], v[192:195], v[78:81]
	v_mfma_f32_16x16x32_bf16 v[70:73], v[150:153], v[224:227], v[70:73]
	v_mfma_f32_16x16x32_bf16 v[66:69], v[158:161], v[224:227], v[66:69]
	s_setprio 0
	s_barrier
	s_add_i32 s26, s87, s45
	v_lshl_add_u64 v[200:201], s[28:29], 0, v[16:17]
	s_mov_b32 m0, s26
	ds_read_b128 v[162:165], v205 offset:16384
	ds_read_b128 v[166:169], v205 offset:17408
	ds_read_b128 v[170:173], v205 offset:18432
	ds_read_b128 v[174:177], v205 offset:19456
	ds_read_b128 v[178:181], v205 offset:20480
	ds_read_b128 v[192:195], v205 offset:21504
	ds_read_b128 v[196:199], v205 offset:22528
	ds_read_b128 v[224:227], v205 offset:23552
	global_load_lds_dwordx4 v[200:201], off
	s_add_i32 m0, s26, 0x2000
	s_add_u32 s26, s28, 0x160000
	v_lshl_add_u64 v[206:207], s[28:29], 0, v[182:183]
	s_addc_u32 s27, s29, 0
	s_add_i32 s87, s88, s45
	global_load_lds_dwordx4 v[206:207], off
	s_mov_b32 m0, s87
	v_lshl_add_u64 v[228:229], s[40:41], 0, v[184:185]
	global_load_lds_dwordx4 v16, s[26:27]
	s_add_i32 m0, s87, 0x2000
	s_nop 0
	global_load_lds_dwordx4 v182, s[26:27]
	v_lshl_add_u64 v[216:217], s[40:41], 0, v[186:187]
	s_mov_b32 m0, s47
	s_nop 0
	global_load_lds_dwordx4 v[216:217], off
	s_mov_b32 m0, s48
	s_nop 0
	global_load_lds_dwordx4 v[228:229], off
	s_waitcnt vmcnt(8)
	s_waitcnt lgkmcnt(0)
	s_barrier
	s_setprio 1
	s_waitcnt lgkmcnt(0)
	s_nop 0
	v_mfma_f32_16x16x32_bf16 v[62:65], v[130:133], v[162:165], v[62:65]
	v_mfma_f32_16x16x32_bf16 v[58:61], v[138:141], v[162:165], v[58:61]
	v_mfma_f32_16x16x32_bf16 v[50:53], v[130:133], v[170:173], v[50:53]
	v_mfma_f32_16x16x32_bf16 v[42:45], v[138:141], v[170:173], v[42:45]
	v_mfma_f32_16x16x32_bf16 v[34:37], v[130:133], v[178:181], v[34:37]
	v_mfma_f32_16x16x32_bf16 v[26:29], v[138:141], v[178:181], v[26:29]
	v_mfma_f32_16x16x32_bf16 v[18:21], v[130:133], v[196:199], v[18:21]
	v_mfma_f32_16x16x32_bf16 v[8:11], v[138:141], v[196:199], v[8:11]
	v_mfma_f32_16x16x32_bf16 v[62:65], v[134:137], v[166:169], v[62:65]
	v_mfma_f32_16x16x32_bf16 v[58:61], v[142:145], v[166:169], v[58:61]
	v_mfma_f32_16x16x32_bf16 v[50:53], v[134:137], v[174:177], v[50:53]
	v_mfma_f32_16x16x32_bf16 v[42:45], v[142:145], v[174:177], v[42:45]
	v_mfma_f32_16x16x32_bf16 v[34:37], v[134:137], v[192:195], v[34:37]
	v_mfma_f32_16x16x32_bf16 v[26:29], v[142:145], v[192:195], v[26:29]
	v_mfma_f32_16x16x32_bf16 v[18:21], v[134:137], v[224:227], v[18:21]
	v_mfma_f32_16x16x32_bf16 v[8:11], v[142:145], v[224:227], v[8:11]
	s_setprio 0
	s_setprio 1
	v_mfma_f32_16x16x32_bf16 v[54:57], v[146:149], v[162:165], v[54:57]
	v_mfma_f32_16x16x32_bf16 v[46:49], v[154:157], v[162:165], v[46:49]
	v_mfma_f32_16x16x32_bf16 v[38:41], v[146:149], v[170:173], v[38:41]
	v_mfma_f32_16x16x32_bf16 v[30:33], v[154:157], v[170:173], v[30:33]
	v_mfma_f32_16x16x32_bf16 v[22:25], v[146:149], v[178:181], v[22:25]
	v_mfma_f32_16x16x32_bf16 v[12:15], v[154:157], v[178:181], v[12:15]
	v_mfma_f32_16x16x32_bf16 v[4:7], v[146:149], v[196:199], v[4:7]
	v_mfma_f32_16x16x32_bf16 v[0:3], v[154:157], v[196:199], v[0:3]
	v_mfma_f32_16x16x32_bf16 v[54:57], v[150:153], v[166:169], v[54:57]
	v_mfma_f32_16x16x32_bf16 v[46:49], v[158:161], v[166:169], v[46:49]
	v_mfma_f32_16x16x32_bf16 v[38:41], v[150:153], v[174:177], v[38:41]
	v_mfma_f32_16x16x32_bf16 v[30:33], v[158:161], v[174:177], v[30:33]
	v_mfma_f32_16x16x32_bf16 v[22:25], v[150:153], v[192:195], v[22:25]
	v_mfma_f32_16x16x32_bf16 v[12:15], v[158:161], v[192:195], v[12:15]
	v_mfma_f32_16x16x32_bf16 v[4:7], v[150:153], v[224:227], v[4:7]
	v_mfma_f32_16x16x32_bf16 v[0:3], v[158:161], v[224:227], v[0:3]
	s_setprio 0
	s_barrier
	s_add_i32 s87, 0, 0x18000
	s_add_i32 s88, 0, 0x1c000
	v_add_u32_e32 v142, s87, v203
	v_add_u32_e32 v158, s88, v203
	ds_read_b128 v[130:133], v142
	ds_read_b128 v[134:137], v142 offset:1024
	ds_read_b128 v[138:141], v142 offset:2048
	ds_read_b128 v[142:145], v142 offset:3072
	ds_read_b128 v[146:149], v158
	ds_read_b128 v[150:153], v158 offset:1024
	ds_read_b128 v[154:157], v158 offset:2048
	ds_read_b128 v[158:161], v158 offset:3072
	s_add_u32 s26, s40, 0x160000
	s_addc_u32 s27, s41, 0
	s_mov_b32 m0, s49
	ds_read_b128 v[162:165], v205 offset:32768
	ds_read_b128 v[166:169], v205 offset:33792
	ds_read_b128 v[170:173], v205 offset:34816
	ds_read_b128 v[174:177], v205 offset:35840
	ds_read_b128 v[178:181], v205 offset:36864
	ds_read_b128 v[192:195], v205 offset:37888
	ds_read_b128 v[196:199], v205 offset:38912
	ds_read_b128 v[224:227], v205 offset:39936
	global_load_lds_dwordx4 v186, s[26:27]
	s_mov_b32 m0, s50
	s_nop 0
	global_load_lds_dwordx4 v184, s[26:27]
	s_waitcnt vmcnt(8)
	s_waitcnt lgkmcnt(0)
	s_barrier
	s_setprio 1
	s_waitcnt lgkmcnt(0)
	s_nop 0
	v_mfma_f32_16x16x32_bf16 v[126:129], v[130:133], v[162:165], v[126:129]
	v_mfma_f32_16x16x32_bf16 v[122:125], v[138:141], v[162:165], v[122:125]
	v_mfma_f32_16x16x32_bf16 v[114:117], v[130:133], v[170:173], v[114:117]
	v_mfma_f32_16x16x32_bf16 v[106:109], v[138:141], v[170:173], v[106:109]
	v_mfma_f32_16x16x32_bf16 v[98:101], v[130:133], v[178:181], v[98:101]
	v_mfma_f32_16x16x32_bf16 v[90:93], v[138:141], v[178:181], v[90:93]
	v_mfma_f32_16x16x32_bf16 v[82:85], v[130:133], v[196:199], v[82:85]
	v_mfma_f32_16x16x32_bf16 v[74:77], v[138:141], v[196:199], v[74:77]
	v_mfma_f32_16x16x32_bf16 v[126:129], v[134:137], v[166:169], v[126:129]
	v_mfma_f32_16x16x32_bf16 v[122:125], v[142:145], v[166:169], v[122:125]
	v_mfma_f32_16x16x32_bf16 v[114:117], v[134:137], v[174:177], v[114:117]
	v_mfma_f32_16x16x32_bf16 v[106:109], v[142:145], v[174:177], v[106:109]
	v_mfma_f32_16x16x32_bf16 v[98:101], v[134:137], v[192:195], v[98:101]
	v_mfma_f32_16x16x32_bf16 v[90:93], v[142:145], v[192:195], v[90:93]
	v_mfma_f32_16x16x32_bf16 v[82:85], v[134:137], v[224:227], v[82:85]
	v_mfma_f32_16x16x32_bf16 v[74:77], v[142:145], v[224:227], v[74:77]
	s_setprio 0
	s_setprio 1
	v_mfma_f32_16x16x32_bf16 v[118:121], v[146:149], v[162:165], v[118:121]
	v_mfma_f32_16x16x32_bf16 v[110:113], v[154:157], v[162:165], v[110:113]
	v_mfma_f32_16x16x32_bf16 v[102:105], v[146:149], v[170:173], v[102:105]
	v_mfma_f32_16x16x32_bf16 v[94:97], v[154:157], v[170:173], v[94:97]
	v_mfma_f32_16x16x32_bf16 v[86:89], v[146:149], v[178:181], v[86:89]
	v_mfma_f32_16x16x32_bf16 v[78:81], v[154:157], v[178:181], v[78:81]
	v_mfma_f32_16x16x32_bf16 v[70:73], v[146:149], v[196:199], v[70:73]
	v_mfma_f32_16x16x32_bf16 v[66:69], v[154:157], v[196:199], v[66:69]
	v_mfma_f32_16x16x32_bf16 v[118:121], v[150:153], v[166:169], v[118:121]
	v_mfma_f32_16x16x32_bf16 v[110:113], v[158:161], v[166:169], v[110:113]
	v_mfma_f32_16x16x32_bf16 v[102:105], v[150:153], v[174:177], v[102:105]
	v_mfma_f32_16x16x32_bf16 v[94:97], v[158:161], v[174:177], v[94:97]
	v_mfma_f32_16x16x32_bf16 v[86:89], v[150:153], v[192:195], v[86:89]
	v_mfma_f32_16x16x32_bf16 v[78:81], v[158:161], v[192:195], v[78:81]
	v_mfma_f32_16x16x32_bf16 v[70:73], v[150:153], v[224:227], v[70:73]
	v_mfma_f32_16x16x32_bf16 v[66:69], v[158:161], v[224:227], v[66:69]
	s_setprio 0
	s_barrier
	s_add_i32 s26, s87, s45
	v_lshl_add_u64 v[200:201], v[200:201], 0, s[34:35]
	s_mov_b32 m0, s26
	ds_read_b128 v[162:165], v205 offset:49152
	ds_read_b128 v[166:169], v205 offset:50176
	ds_read_b128 v[170:173], v205 offset:51200
	ds_read_b128 v[174:177], v205 offset:52224
	ds_read_b128 v[178:181], v205 offset:53248
	ds_read_b128 v[192:195], v205 offset:54272
	ds_read_b128 v[196:199], v205 offset:55296
	ds_read_b128 v[224:227], v205 offset:56320
	global_load_lds_dwordx4 v[200:201], off
	s_add_i32 m0, s26, 0x2000
	s_add_u32 s26, s28, 0x160080
	v_lshl_add_u64 v[200:201], v[206:207], 0, s[34:35]
	s_addc_u32 s27, s29, 0
	s_add_i32 s28, s88, s45
	global_load_lds_dwordx4 v[200:201], off
	s_mov_b32 m0, s28
	s_nop 0
	global_load_lds_dwordx4 v16, s[26:27]
	s_add_i32 m0, s28, 0x2000
	s_nop 0
	global_load_lds_dwordx4 v182, s[26:27]
	v_lshl_add_u64 v[200:201], v[216:217], 0, s[34:35]
	s_mov_b32 m0, s53
	s_nop 0
	global_load_lds_dwordx4 v[200:201], off
	v_lshl_add_u64 v[200:201], v[228:229], 0, s[34:35]
	s_mov_b32 m0, s57
	s_nop 0
	global_load_lds_dwordx4 v[200:201], off
	s_waitcnt vmcnt(8)
	s_waitcnt lgkmcnt(0)
	s_barrier
	s_setprio 1
	s_waitcnt lgkmcnt(0)
	v_mfma_f32_16x16x32_bf16 v[62:65], v[130:133], v[162:165], v[62:65]
	v_mfma_f32_16x16x32_bf16 v[58:61], v[138:141], v[162:165], v[58:61]
	v_mfma_f32_16x16x32_bf16 v[50:53], v[130:133], v[170:173], v[50:53]
	v_mfma_f32_16x16x32_bf16 v[42:45], v[138:141], v[170:173], v[42:45]
	v_mfma_f32_16x16x32_bf16 v[34:37], v[130:133], v[178:181], v[34:37]
	v_mfma_f32_16x16x32_bf16 v[26:29], v[138:141], v[178:181], v[26:29]
	v_mfma_f32_16x16x32_bf16 v[18:21], v[130:133], v[196:199], v[18:21]
	v_mfma_f32_16x16x32_bf16 v[8:11], v[138:141], v[196:199], v[8:11]
	v_mfma_f32_16x16x32_bf16 v[62:65], v[134:137], v[166:169], v[62:65]
	v_mfma_f32_16x16x32_bf16 v[58:61], v[142:145], v[166:169], v[58:61]
	v_mfma_f32_16x16x32_bf16 v[50:53], v[134:137], v[174:177], v[50:53]
	v_mfma_f32_16x16x32_bf16 v[42:45], v[142:145], v[174:177], v[42:45]
	v_mfma_f32_16x16x32_bf16 v[34:37], v[134:137], v[192:195], v[34:37]
	v_mfma_f32_16x16x32_bf16 v[26:29], v[142:145], v[192:195], v[26:29]
	v_mfma_f32_16x16x32_bf16 v[18:21], v[134:137], v[224:227], v[18:21]
	v_mfma_f32_16x16x32_bf16 v[8:11], v[142:145], v[224:227], v[8:11]
	s_setprio 0
	s_setprio 1
	v_mfma_f32_16x16x32_bf16 v[54:57], v[146:149], v[162:165], v[54:57]
	v_mfma_f32_16x16x32_bf16 v[46:49], v[154:157], v[162:165], v[46:49]
	v_mfma_f32_16x16x32_bf16 v[38:41], v[146:149], v[170:173], v[38:41]
	v_mfma_f32_16x16x32_bf16 v[30:33], v[154:157], v[170:173], v[30:33]
	v_mfma_f32_16x16x32_bf16 v[22:25], v[146:149], v[178:181], v[22:25]
	v_mfma_f32_16x16x32_bf16 v[12:15], v[154:157], v[178:181], v[12:15]
	v_mfma_f32_16x16x32_bf16 v[4:7], v[146:149], v[196:199], v[4:7]
	v_mfma_f32_16x16x32_bf16 v[0:3], v[154:157], v[196:199], v[0:3]
	v_mfma_f32_16x16x32_bf16 v[54:57], v[150:153], v[166:169], v[54:57]
	v_mfma_f32_16x16x32_bf16 v[46:49], v[158:161], v[166:169], v[46:49]
	v_mfma_f32_16x16x32_bf16 v[38:41], v[150:153], v[174:177], v[38:41]
	v_mfma_f32_16x16x32_bf16 v[30:33], v[158:161], v[174:177], v[30:33]
	v_mfma_f32_16x16x32_bf16 v[22:25], v[150:153], v[192:195], v[22:25]
	v_mfma_f32_16x16x32_bf16 v[12:15], v[158:161], v[192:195], v[12:15]
	v_mfma_f32_16x16x32_bf16 v[4:7], v[150:153], v[224:227], v[4:7]
	v_mfma_f32_16x16x32_bf16 v[0:3], v[158:161], v[224:227], v[0:3]
	s_setprio 0
	s_barrier
	s_add_i32 s86, s86, 2
	s_add_u32 s42, s42, 0x100
	s_addc_u32 s43, s43, 0
	s_cmpk_gt_u32 s86, 0x55
	s_mov_b64 s[26:27], s[36:37]
	s_cbranch_scc0 .LBB0_992
